# MLA: per-step rowmax replaced by row-sum-based lazy rescale trigger (late detection, same math); ds_read pairs hoisted above MFMA wait
# speedup vs baseline: 1.0167x; 1.0167x over previous
; template <bool NA>
; __device__ __forceinline__ void attn_unit(LAS unsigned char* lds, const bf16_t* Q, const bf16_t* Kg, const bf16_t* Kr, const bf16_t* Vt, bf16_t* O,
;                                           int h, int seqrow0, int q0, int t0, int NT, int rows, int g0, const float* rpb_h, int wid) {
;     ...
;     const unsigned lds_u = (unsigned)(uintptr_t)lds;
;     const char* dk_src[2] = {nullptr, nullptr}; unsigned dk_str[2] = {0u, 0u}; const char* dv_src[2] = {nullptr, nullptr};
;     {
;         constexpr int CPR = NA ? 9 : 13;
; #pragma unroll
;         for (int j = 0; j < 2; ++j) { const int ci = 64 * (wid + 8 * j) + lane, row = (ci / CPR) & 63, col = ci % CPR;
;             const bool rope = !NA && (col >= 8 && col < 12);
;             dk_src[j] = rope ? (const char*)(Kr + (size_t)(seqrow0 + t0 * 64 + row) * 32 + 8 * (col - 8)) : (const char*)(Kg + (size_t)(seqrow0 + t0 * 64 + row) * 512 + h * 64 + 8 * (col & 7));
;             dk_str[j] = rope ? 64u * 64u : 64u * 1024u; }
; #pragma unroll
;         for (int j = 0; j < 2; ++j) { const int ci = 64 * (wid + 8 * j) + lane, row = ci / 9, col = ci - 9 * row;
;             dv_src[j] = (const char*)(Vt + (size_t)(h * 64 + (row & 63)) * MT + seqrow0 + t0 * 64 + 8 * (col & 7)); }
;     }
; __global__ void __launch_bounds__(512, 2) fwd_kernel(Params P) {
;     ...
;         for (int u = vcu; u < 2048; u += G) {
;             const int pair = u >> 5, qb = u & 31;
;             attn_unit<false>(lds, QM, KN, krope, VTM, MLAO, pair & 7, (pair >> 3) * SP, 256 * qb, 0, SP / 64, 0, 0, nullptr, wave);
.LBB0_871:
	v_readlane_b32 s33, v244, 17
	v_readlane_b32 s74, v244, 12
	v_readlane_b32 s78, v244, 10
	v_readlane_b32 s84, v244, 5
	s_cmpk_gt_i32 s33, 0x7ff
	v_readlane_b32 s72, v244, 14
	v_readlane_b32 s75, v244, 13
	v_readlane_b32 s79, v244, 11
	v_readlane_b32 s73, v244, 9
	v_readlane_b32 s77, v244, 8
	v_readlane_b32 s80, v244, 7
	v_readlane_b32 s85, v244, 6
	v_readlane_b32 s81, v244, 3
	v_readlane_b32 s86, v244, 4
	v_readlane_b32 s87, v244, 0
	s_cbranch_scc1 .LBB0_948
	v_readlane_b32 s0, v244, 18
	v_readlane_b32 s1, v244, 19
	s_load_dwordx2 s[0:1], s[0:1], 0xb0
	s_movk_i32 s30, 0xff80
	s_mov_b32 s9, 0
	s_mov_b32 s48, 0x4ec4ec4f
	v_mov_b32_e32 v169, 0
	s_waitcnt lgkmcnt(0)
	s_add_u32 s2, s0, 0x5c00000
	s_addc_u32 s3, s1, 0
	s_add_u32 s49, s0, 0x2cc00000
	s_addc_u32 s50, s1, 0
	s_add_u32 s24, s0, 0x2600000
	s_addc_u32 s25, s1, 0
	s_add_u32 s51, s0, 0x34400000
	s_addc_u32 s52, s1, 0
	s_add_u32 s26, s0, 0x23c00000
	s_addc_u32 s27, s1, 0
	s_lshl_b32 s6, s87, 10
	s_cmpk_lt_u32 s86, 0x140
	s_cselect_b64 s[0:1], -1, 0
	s_cmp_eq_u32 s86, 0x140
	s_cselect_b64 s[28:29], -1, 0
	v_cndmask_b32_e64 v0, 0, 1, s[0:1]
	s_add_i32 s62, s6, 0
	s_mov_b32 s31, -1
	s_movk_i32 s53, 0x600
	v_mov_b64_e32 v[170:171], s[2:3]
	v_mov_b32_e32 v207, s6
	v_cmp_ne_u32_e64 s[4:5], 1, v0
	s_mov_b32 s54, 0x38e38e39
	s_add_i32 s55, 0, 0xf000
	s_mov_b64 s[34:35], 0x80
	s_add_i32 s56, 0, 0x11400
	s_movk_i32 s57, 0x68
	s_mov_b32 s58, 0x43800000
	s_mov_b32 s59, 0xe0ad78ec
	s_mov_b64 s[36:37], 0x100
	s_add_i32 s60, 0, 0x13800
	s_mov_b64 s[38:39], 0x180
	s_add_i32 s61, 0, 0x15c00
	s_mov_b64 s[40:41], 0x200
	s_mov_b64 s[42:43], 0x280
	s_mov_b64 s[44:45], 0x300
	s_mov_b64 s[46:47], 0x380
	v_mbcnt_hi_u32_b32 v208, -1, v206
	s_add_i32 s63, s62, 0x2000
	s_add_i32 s64, s62, 0xd000
	s_add_i32 s65, s62, 0x3400
	s_add_i32 s66, s62, 0x5400
	s_add_i32 s67, s62, 0x6800
	s_add_i32 s68, s62, 0x8800
	s_add_i32 s69, s62, 0xf400
	s_mov_b32 s70, s33
	s_branch .LBB0_874

; __device__ __forceinline__ unsigned pk2(float lo, float hi) { return pg8::cvt_pk_bf16(lo, hi); }
; template <int LO, int HI> __device__ __forceinline__ void g_exp(f32x16& X) {
; #pragma unroll
;     for (int r = LO; r < HI; ++r) X[r] = __builtin_amdgcn_exp2f(X[r]);
; }
; template <int LO, int HI> __device__ __forceinline__ void g_sumpk(const f32x16& X, float& psa, float& psb, u32x4& pwlo, u32x4& pwhi) {
; #pragma unroll
;     for (int r = LO; r < HI; r += 2) { psa += X[r]; psb += X[r + 1]; const unsigned w = pk2(X[r], X[r + 1]); if (r < 8) pwlo[(r >> 1) & 3] = w; else pwhi[(r >> 1) & 3] = w; }
;     asm volatile("" : "+v"(psa), "+v"(psb));
; }
.LBB0_893:
	ds_read_b128 v[118:121], v181 offset:32
	ds_read_b128 v[138:141], v181 offset:6688
	s_waitcnt lgkmcnt(3)
	v_mfma_f32_32x32x16_bf16 v[80:95], v[64:67], v[144:147], v[32:47]
	v_exp_f32_e32 v117, v122
	v_exp_f32_e32 v142, v123
	v_exp_f32_e32 v143, v124
	v_exp_f32_e32 v202, v125
	v_exp_f32_e32 v126, v126
	v_exp_f32_e32 v127, v127
	s_waitcnt lgkmcnt(2)
	v_mfma_f32_32x32x16_bf16 v[64:79], v[112:115], v[144:147], v[32:47]
	ds_read_b128 v[112:115], v181 offset:64
	ds_read_b128 v[122:125], v181 offset:6720
	s_waitcnt lgkmcnt(3)
	v_mfma_f32_32x32x16_bf16 v[80:95], v[118:121], v[148:151], v[80:95]
	v_add_f32_e32 v119, 0, v117
	v_add_f32_e32 v120, 0, v142
	v_cvt_pk_bf16_f32 v118, v117, v142
	v_add_f32_e32 v117, v143, v119
	v_add_f32_e32 v120, v202, v120
	v_add_f32_e32 v117, v126, v117
	s_waitcnt lgkmcnt(2)
	v_mfma_f32_32x32x16_bf16 v[64:79], v[138:141], v[148:151], v[64:79]
	v_add_f32_e32 v121, v127, v120
	v_exp_f32_e32 v203, v128
	v_exp_f32_e32 v204, v129
	v_exp_f32_e32 v205, v130
	v_exp_f32_e32 v213, v131
	v_exp_f32_e32 v214, v132
	v_exp_f32_e32 v215, v133
	v_cvt_pk_bf16_f32 v119, v143, v202
	v_cvt_pk_bf16_f32 v120, v126, v127
	ds_read_b128 v[126:129], v181 offset:96
	ds_read_b128 v[130:133], v181 offset:6752
	s_waitcnt lgkmcnt(3)
	v_mfma_f32_32x32x16_bf16 v[80:95], v[112:115], v[152:155], v[80:95]
	v_add_f32_e32 v112, v203, v117
	v_add_f32_e32 v113, v204, v121
	v_add_f32_e32 v114, v205, v112
	v_add_f32_e32 v113, v213, v113
	v_add_f32_e32 v114, v214, v114
	v_add_f32_e32 v115, v215, v113
	s_waitcnt lgkmcnt(2)
	v_mfma_f32_32x32x16_bf16 v[64:79], v[122:125], v[152:155], v[64:79]
	v_exp_f32_e32 v138, v134
	v_exp_f32_e32 v139, v135
	v_exp_f32_e32 v140, v136
	v_exp_f32_e32 v141, v137
	v_cvt_pk_bf16_f32 v121, v203, v204
	v_cvt_pk_bf16_f32 v112, v205, v213
	v_cvt_pk_bf16_f32 v113, v214, v215
	ds_read_b128 v[122:125], v181 offset:128
	ds_read_b128 v[134:137], v181 offset:6784
	s_waitcnt lgkmcnt(3)
	v_mfma_f32_32x32x16_bf16 v[80:95], v[126:129], v[156:159], v[80:95]
	v_exp_f32_e32 v117, v96
	v_exp_f32_e32 v142, v97
	v_add_f32_e32 v96, v138, v114
	v_add_f32_e32 v97, v139, v115
	v_exp_f32_e32 v203, v100
	v_exp_f32_e32 v204, v101
	s_waitcnt lgkmcnt(2)
	v_mfma_f32_32x32x16_bf16 v[64:79], v[130:133], v[156:159], v[64:79]
	v_add_f32_e32 v100, v140, v96
	v_add_f32_e32 v101, v141, v97
	v_exp_f32_e32 v143, v98
	v_exp_f32_e32 v202, v99
	v_cvt_pk_bf16_f32 v114, v138, v139
	v_cvt_pk_bf16_f32 v115, v140, v141
	ds_read_b128 v[96:99], v181 offset:160
	ds_read_b128 v[126:129], v181 offset:6816
	s_waitcnt lgkmcnt(3)
	v_mfma_f32_32x32x16_bf16 v[80:95], v[122:125], v[160:163], v[80:95]
	v_exp_f32_e32 v130, v102
	v_add_f32_e32 v102, v117, v100
	v_add_f32_e32 v101, v142, v101
	v_exp_f32_e32 v131, v104
	v_add_f32_e32 v102, v143, v102
	v_add_f32_e32 v104, v202, v101
	s_waitcnt lgkmcnt(2)
	v_mfma_f32_32x32x16_bf16 v[64:79], v[134:137], v[160:163], v[64:79]
	v_cvt_pk_bf16_f32 v100, v117, v142
	v_add_f32_e32 v117, v203, v102
	v_add_f32_e32 v134, v204, v104
	v_exp_f32_e32 v103, v103
	v_exp_f32_e32 v132, v105
	v_exp_f32_e32 v133, v106
	v_exp_f32_e32 v138, v107
	v_cvt_pk_bf16_f32 v101, v143, v202
	v_cvt_pk_bf16_f32 v102, v203, v204
	ds_read_b128 v[104:107], v211 offset:27648
	ds_read_b128 v[122:125], v211 offset:32256
	s_waitcnt lgkmcnt(3)
	v_mfma_f32_32x32x16_bf16 v[80:95], v[96:99], v[164:167], v[80:95]
	v_add_f32_e32 v96, v130, v117
	v_add_f32_e32 v97, v103, v134
	v_add_f32_e32 v98, v131, v96
	v_add_f32_e32 v97, v132, v97
	v_add_f32_e32 v98, v133, v98
	v_add_f32_e32 v99, v138, v97
	s_waitcnt lgkmcnt(2)
	v_mfma_f32_32x32x16_bf16 v[64:79], v[126:129], v[164:167], v[64:79]
	v_exp_f32_e32 v135, v108
	v_exp_f32_e32 v136, v109
	v_exp_f32_e32 v137, v110
	v_exp_f32_e32 v139, v111
	v_cvt_pk_bf16_f32 v103, v130, v103
	v_cvt_pk_bf16_f32 v96, v131, v132
	v_cvt_pk_bf16_f32 v97, v133, v138
	ds_read_b128 v[108:111], v211 offset:27680
	ds_read_b128 v[126:129], v211 offset:32288
	s_waitcnt lgkmcnt(3)
	v_mfma_f32_32x32x16_bf16 v[0:15], v[104:107], v[118:121], v[0:15]
	v_add_f32_e32 v104, v135, v98
	v_add_f32_e32 v99, v136, v99
	v_add_f32_e32 v117, v137, v104
	v_add_f32_e32 v130, v139, v99
	v_cvt_pk_bf16_f32 v98, v135, v136
	v_cvt_pk_bf16_f32 v99, v137, v139
	s_waitcnt lgkmcnt(2)
	v_mfma_f32_32x32x16_bf16 v[16:31], v[122:125], v[118:121], v[16:31]
	ds_read_b128 v[104:107], v211 offset:27712
	s_waitcnt lgkmcnt(2)
	v_mfma_f32_32x32x16_bf16 v[0:15], v[108:111], v[112:115], v[0:15]
	ds_read_b128 v[108:111], v211 offset:32320
	s_waitcnt lgkmcnt(2)
	v_mfma_f32_32x32x16_bf16 v[16:31], v[126:129], v[112:115], v[16:31]
	ds_read_b128 v[112:115], v211 offset:27744
	ds_read_b128 v[118:121], v211 offset:32352
	s_waitcnt lgkmcnt(3)
	v_mfma_f32_32x32x16_bf16 v[0:15], v[104:107], v[100:103], v[0:15]
	s_waitcnt lgkmcnt(2)
	v_mfma_f32_32x32x16_bf16 v[16:31], v[108:111], v[100:103], v[16:31]
	s_waitcnt lgkmcnt(1)
	v_mfma_f32_32x32x16_bf16 v[0:15], v[112:115], v[96:99], v[0:15]
	v_add_f32_e32 v221, v117, v130
	v_add_f32_e32 v116, v116, v221
	s_waitcnt lgkmcnt(0)
	v_mfma_f32_32x32x16_bf16 v[16:31], v[118:121], v[96:99], v[16:31]
	s_waitcnt vmcnt(0)
	s_add_u32 s10, s10, 0x400
	s_addc_u32 s11, s11, 0
	v_lshl_add_u64 v[200:201], v[200:201], 0, v[168:169]
	s_cmpk_lt_u32 s16, 0x78
	v_lshl_add_u64 v[196:197], v[196:197], 0, v[198:199]
	s_barrier
	s_cbranch_scc0 .LBB0_873
.LBB0_894:
	ds_read_b128 v[96:99], v181 offset:13312
	ds_read_b128 v[112:115], v181 offset:19968
	s_cmp_eq_u32 s10, 0
	s_cbranch_scc1 .LBB0_947
	v_cmp_lt_f32_e32 vcc, s58, v221
	s_mov_b64 s[14:15], 0
	s_mov_b64 s[12:13], 0
	s_cbranch_vccz .LBB0_897
	v_mov_b32_e32 v222, v221
	v_mov_b32_e32 v223, v221
	s_nop 1
	v_permlane32_swap_b32_e32 v222, v223
	v_add_f32_e32 v222, v222, v223
	v_log_f32_e32 v222, v222
	s_nop 0
	v_max_f32_e32 v101, 0, v222
	s_mov_b64 s[12:13], -1

.LBB0_905:
	ds_read_b128 v[118:121], v181 offset:13344
	ds_read_b128 v[122:125], v181 offset:20000
	s_waitcnt lgkmcnt(3)
	v_mfma_f32_32x32x16_bf16 v[128:143], v[96:99], v[144:147], v[32:47]
	v_exp_f32_e32 v117, v80
	v_exp_f32_e32 v126, v81
	v_exp_f32_e32 v127, v82
	v_exp_f32_e32 v213, v83
	v_exp_f32_e32 v214, v84
	v_exp_f32_e32 v215, v85
	s_waitcnt lgkmcnt(2)
	v_mfma_f32_32x32x16_bf16 v[96:111], v[112:115], v[144:147], v[32:47]
	ds_read_b128 v[80:83], v181 offset:13376
	ds_read_b128 v[112:115], v181 offset:20032
	s_waitcnt lgkmcnt(3)
	v_mfma_f32_32x32x16_bf16 v[128:143], v[118:121], v[148:151], v[128:143]
	v_exp_f32_e32 v216, v86
	v_add_f32_e32 v85, 0, v117
	v_add_f32_e32 v86, 0, v126
	v_exp_f32_e32 v217, v88
	v_add_f32_e32 v88, v127, v85
	v_add_f32_e32 v86, v213, v86
	s_waitcnt lgkmcnt(2)
	v_mfma_f32_32x32x16_bf16 v[96:111], v[122:125], v[148:151], v[96:111]
	v_cvt_pk_bf16_f32 v84, v117, v126
	v_add_f32_e32 v117, v214, v88
	v_add_f32_e32 v122, v215, v86
	v_exp_f32_e32 v87, v87
	v_exp_f32_e32 v218, v89
	v_exp_f32_e32 v219, v90
	v_exp_f32_e32 v220, v91
	v_cvt_pk_bf16_f32 v85, v127, v213
	v_cvt_pk_bf16_f32 v86, v214, v215
	ds_read_b128 v[88:91], v181 offset:13408
	ds_read_b128 v[118:121], v181 offset:20064
	s_waitcnt lgkmcnt(3)
	v_mfma_f32_32x32x16_bf16 v[128:143], v[80:83], v[152:155], v[128:143]
	v_add_f32_e32 v80, v216, v117
	v_add_f32_e32 v81, v87, v122
	v_add_f32_e32 v82, v217, v80
	v_add_f32_e32 v81, v218, v81
	v_add_f32_e32 v82, v219, v82
	v_add_f32_e32 v83, v220, v81
	s_waitcnt lgkmcnt(2)
	v_mfma_f32_32x32x16_bf16 v[96:111], v[112:115], v[152:155], v[96:111]
	v_exp_f32_e32 v123, v92
	v_exp_f32_e32 v124, v93
	v_exp_f32_e32 v125, v94
	v_exp_f32_e32 v126, v95
	v_cvt_pk_bf16_f32 v87, v216, v87
	v_cvt_pk_bf16_f32 v80, v217, v218
	v_cvt_pk_bf16_f32 v81, v219, v220
	ds_read_b128 v[92:95], v181 offset:13440
	ds_read_b128 v[112:115], v181 offset:20096
	s_waitcnt lgkmcnt(3)
	v_mfma_f32_32x32x16_bf16 v[128:143], v[88:91], v[156:159], v[128:143]
	v_exp_f32_e32 v117, v64
	v_exp_f32_e32 v122, v65
	v_add_f32_e32 v64, v123, v82
	v_add_f32_e32 v65, v124, v83
	v_exp_f32_e32 v214, v68
	v_exp_f32_e32 v215, v69
	s_waitcnt lgkmcnt(2)
	v_mfma_f32_32x32x16_bf16 v[96:111], v[118:121], v[156:159], v[96:111]
	v_add_f32_e32 v68, v125, v64
	v_add_f32_e32 v69, v126, v65
	v_exp_f32_e32 v127, v66
	v_exp_f32_e32 v213, v67
	v_cvt_pk_bf16_f32 v82, v123, v124
	v_cvt_pk_bf16_f32 v83, v125, v126
	ds_read_b128 v[64:67], v181 offset:13472
	ds_read_b128 v[88:91], v181 offset:20128
	s_waitcnt lgkmcnt(3)
	v_mfma_f32_32x32x16_bf16 v[128:143], v[92:95], v[160:163], v[128:143]
	v_exp_f32_e32 v118, v70
	v_add_f32_e32 v70, v117, v68
	v_add_f32_e32 v69, v122, v69
	v_exp_f32_e32 v119, v72
	v_add_f32_e32 v70, v127, v70
	v_add_f32_e32 v72, v213, v69
	s_waitcnt lgkmcnt(2)
	v_mfma_f32_32x32x16_bf16 v[96:111], v[112:115], v[160:163], v[96:111]
	v_add_f32_e32 v112, v214, v70
	v_add_f32_e32 v113, v215, v72
	v_exp_f32_e32 v71, v71
	v_exp_f32_e32 v120, v73
	v_exp_f32_e32 v121, v74
	v_exp_f32_e32 v123, v75
	v_cvt_pk_bf16_f32 v68, v117, v122
	v_cvt_pk_bf16_f32 v69, v127, v213
	v_cvt_pk_bf16_f32 v70, v214, v215
	ds_read_b128 v[72:75], v210 offset:53248
	ds_read_b128 v[92:95], v210 offset:57856
	s_waitcnt lgkmcnt(3)
	v_mfma_f32_32x32x16_bf16 v[128:143], v[64:67], v[164:167], v[128:143]
	v_add_f32_e32 v64, v118, v112
	v_add_f32_e32 v65, v71, v113
	v_add_f32_e32 v66, v119, v64
	v_add_f32_e32 v65, v120, v65
	v_add_f32_e32 v66, v121, v66
	v_add_f32_e32 v67, v123, v65
	s_waitcnt lgkmcnt(2)
	v_mfma_f32_32x32x16_bf16 v[96:111], v[88:91], v[164:167], v[96:111]
	v_exp_f32_e32 v114, v76
	v_exp_f32_e32 v115, v77
	v_exp_f32_e32 v117, v78
	v_exp_f32_e32 v122, v79
	v_cvt_pk_bf16_f32 v71, v118, v71
	v_cvt_pk_bf16_f32 v64, v119, v120
	v_cvt_pk_bf16_f32 v65, v121, v123
	ds_read_b128 v[76:79], v210 offset:53280
	ds_read_b128 v[88:91], v210 offset:57888
	s_waitcnt lgkmcnt(3)
	v_mfma_f32_32x32x16_bf16 v[0:15], v[72:75], v[84:87], v[0:15]
	v_add_f32_e32 v72, v114, v66
	v_add_f32_e32 v67, v115, v67
	v_add_f32_e32 v112, v117, v72
	v_add_f32_e32 v113, v122, v67
	v_cvt_pk_bf16_f32 v66, v114, v115
	v_cvt_pk_bf16_f32 v67, v117, v122
	s_waitcnt lgkmcnt(2)
	v_mfma_f32_32x32x16_bf16 v[16:31], v[92:95], v[84:87], v[16:31]
	ds_read_b128 v[72:75], v210 offset:53312
	s_waitcnt lgkmcnt(2)
	v_mfma_f32_32x32x16_bf16 v[0:15], v[76:79], v[80:83], v[0:15]
	ds_read_b128 v[76:79], v210 offset:57920
	s_waitcnt lgkmcnt(2)
	v_mfma_f32_32x32x16_bf16 v[16:31], v[88:91], v[80:83], v[16:31]
	ds_read_b128 v[80:83], v210 offset:53344
	ds_read_b128 v[88:91], v210 offset:57952
	s_waitcnt lgkmcnt(3)
	v_mfma_f32_32x32x16_bf16 v[0:15], v[72:75], v[68:71], v[0:15]
	s_waitcnt lgkmcnt(2)
	v_mfma_f32_32x32x16_bf16 v[16:31], v[76:79], v[68:71], v[16:31]
	s_waitcnt lgkmcnt(1)
	v_mfma_f32_32x32x16_bf16 v[0:15], v[80:83], v[64:67], v[0:15]
	v_add_f32_e32 v221, v112, v113
	v_add_f32_e32 v86, v116, v221
	s_waitcnt lgkmcnt(0)
	v_mfma_f32_32x32x16_bf16 v[16:31], v[88:91], v[64:67], v[16:31]
	ds_read_b128 v[64:67], v181 offset:26624
	ds_read_b128 v[80:83], v181 offset:33280
	v_cmp_lt_f32_e32 vcc, s58, v221
	s_cbranch_vccz .LBB0_907
	v_mov_b32_e32 v222, v221
	v_mov_b32_e32 v223, v221
	s_nop 1
	v_permlane32_swap_b32_e32 v222, v223
	v_add_f32_e32 v222, v222, v223
	v_log_f32_e32 v222, v222
	s_nop 0
	v_max_f32_e32 v33, 0, v222
	v_exp_f32_e64 v34, -v33
	v_add_f32_e32 v212, v212, v33
	v_xor_b32_e32 v32, 0x80000000, v212
	v_sub_f32_e32 v143, v143, v33
	v_pk_mul_f32 v[14:15], v[14:15], v[34:35] op_sel_hi:[1,0]
	v_pk_mul_f32 v[12:13], v[12:13], v[34:35] op_sel_hi:[1,0]
	v_pk_mul_f32 v[10:11], v[10:11], v[34:35] op_sel_hi:[1,0]
	v_pk_mul_f32 v[8:9], v[8:9], v[34:35] op_sel_hi:[1,0]
	v_pk_mul_f32 v[6:7], v[6:7], v[34:35] op_sel_hi:[1,0]
	v_pk_mul_f32 v[4:5], v[4:5], v[34:35] op_sel_hi:[1,0]
	v_pk_mul_f32 v[2:3], v[2:3], v[34:35] op_sel_hi:[1,0]
	v_pk_mul_f32 v[0:1], v[0:1], v[34:35] op_sel_hi:[1,0]
	v_pk_mul_f32 v[30:31], v[30:31], v[34:35] op_sel_hi:[1,0]
	v_pk_mul_f32 v[28:29], v[28:29], v[34:35] op_sel_hi:[1,0]
	v_pk_mul_f32 v[26:27], v[26:27], v[34:35] op_sel_hi:[1,0]
	v_pk_mul_f32 v[24:25], v[24:25], v[34:35] op_sel_hi:[1,0]
	v_pk_mul_f32 v[22:23], v[22:23], v[34:35] op_sel_hi:[1,0]
	v_pk_mul_f32 v[20:21], v[20:21], v[34:35] op_sel_hi:[1,0]
	v_pk_mul_f32 v[18:19], v[18:19], v[34:35] op_sel_hi:[1,0]
	v_pk_mul_f32 v[16:17], v[16:17], v[34:35] op_sel_hi:[1,0]
	v_sub_f32_e32 v142, v142, v33
	v_sub_f32_e32 v141, v141, v33
	v_sub_f32_e32 v140, v140, v33
	v_sub_f32_e32 v139, v139, v33
	v_sub_f32_e32 v138, v138, v33
	v_sub_f32_e32 v137, v137, v33
	v_sub_f32_e32 v136, v136, v33
	v_sub_f32_e32 v135, v135, v33
	v_sub_f32_e32 v134, v134, v33
	v_sub_f32_e32 v133, v133, v33
	v_sub_f32_e32 v132, v132, v33
	v_sub_f32_e32 v131, v131, v33
	v_sub_f32_e32 v130, v130, v33
	v_sub_f32_e32 v129, v129, v33
	v_sub_f32_e32 v128, v128, v33
	v_sub_f32_e32 v111, v111, v33
	v_sub_f32_e32 v110, v110, v33
	v_sub_f32_e32 v109, v109, v33
	v_sub_f32_e32 v108, v108, v33
	v_sub_f32_e32 v107, v107, v33
	v_sub_f32_e32 v106, v106, v33
	v_sub_f32_e32 v105, v105, v33
	v_sub_f32_e32 v104, v104, v33
	v_sub_f32_e32 v103, v103, v33
	v_sub_f32_e32 v102, v102, v33
	v_sub_f32_e32 v101, v101, v33
	v_sub_f32_e32 v100, v100, v33
	v_sub_f32_e32 v99, v99, v33
	v_sub_f32_e32 v98, v98, v33
	v_sub_f32_e32 v97, v97, v33
	v_sub_f32_e32 v96, v96, v33
	v_mul_f32_e32 v86, v86, v34
	v_mov_b32_e32 v33, v32
	v_mov_b32_e32 v34, v32
	v_mov_b32_e32 v35, v32
	v_mov_b32_e32 v36, v32
	v_mov_b32_e32 v37, v32
	v_mov_b32_e32 v38, v32
	v_mov_b32_e32 v39, v32
	v_mov_b32_e32 v40, v32
	v_mov_b32_e32 v41, v32
	v_mov_b32_e32 v42, v32
	v_mov_b32_e32 v43, v32
	v_mov_b32_e32 v44, v32
	v_mov_b32_e32 v45, v32
	v_mov_b32_e32 v46, v32
	v_mov_b32_e32 v47, v32
	v_mov_b32_e32 v48, v32
	v_mov_b32_e32 v49, v32
	v_mov_b32_e32 v50, v32
	v_mov_b32_e32 v51, v32
	v_mov_b32_e32 v52, v32
	v_mov_b32_e32 v53, v32
	v_mov_b32_e32 v54, v32
	v_mov_b32_e32 v55, v32
	v_mov_b32_e32 v56, v32
	v_mov_b32_e32 v57, v32
	v_mov_b32_e32 v58, v32
	v_mov_b32_e32 v59, v32
	v_mov_b32_e32 v60, v32
	v_mov_b32_e32 v61, v32
	v_mov_b32_e32 v62, v32
	v_mov_b32_e32 v63, v32

.LBB0_911:
	ds_read_b128 v[88:91], v181 offset:26656
	ds_read_b128 v[92:95], v181 offset:33312
	s_waitcnt lgkmcnt(3)
	v_mfma_f32_32x32x16_bf16 v[112:127], v[64:67], v[144:147], v[32:47]
	v_exp_f32_e32 v87, v128
	v_exp_f32_e32 v213, v129
	v_exp_f32_e32 v214, v130
	v_exp_f32_e32 v215, v131
	v_exp_f32_e32 v132, v132
	v_exp_f32_e32 v133, v133
	s_waitcnt lgkmcnt(2)
	v_mfma_f32_32x32x16_bf16 v[64:79], v[80:83], v[144:147], v[32:47]
	ds_read_b128 v[80:83], v181 offset:26688
	ds_read_b128 v[128:131], v181 offset:33344
	s_waitcnt lgkmcnt(3)
	v_mfma_f32_32x32x16_bf16 v[112:127], v[88:91], v[148:151], v[112:127]
	v_add_f32_e32 v89, 0, v87
	v_add_f32_e32 v90, 0, v213
	v_cvt_pk_bf16_f32 v88, v87, v213
	v_add_f32_e32 v87, v214, v89
	v_add_f32_e32 v90, v215, v90
	v_add_f32_e32 v87, v132, v87
	s_waitcnt lgkmcnt(2)
	v_mfma_f32_32x32x16_bf16 v[64:79], v[92:95], v[148:151], v[64:79]
	v_add_f32_e32 v91, v133, v90
	v_exp_f32_e32 v216, v134
	v_exp_f32_e32 v217, v135
	v_exp_f32_e32 v136, v136
	v_exp_f32_e32 v137, v137
	v_exp_f32_e32 v138, v138
	v_exp_f32_e32 v139, v139
	v_cvt_pk_bf16_f32 v89, v214, v215
	v_cvt_pk_bf16_f32 v90, v132, v133
	ds_read_b128 v[92:95], v181 offset:26720
	ds_read_b128 v[132:135], v181 offset:33376
	s_waitcnt lgkmcnt(3)
	v_mfma_f32_32x32x16_bf16 v[112:127], v[80:83], v[152:155], v[112:127]
	v_add_f32_e32 v80, v216, v87
	v_add_f32_e32 v81, v217, v91
	v_add_f32_e32 v82, v136, v80
	v_add_f32_e32 v81, v137, v81
	v_add_f32_e32 v82, v138, v82
	v_add_f32_e32 v83, v139, v81
	s_waitcnt lgkmcnt(2)
	v_mfma_f32_32x32x16_bf16 v[64:79], v[128:131], v[152:155], v[64:79]
	v_exp_f32_e32 v140, v140
	v_exp_f32_e32 v141, v141
	v_exp_f32_e32 v142, v142
	v_exp_f32_e32 v143, v143
	v_cvt_pk_bf16_f32 v91, v216, v217
	v_cvt_pk_bf16_f32 v80, v136, v137
	v_cvt_pk_bf16_f32 v81, v138, v139
	ds_read_b128 v[128:131], v181 offset:26752
	ds_read_b128 v[136:139], v181 offset:33408
	s_waitcnt lgkmcnt(3)
	v_mfma_f32_32x32x16_bf16 v[112:127], v[92:95], v[156:159], v[112:127]
	v_exp_f32_e32 v87, v96
	v_add_f32_e32 v92, v140, v82
	v_add_f32_e32 v83, v141, v83
	v_exp_f32_e32 v216, v100
	v_exp_f32_e32 v217, v101
	v_add_f32_e32 v100, v142, v92
	s_waitcnt lgkmcnt(2)
	v_mfma_f32_32x32x16_bf16 v[64:79], v[132:135], v[156:159], v[64:79]
	v_add_f32_e32 v101, v143, v83
	v_exp_f32_e32 v213, v97
	v_exp_f32_e32 v214, v98
	v_exp_f32_e32 v215, v99
	v_cvt_pk_bf16_f32 v82, v140, v141
	v_cvt_pk_bf16_f32 v83, v142, v143
	ds_read_b128 v[92:95], v181 offset:26784
	ds_read_b128 v[96:99], v181 offset:33440
	s_waitcnt lgkmcnt(3)
	v_mfma_f32_32x32x16_bf16 v[112:127], v[128:131], v[160:163], v[112:127]
	v_exp_f32_e32 v132, v102
	v_add_f32_e32 v102, v87, v100
	v_add_f32_e32 v101, v213, v101
	v_cvt_pk_bf16_f32 v100, v87, v213
	v_add_f32_e32 v87, v214, v102
	v_add_f32_e32 v102, v215, v101
	s_waitcnt lgkmcnt(2)
	v_mfma_f32_32x32x16_bf16 v[64:79], v[136:139], v[160:163], v[64:79]
	v_add_f32_e32 v87, v216, v87
	v_add_f32_e32 v136, v217, v102
	v_exp_f32_e32 v103, v103
	v_exp_f32_e32 v133, v104
	v_exp_f32_e32 v134, v105
	v_exp_f32_e32 v135, v106
	v_exp_f32_e32 v140, v107
	v_cvt_pk_bf16_f32 v101, v214, v215
	v_cvt_pk_bf16_f32 v102, v216, v217
	ds_read_b128 v[104:107], v210 offset:62464
	ds_read_b128 v[128:131], v211 offset:13824
	s_waitcnt lgkmcnt(3)
	v_mfma_f32_32x32x16_bf16 v[112:127], v[92:95], v[164:167], v[112:127]
	v_add_f32_e32 v87, v132, v87
	v_add_f32_e32 v92, v103, v136
	v_add_f32_e32 v87, v133, v87
	v_add_f32_e32 v93, v134, v92
	v_add_f32_e32 v87, v135, v87
	v_add_f32_e32 v94, v140, v93
	s_waitcnt lgkmcnt(2)
	v_mfma_f32_32x32x16_bf16 v[64:79], v[96:99], v[164:167], v[64:79]
	v_exp_f32_e32 v137, v108
	v_exp_f32_e32 v138, v109
	v_exp_f32_e32 v139, v110
	v_exp_f32_e32 v141, v111
	v_cvt_pk_bf16_f32 v103, v132, v103
	v_cvt_pk_bf16_f32 v92, v133, v134
	v_cvt_pk_bf16_f32 v93, v135, v140
	ds_read_b128 v[96:99], v210 offset:62496
	ds_read_b128 v[108:111], v211 offset:13856
	s_waitcnt lgkmcnt(3)
	v_mfma_f32_32x32x16_bf16 v[0:15], v[104:107], v[88:91], v[0:15]
	v_add_f32_e32 v87, v137, v87
	v_add_f32_e32 v95, v138, v94
	v_add_f32_e32 v132, v139, v87
	v_add_f32_e32 v133, v141, v95
	v_cvt_pk_bf16_f32 v94, v137, v138
	v_cvt_pk_bf16_f32 v95, v139, v141
	s_waitcnt lgkmcnt(2)
	v_mfma_f32_32x32x16_bf16 v[16:31], v[128:131], v[88:91], v[16:31]
	ds_read_b128 v[88:91], v210 offset:62528
	s_waitcnt lgkmcnt(2)
	v_mfma_f32_32x32x16_bf16 v[0:15], v[96:99], v[80:83], v[0:15]
	ds_read_b128 v[96:99], v211 offset:13888
	s_waitcnt lgkmcnt(2)
	v_mfma_f32_32x32x16_bf16 v[16:31], v[108:111], v[80:83], v[16:31]
	ds_read_b128 v[80:83], v210 offset:62560
	ds_read_b128 v[104:107], v211 offset:13920
	s_waitcnt lgkmcnt(3)
	v_mfma_f32_32x32x16_bf16 v[0:15], v[88:91], v[100:103], v[0:15]
	s_waitcnt lgkmcnt(2)
	v_mfma_f32_32x32x16_bf16 v[16:31], v[96:99], v[100:103], v[16:31]
	s_waitcnt lgkmcnt(1)
	v_mfma_f32_32x32x16_bf16 v[0:15], v[80:83], v[92:95], v[0:15]
	v_add_f32_e32 v221, v132, v133
	v_add_f32_e32 v102, v86, v221
	s_waitcnt lgkmcnt(0)
	v_mfma_f32_32x32x16_bf16 v[16:31], v[104:107], v[92:95], v[16:31]
	s_waitcnt vmcnt(0)
	s_barrier
	ds_read_b128 v[80:83], v181 offset:39936
	ds_read_b128 v[96:99], v181 offset:46592
	v_cmp_lt_f32_e32 vcc, s58, v221
	s_cbranch_vccz .LBB0_913
	v_mov_b32_e32 v222, v221
	v_mov_b32_e32 v223, v221
	s_nop 1
	v_permlane32_swap_b32_e32 v222, v223
	v_add_f32_e32 v222, v222, v223
	v_log_f32_e32 v222, v222
	s_nop 0
	v_max_f32_e32 v33, 0, v222
	v_exp_f32_e64 v34, -v33
	v_add_f32_e32 v212, v212, v33
	v_xor_b32_e32 v32, 0x80000000, v212
	v_sub_f32_e32 v127, v127, v33
	v_pk_mul_f32 v[14:15], v[14:15], v[34:35] op_sel_hi:[1,0]
	v_pk_mul_f32 v[12:13], v[12:13], v[34:35] op_sel_hi:[1,0]
	v_pk_mul_f32 v[10:11], v[10:11], v[34:35] op_sel_hi:[1,0]
	v_pk_mul_f32 v[8:9], v[8:9], v[34:35] op_sel_hi:[1,0]
	v_pk_mul_f32 v[6:7], v[6:7], v[34:35] op_sel_hi:[1,0]
	v_pk_mul_f32 v[4:5], v[4:5], v[34:35] op_sel_hi:[1,0]
	v_pk_mul_f32 v[2:3], v[2:3], v[34:35] op_sel_hi:[1,0]
	v_pk_mul_f32 v[0:1], v[0:1], v[34:35] op_sel_hi:[1,0]
	v_pk_mul_f32 v[30:31], v[30:31], v[34:35] op_sel_hi:[1,0]
	v_pk_mul_f32 v[28:29], v[28:29], v[34:35] op_sel_hi:[1,0]
	v_pk_mul_f32 v[26:27], v[26:27], v[34:35] op_sel_hi:[1,0]
	v_pk_mul_f32 v[24:25], v[24:25], v[34:35] op_sel_hi:[1,0]
	v_pk_mul_f32 v[22:23], v[22:23], v[34:35] op_sel_hi:[1,0]
	v_pk_mul_f32 v[20:21], v[20:21], v[34:35] op_sel_hi:[1,0]
	v_pk_mul_f32 v[18:19], v[18:19], v[34:35] op_sel_hi:[1,0]
	v_pk_mul_f32 v[16:17], v[16:17], v[34:35] op_sel_hi:[1,0]
	v_sub_f32_e32 v126, v126, v33
	v_sub_f32_e32 v125, v125, v33
	v_sub_f32_e32 v124, v124, v33
	v_sub_f32_e32 v123, v123, v33
	v_sub_f32_e32 v122, v122, v33
	v_sub_f32_e32 v121, v121, v33
	v_sub_f32_e32 v120, v120, v33
	v_sub_f32_e32 v119, v119, v33
	v_sub_f32_e32 v118, v118, v33
	v_sub_f32_e32 v117, v117, v33
	v_sub_f32_e32 v116, v116, v33
	v_sub_f32_e32 v115, v115, v33
	v_sub_f32_e32 v114, v114, v33
	v_sub_f32_e32 v113, v113, v33
	v_sub_f32_e32 v112, v112, v33
	v_sub_f32_e32 v79, v79, v33
	v_sub_f32_e32 v78, v78, v33
	v_sub_f32_e32 v77, v77, v33
	v_sub_f32_e32 v76, v76, v33
	v_sub_f32_e32 v75, v75, v33
	v_sub_f32_e32 v74, v74, v33
	v_sub_f32_e32 v73, v73, v33
	v_sub_f32_e32 v72, v72, v33
	v_sub_f32_e32 v71, v71, v33
	v_sub_f32_e32 v70, v70, v33
	v_sub_f32_e32 v69, v69, v33
	v_sub_f32_e32 v68, v68, v33
	v_sub_f32_e32 v67, v67, v33
	v_sub_f32_e32 v66, v66, v33
	v_sub_f32_e32 v65, v65, v33
	v_sub_f32_e32 v64, v64, v33
	v_mul_f32_e32 v102, v102, v34
	v_mov_b32_e32 v33, v32
	v_mov_b32_e32 v34, v32
	v_mov_b32_e32 v35, v32
	v_mov_b32_e32 v36, v32
	v_mov_b32_e32 v37, v32
	v_mov_b32_e32 v38, v32
	v_mov_b32_e32 v39, v32
	v_mov_b32_e32 v40, v32
	v_mov_b32_e32 v41, v32
	v_mov_b32_e32 v42, v32
	v_mov_b32_e32 v43, v32
	v_mov_b32_e32 v44, v32
	v_mov_b32_e32 v45, v32
	v_mov_b32_e32 v46, v32
	v_mov_b32_e32 v47, v32
	v_mov_b32_e32 v48, v32
	v_mov_b32_e32 v49, v32
	v_mov_b32_e32 v50, v32
	v_mov_b32_e32 v51, v32
	v_mov_b32_e32 v52, v32
	v_mov_b32_e32 v53, v32
	v_mov_b32_e32 v54, v32
	v_mov_b32_e32 v55, v32
	v_mov_b32_e32 v56, v32
	v_mov_b32_e32 v57, v32
	v_mov_b32_e32 v58, v32
	v_mov_b32_e32 v59, v32
	v_mov_b32_e32 v60, v32
	v_mov_b32_e32 v61, v32
	v_mov_b32_e32 v62, v32
	v_mov_b32_e32 v63, v32

.LBB0_917:
	ds_read_b128 v[104:107], v181 offset:39968
	ds_read_b128 v[108:111], v181 offset:46624
	s_waitcnt lgkmcnt(3)
	v_mfma_f32_32x32x16_bf16 v[128:143], v[80:83], v[144:147], v[32:47]
	v_exp_f32_e32 v103, v112
	v_exp_f32_e32 v213, v113
	v_exp_f32_e32 v214, v114
	v_exp_f32_e32 v215, v115
	v_exp_f32_e32 v116, v116
	v_exp_f32_e32 v117, v117
	s_waitcnt lgkmcnt(2)
	v_mfma_f32_32x32x16_bf16 v[80:95], v[96:99], v[144:147], v[32:47]
	ds_read_b128 v[96:99], v181 offset:40000
	ds_read_b128 v[112:115], v181 offset:46656
	s_waitcnt lgkmcnt(3)
	v_mfma_f32_32x32x16_bf16 v[128:143], v[104:107], v[148:151], v[128:143]
	v_add_f32_e32 v105, 0, v103
	v_add_f32_e32 v106, 0, v213
	v_cvt_pk_bf16_f32 v104, v103, v213
	v_add_f32_e32 v103, v214, v105
	v_add_f32_e32 v106, v215, v106
	v_add_f32_e32 v103, v116, v103
	s_waitcnt lgkmcnt(2)
	v_mfma_f32_32x32x16_bf16 v[80:95], v[108:111], v[148:151], v[80:95]
	v_add_f32_e32 v107, v117, v106
	v_exp_f32_e32 v216, v118
	v_exp_f32_e32 v217, v119
	v_exp_f32_e32 v120, v120
	v_exp_f32_e32 v121, v121
	v_exp_f32_e32 v122, v122
	v_exp_f32_e32 v123, v123
	v_cvt_pk_bf16_f32 v105, v214, v215
	v_cvt_pk_bf16_f32 v106, v116, v117
	ds_read_b128 v[108:111], v181 offset:40032
	ds_read_b128 v[116:119], v181 offset:46688
	s_waitcnt lgkmcnt(3)
	v_mfma_f32_32x32x16_bf16 v[128:143], v[96:99], v[152:155], v[128:143]
	v_add_f32_e32 v96, v216, v103
	v_add_f32_e32 v97, v217, v107
	v_add_f32_e32 v98, v120, v96
	v_add_f32_e32 v97, v121, v97
	v_add_f32_e32 v98, v122, v98
	v_add_f32_e32 v99, v123, v97
	s_waitcnt lgkmcnt(2)
	v_mfma_f32_32x32x16_bf16 v[80:95], v[112:115], v[152:155], v[80:95]
	v_exp_f32_e32 v124, v124
	v_exp_f32_e32 v125, v125
	v_exp_f32_e32 v126, v126
	v_exp_f32_e32 v127, v127
	v_cvt_pk_bf16_f32 v107, v216, v217
	v_cvt_pk_bf16_f32 v96, v120, v121
	v_cvt_pk_bf16_f32 v97, v122, v123
	ds_read_b128 v[112:115], v181 offset:40064
	ds_read_b128 v[120:123], v181 offset:46720
	s_waitcnt lgkmcnt(3)
	v_mfma_f32_32x32x16_bf16 v[128:143], v[108:111], v[156:159], v[128:143]
	v_exp_f32_e32 v103, v64
	v_exp_f32_e32 v213, v65
	v_add_f32_e32 v64, v124, v98
	v_add_f32_e32 v65, v125, v99
	v_exp_f32_e32 v216, v68
	v_exp_f32_e32 v217, v69
	s_waitcnt lgkmcnt(2)
	v_mfma_f32_32x32x16_bf16 v[80:95], v[116:119], v[156:159], v[80:95]
	v_add_f32_e32 v68, v126, v64
	v_add_f32_e32 v69, v127, v65
	v_exp_f32_e32 v214, v66
	v_exp_f32_e32 v215, v67
	v_cvt_pk_bf16_f32 v98, v124, v125
	v_cvt_pk_bf16_f32 v99, v126, v127
	ds_read_b128 v[64:67], v181 offset:40096
	ds_read_b128 v[108:111], v181 offset:46752
	s_waitcnt lgkmcnt(3)
	v_mfma_f32_32x32x16_bf16 v[128:143], v[112:115], v[160:163], v[128:143]
	v_exp_f32_e32 v118, v73
	v_exp_f32_e32 v116, v70
	v_add_f32_e32 v70, v103, v68
	v_add_f32_e32 v69, v213, v69
	v_exp_f32_e32 v117, v72
	v_add_f32_e32 v70, v214, v70
	s_waitcnt lgkmcnt(2)
	v_mfma_f32_32x32x16_bf16 v[80:95], v[120:123], v[160:163], v[80:95]
	v_add_f32_e32 v72, v215, v69
	v_cvt_pk_bf16_f32 v68, v103, v213
	v_add_f32_e32 v103, v216, v70
	v_add_f32_e32 v120, v217, v72
	v_exp_f32_e32 v71, v71
	v_exp_f32_e32 v119, v74
	v_exp_f32_e32 v124, v75
	v_cvt_pk_bf16_f32 v69, v214, v215
	v_cvt_pk_bf16_f32 v70, v216, v217
	ds_read_b128 v[72:75], v211 offset:18432
	ds_read_b128 v[112:115], v211 offset:23040
	s_waitcnt lgkmcnt(3)
	v_mfma_f32_32x32x16_bf16 v[128:143], v[64:67], v[164:167], v[128:143]
	v_add_f32_e32 v64, v116, v103
	v_add_f32_e32 v65, v71, v120
	v_add_f32_e32 v66, v117, v64
	v_add_f32_e32 v65, v118, v65
	v_add_f32_e32 v66, v119, v66
	v_add_f32_e32 v67, v124, v65
	s_waitcnt lgkmcnt(2)
	v_mfma_f32_32x32x16_bf16 v[80:95], v[108:111], v[164:167], v[80:95]
	v_exp_f32_e32 v121, v76
	v_exp_f32_e32 v122, v77
	v_exp_f32_e32 v123, v78
	v_exp_f32_e32 v125, v79
	v_cvt_pk_bf16_f32 v71, v116, v71
	v_cvt_pk_bf16_f32 v64, v117, v118
	v_cvt_pk_bf16_f32 v65, v119, v124
	ds_read_b128 v[76:79], v211 offset:18464
	ds_read_b128 v[108:111], v211 offset:23072
	s_waitcnt lgkmcnt(3)
	v_mfma_f32_32x32x16_bf16 v[0:15], v[72:75], v[104:107], v[0:15]
	v_add_f32_e32 v72, v121, v66
	v_add_f32_e32 v67, v122, v67
	v_add_f32_e32 v103, v123, v72
	v_add_f32_e32 v116, v125, v67
	v_cvt_pk_bf16_f32 v66, v121, v122
	v_cvt_pk_bf16_f32 v67, v123, v125
	s_waitcnt lgkmcnt(2)
	v_mfma_f32_32x32x16_bf16 v[16:31], v[112:115], v[104:107], v[16:31]
	ds_read_b128 v[72:75], v211 offset:18496
	s_waitcnt lgkmcnt(2)
	v_mfma_f32_32x32x16_bf16 v[0:15], v[76:79], v[96:99], v[0:15]
	ds_read_b128 v[76:79], v211 offset:23104
	s_waitcnt lgkmcnt(2)
	v_mfma_f32_32x32x16_bf16 v[16:31], v[108:111], v[96:99], v[16:31]
	ds_read_b128 v[96:99], v211 offset:18528
	ds_read_b128 v[104:107], v211 offset:23136
	s_waitcnt lgkmcnt(3)
	v_mfma_f32_32x32x16_bf16 v[0:15], v[72:75], v[68:71], v[0:15]
	s_waitcnt lgkmcnt(2)
	v_mfma_f32_32x32x16_bf16 v[16:31], v[76:79], v[68:71], v[16:31]
	s_waitcnt lgkmcnt(1)
	v_mfma_f32_32x32x16_bf16 v[0:15], v[96:99], v[64:67], v[0:15]
	v_add_f32_e32 v221, v103, v116
	v_add_f32_e32 v118, v102, v221
	s_waitcnt lgkmcnt(0)
	v_mfma_f32_32x32x16_bf16 v[16:31], v[104:107], v[64:67], v[16:31]
	ds_read_b128 v[64:67], v181
	ds_read_b128 v[112:115], v181 offset:6656
	v_cmp_lt_f32_e32 vcc, s58, v221
	s_cbranch_vccz .LBB0_919
	v_mov_b32_e32 v222, v221
	v_mov_b32_e32 v223, v221
	s_nop 1
	v_permlane32_swap_b32_e32 v222, v223
	v_add_f32_e32 v222, v222, v223
	v_log_f32_e32 v222, v222
	s_nop 0
	v_max_f32_e32 v33, 0, v222
	v_exp_f32_e64 v34, -v33
	v_add_f32_e32 v212, v212, v33
	v_xor_b32_e32 v32, 0x80000000, v212
	v_sub_f32_e32 v143, v143, v33
	v_pk_mul_f32 v[14:15], v[14:15], v[34:35] op_sel_hi:[1,0]
	v_pk_mul_f32 v[12:13], v[12:13], v[34:35] op_sel_hi:[1,0]
	v_pk_mul_f32 v[10:11], v[10:11], v[34:35] op_sel_hi:[1,0]
	v_pk_mul_f32 v[8:9], v[8:9], v[34:35] op_sel_hi:[1,0]
	v_pk_mul_f32 v[6:7], v[6:7], v[34:35] op_sel_hi:[1,0]
	v_pk_mul_f32 v[4:5], v[4:5], v[34:35] op_sel_hi:[1,0]
	v_pk_mul_f32 v[2:3], v[2:3], v[34:35] op_sel_hi:[1,0]
	v_pk_mul_f32 v[0:1], v[0:1], v[34:35] op_sel_hi:[1,0]
	v_pk_mul_f32 v[30:31], v[30:31], v[34:35] op_sel_hi:[1,0]
	v_pk_mul_f32 v[28:29], v[28:29], v[34:35] op_sel_hi:[1,0]
	v_pk_mul_f32 v[26:27], v[26:27], v[34:35] op_sel_hi:[1,0]
	v_pk_mul_f32 v[24:25], v[24:25], v[34:35] op_sel_hi:[1,0]
	v_pk_mul_f32 v[22:23], v[22:23], v[34:35] op_sel_hi:[1,0]
	v_pk_mul_f32 v[20:21], v[20:21], v[34:35] op_sel_hi:[1,0]
	v_pk_mul_f32 v[18:19], v[18:19], v[34:35] op_sel_hi:[1,0]
	v_pk_mul_f32 v[16:17], v[16:17], v[34:35] op_sel_hi:[1,0]
	v_sub_f32_e32 v142, v142, v33
	v_sub_f32_e32 v141, v141, v33
	v_sub_f32_e32 v140, v140, v33
	v_sub_f32_e32 v139, v139, v33
	v_sub_f32_e32 v138, v138, v33
	v_sub_f32_e32 v137, v137, v33
	v_sub_f32_e32 v136, v136, v33
	v_sub_f32_e32 v135, v135, v33
	v_sub_f32_e32 v134, v134, v33
	v_sub_f32_e32 v133, v133, v33
	v_sub_f32_e32 v132, v132, v33
	v_sub_f32_e32 v131, v131, v33
	v_sub_f32_e32 v130, v130, v33
	v_sub_f32_e32 v129, v129, v33
	v_sub_f32_e32 v128, v128, v33
	v_sub_f32_e32 v95, v95, v33
	v_sub_f32_e32 v94, v94, v33
	v_sub_f32_e32 v93, v93, v33
	v_sub_f32_e32 v92, v92, v33
	v_sub_f32_e32 v91, v91, v33
	v_sub_f32_e32 v90, v90, v33
	v_sub_f32_e32 v89, v89, v33
	v_sub_f32_e32 v88, v88, v33
	v_sub_f32_e32 v87, v87, v33
	v_sub_f32_e32 v86, v86, v33
	v_sub_f32_e32 v85, v85, v33
	v_sub_f32_e32 v84, v84, v33
	v_sub_f32_e32 v83, v83, v33
	v_sub_f32_e32 v82, v82, v33
	v_sub_f32_e32 v81, v81, v33
	v_sub_f32_e32 v80, v80, v33
	v_mul_f32_e32 v118, v118, v34
	v_mov_b32_e32 v33, v32
	v_mov_b32_e32 v34, v32
	v_mov_b32_e32 v35, v32
	v_mov_b32_e32 v36, v32
	v_mov_b32_e32 v37, v32
	v_mov_b32_e32 v38, v32
	v_mov_b32_e32 v39, v32
	v_mov_b32_e32 v40, v32
	v_mov_b32_e32 v41, v32
	v_mov_b32_e32 v42, v32
	v_mov_b32_e32 v43, v32
	v_mov_b32_e32 v44, v32
	v_mov_b32_e32 v45, v32
	v_mov_b32_e32 v46, v32
	v_mov_b32_e32 v47, v32
	v_mov_b32_e32 v48, v32
	v_mov_b32_e32 v49, v32
	v_mov_b32_e32 v50, v32
	v_mov_b32_e32 v51, v32
	v_mov_b32_e32 v52, v32
	v_mov_b32_e32 v53, v32
	v_mov_b32_e32 v54, v32
	v_mov_b32_e32 v55, v32
	v_mov_b32_e32 v56, v32
	v_mov_b32_e32 v57, v32
	v_mov_b32_e32 v58, v32
	v_mov_b32_e32 v59, v32
	v_mov_b32_e32 v60, v32
	v_mov_b32_e32 v61, v32
	v_mov_b32_e32 v62, v32
	v_mov_b32_e32 v63, v32

.LBB0_923:
	ds_read_b128 v[120:123], v181 offset:32
	ds_read_b128 v[124:127], v181 offset:6688
	s_waitcnt lgkmcnt(3)
	v_mfma_f32_32x32x16_bf16 v[96:111], v[64:67], v[144:147], v[32:47]
	v_exp_f32_e32 v119, v128
	v_exp_f32_e32 v213, v129
	v_exp_f32_e32 v214, v130
	v_exp_f32_e32 v215, v131
	v_exp_f32_e32 v132, v132
	v_exp_f32_e32 v133, v133
	s_waitcnt lgkmcnt(2)
	v_mfma_f32_32x32x16_bf16 v[64:79], v[112:115], v[144:147], v[32:47]
	ds_read_b128 v[112:115], v181 offset:64
	ds_read_b128 v[128:131], v181 offset:6720
	s_waitcnt lgkmcnt(3)
	v_mfma_f32_32x32x16_bf16 v[96:111], v[120:123], v[148:151], v[96:111]
	v_add_f32_e32 v121, 0, v119
	v_add_f32_e32 v122, 0, v213
	v_cvt_pk_bf16_f32 v120, v119, v213
	v_add_f32_e32 v119, v214, v121
	v_add_f32_e32 v122, v215, v122
	v_add_f32_e32 v119, v132, v119
	s_waitcnt lgkmcnt(2)
	v_mfma_f32_32x32x16_bf16 v[64:79], v[124:127], v[148:151], v[64:79]
	v_add_f32_e32 v123, v133, v122
	v_exp_f32_e32 v216, v134
	v_exp_f32_e32 v217, v135
	v_exp_f32_e32 v136, v136
	v_exp_f32_e32 v137, v137
	v_exp_f32_e32 v138, v138
	v_exp_f32_e32 v139, v139
	v_cvt_pk_bf16_f32 v121, v214, v215
	v_cvt_pk_bf16_f32 v122, v132, v133
	ds_read_b128 v[124:127], v181 offset:96
	ds_read_b128 v[132:135], v181 offset:6752
	s_waitcnt lgkmcnt(3)
	v_mfma_f32_32x32x16_bf16 v[96:111], v[112:115], v[152:155], v[96:111]
	v_add_f32_e32 v112, v216, v119
	v_add_f32_e32 v113, v217, v123
	v_add_f32_e32 v114, v136, v112
	v_add_f32_e32 v113, v137, v113
	v_add_f32_e32 v114, v138, v114
	v_add_f32_e32 v115, v139, v113
	s_waitcnt lgkmcnt(2)
	v_mfma_f32_32x32x16_bf16 v[64:79], v[128:131], v[152:155], v[64:79]
	v_exp_f32_e32 v140, v140
	v_exp_f32_e32 v141, v141
	v_exp_f32_e32 v142, v142
	v_exp_f32_e32 v143, v143
	v_cvt_pk_bf16_f32 v123, v216, v217
	v_cvt_pk_bf16_f32 v112, v136, v137
	v_cvt_pk_bf16_f32 v113, v138, v139
	ds_read_b128 v[128:131], v181 offset:128
	ds_read_b128 v[136:139], v181 offset:6784
	s_waitcnt lgkmcnt(3)
	v_mfma_f32_32x32x16_bf16 v[96:111], v[124:127], v[156:159], v[96:111]
	v_exp_f32_e32 v119, v80
	v_exp_f32_e32 v213, v81
	v_add_f32_e32 v80, v140, v114
	v_add_f32_e32 v81, v141, v115
	v_exp_f32_e32 v216, v84
	v_exp_f32_e32 v217, v85
	s_waitcnt lgkmcnt(2)
	v_mfma_f32_32x32x16_bf16 v[64:79], v[132:135], v[156:159], v[64:79]
	v_add_f32_e32 v84, v142, v80
	v_add_f32_e32 v85, v143, v81
	v_exp_f32_e32 v214, v82
	v_exp_f32_e32 v215, v83
	v_cvt_pk_bf16_f32 v114, v140, v141
	v_cvt_pk_bf16_f32 v115, v142, v143
	ds_read_b128 v[80:83], v181 offset:160
	ds_read_b128 v[124:127], v181 offset:6816
	s_waitcnt lgkmcnt(3)
	v_mfma_f32_32x32x16_bf16 v[96:111], v[128:131], v[160:163], v[96:111]
	v_exp_f32_e32 v132, v86
	v_add_f32_e32 v86, v119, v84
	v_add_f32_e32 v85, v213, v85
	v_exp_f32_e32 v133, v88
	v_add_f32_e32 v86, v214, v86
	v_add_f32_e32 v88, v215, v85
	s_waitcnt lgkmcnt(2)
	v_mfma_f32_32x32x16_bf16 v[64:79], v[136:139], v[160:163], v[64:79]
	v_cvt_pk_bf16_f32 v84, v119, v213
	v_add_f32_e32 v119, v216, v86
	v_add_f32_e32 v136, v217, v88
	v_exp_f32_e32 v87, v87
	v_exp_f32_e32 v134, v89
	v_exp_f32_e32 v135, v90
	v_exp_f32_e32 v140, v91
	v_cvt_pk_bf16_f32 v85, v214, v215
	v_cvt_pk_bf16_f32 v86, v216, v217
	ds_read_b128 v[88:91], v211 offset:27648
	ds_read_b128 v[128:131], v211 offset:32256
	s_waitcnt lgkmcnt(3)
	v_mfma_f32_32x32x16_bf16 v[96:111], v[80:83], v[164:167], v[96:111]
	v_add_f32_e32 v80, v132, v119
	v_add_f32_e32 v81, v87, v136
	v_add_f32_e32 v82, v133, v80
	v_add_f32_e32 v81, v134, v81
	v_add_f32_e32 v82, v135, v82
	v_add_f32_e32 v83, v140, v81
	s_waitcnt lgkmcnt(2)
	v_mfma_f32_32x32x16_bf16 v[64:79], v[124:127], v[164:167], v[64:79]
	v_exp_f32_e32 v137, v92
	v_exp_f32_e32 v138, v93
	v_exp_f32_e32 v139, v94
	v_exp_f32_e32 v141, v95
	v_cvt_pk_bf16_f32 v87, v132, v87
	v_cvt_pk_bf16_f32 v80, v133, v134
	v_cvt_pk_bf16_f32 v81, v135, v140
	ds_read_b128 v[92:95], v211 offset:27680
	ds_read_b128 v[124:127], v211 offset:32288
	s_waitcnt lgkmcnt(3)
	v_mfma_f32_32x32x16_bf16 v[0:15], v[88:91], v[120:123], v[0:15]
	v_add_f32_e32 v88, v137, v82
	v_add_f32_e32 v83, v138, v83
	v_add_f32_e32 v119, v139, v88
	v_add_f32_e32 v132, v141, v83
	v_cvt_pk_bf16_f32 v82, v137, v138
	v_cvt_pk_bf16_f32 v83, v139, v141
	s_waitcnt lgkmcnt(2)
	v_mfma_f32_32x32x16_bf16 v[16:31], v[128:131], v[120:123], v[16:31]
	ds_read_b128 v[88:91], v211 offset:27712
	s_waitcnt lgkmcnt(2)
	v_mfma_f32_32x32x16_bf16 v[0:15], v[92:95], v[112:115], v[0:15]
	ds_read_b128 v[92:95], v211 offset:32320
	s_waitcnt lgkmcnt(2)
	v_mfma_f32_32x32x16_bf16 v[16:31], v[124:127], v[112:115], v[16:31]
	ds_read_b128 v[112:115], v211 offset:27744
	ds_read_b128 v[120:123], v211 offset:32352
	s_waitcnt lgkmcnt(3)
	v_mfma_f32_32x32x16_bf16 v[0:15], v[88:91], v[84:87], v[0:15]
	s_waitcnt lgkmcnt(2)
	v_mfma_f32_32x32x16_bf16 v[16:31], v[92:95], v[84:87], v[16:31]
	s_waitcnt lgkmcnt(1)
	v_mfma_f32_32x32x16_bf16 v[0:15], v[112:115], v[80:83], v[0:15]
	v_add_f32_e32 v221, v119, v132
	v_add_f32_e32 v118, v118, v221
	s_waitcnt lgkmcnt(0)
	v_mfma_f32_32x32x16_bf16 v[16:31], v[120:123], v[80:83], v[16:31]
	s_waitcnt vmcnt(0)
	s_barrier
	ds_read_b128 v[80:83], v181 offset:13312
	ds_read_b128 v[112:115], v181 offset:19968
	v_cmp_lt_f32_e32 vcc, s58, v221
	s_cbranch_vccz .LBB0_925
	v_mov_b32_e32 v222, v221
	v_mov_b32_e32 v223, v221
	s_nop 1
	v_permlane32_swap_b32_e32 v222, v223
	v_add_f32_e32 v222, v222, v223
	v_log_f32_e32 v222, v222
	s_nop 0
	v_max_f32_e32 v33, 0, v222
	v_exp_f32_e64 v34, -v33
	v_add_f32_e32 v212, v212, v33
	v_xor_b32_e32 v32, 0x80000000, v212
	v_sub_f32_e32 v111, v111, v33
	v_pk_mul_f32 v[14:15], v[14:15], v[34:35] op_sel_hi:[1,0]
	v_pk_mul_f32 v[12:13], v[12:13], v[34:35] op_sel_hi:[1,0]
	v_pk_mul_f32 v[10:11], v[10:11], v[34:35] op_sel_hi:[1,0]
	v_pk_mul_f32 v[8:9], v[8:9], v[34:35] op_sel_hi:[1,0]
	v_pk_mul_f32 v[6:7], v[6:7], v[34:35] op_sel_hi:[1,0]
	v_pk_mul_f32 v[4:5], v[4:5], v[34:35] op_sel_hi:[1,0]
	v_pk_mul_f32 v[2:3], v[2:3], v[34:35] op_sel_hi:[1,0]
	v_pk_mul_f32 v[0:1], v[0:1], v[34:35] op_sel_hi:[1,0]
	v_pk_mul_f32 v[30:31], v[30:31], v[34:35] op_sel_hi:[1,0]
	v_pk_mul_f32 v[28:29], v[28:29], v[34:35] op_sel_hi:[1,0]
	v_pk_mul_f32 v[26:27], v[26:27], v[34:35] op_sel_hi:[1,0]
	v_pk_mul_f32 v[24:25], v[24:25], v[34:35] op_sel_hi:[1,0]
	v_pk_mul_f32 v[22:23], v[22:23], v[34:35] op_sel_hi:[1,0]
	v_pk_mul_f32 v[20:21], v[20:21], v[34:35] op_sel_hi:[1,0]
	v_pk_mul_f32 v[18:19], v[18:19], v[34:35] op_sel_hi:[1,0]
	v_pk_mul_f32 v[16:17], v[16:17], v[34:35] op_sel_hi:[1,0]
	v_sub_f32_e32 v110, v110, v33
	v_sub_f32_e32 v109, v109, v33
	v_sub_f32_e32 v108, v108, v33
	v_sub_f32_e32 v107, v107, v33
	v_sub_f32_e32 v106, v106, v33
	v_sub_f32_e32 v105, v105, v33
	v_sub_f32_e32 v104, v104, v33
	v_sub_f32_e32 v103, v103, v33
	v_sub_f32_e32 v102, v102, v33
	v_sub_f32_e32 v101, v101, v33
	v_sub_f32_e32 v100, v100, v33
	v_sub_f32_e32 v99, v99, v33
	v_sub_f32_e32 v98, v98, v33
	v_sub_f32_e32 v97, v97, v33
	v_sub_f32_e32 v96, v96, v33
	v_sub_f32_e32 v79, v79, v33
	v_sub_f32_e32 v78, v78, v33
	v_sub_f32_e32 v77, v77, v33
	v_sub_f32_e32 v76, v76, v33
	v_sub_f32_e32 v75, v75, v33
	v_sub_f32_e32 v74, v74, v33
	v_sub_f32_e32 v73, v73, v33
	v_sub_f32_e32 v72, v72, v33
	v_sub_f32_e32 v71, v71, v33
	v_sub_f32_e32 v70, v70, v33
	v_sub_f32_e32 v69, v69, v33
	v_sub_f32_e32 v68, v68, v33
	v_sub_f32_e32 v67, v67, v33
	v_sub_f32_e32 v66, v66, v33
	v_sub_f32_e32 v65, v65, v33
	v_sub_f32_e32 v64, v64, v33
	v_mul_f32_e32 v118, v118, v34
	v_mov_b32_e32 v33, v32
	v_mov_b32_e32 v34, v32
	v_mov_b32_e32 v35, v32
	v_mov_b32_e32 v36, v32
	v_mov_b32_e32 v37, v32
	v_mov_b32_e32 v38, v32
	v_mov_b32_e32 v39, v32
	v_mov_b32_e32 v40, v32
	v_mov_b32_e32 v41, v32
	v_mov_b32_e32 v42, v32
	v_mov_b32_e32 v43, v32
	v_mov_b32_e32 v44, v32
	v_mov_b32_e32 v45, v32
	v_mov_b32_e32 v46, v32
	v_mov_b32_e32 v47, v32
	v_mov_b32_e32 v48, v32
	v_mov_b32_e32 v49, v32
	v_mov_b32_e32 v50, v32
	v_mov_b32_e32 v51, v32
	v_mov_b32_e32 v52, v32
	v_mov_b32_e32 v53, v32
	v_mov_b32_e32 v54, v32
	v_mov_b32_e32 v55, v32
	v_mov_b32_e32 v56, v32
	v_mov_b32_e32 v57, v32
	v_mov_b32_e32 v58, v32
	v_mov_b32_e32 v59, v32
	v_mov_b32_e32 v60, v32
	v_mov_b32_e32 v61, v32
	v_mov_b32_e32 v62, v32
	v_mov_b32_e32 v63, v32

.LBB0_929:
	ds_read_b128 v[138:141], v181 offset:13344
	ds_read_b128 v[214:217], v181 offset:20000
	s_waitcnt lgkmcnt(3)
	v_mfma_f32_32x32x16_bf16 v[122:137], v[80:83], v[144:147], v[32:47]
	v_exp_f32_e32 v116, v96
	v_exp_f32_e32 v117, v97
	v_exp_f32_e32 v119, v98
	v_exp_f32_e32 v120, v99
	v_exp_f32_e32 v121, v100
	v_exp_f32_e32 v142, v101
	s_waitcnt lgkmcnt(2)
	v_mfma_f32_32x32x16_bf16 v[80:95], v[112:115], v[144:147], v[32:47]
	ds_read_b128 v[96:99], v181 offset:13376
	ds_read_b128 v[112:115], v181 offset:20032
	s_waitcnt lgkmcnt(3)
	v_mfma_f32_32x32x16_bf16 v[122:137], v[138:141], v[148:151], v[122:137]
	v_exp_f32_e32 v143, v102
	v_add_f32_e32 v101, 0, v116
	v_add_f32_e32 v102, 0, v117
	v_exp_f32_e32 v213, v104
	v_add_f32_e32 v104, v119, v101
	v_add_f32_e32 v102, v120, v102
	s_waitcnt lgkmcnt(2)
	v_mfma_f32_32x32x16_bf16 v[80:95], v[214:217], v[148:151], v[80:95]
	v_cvt_pk_bf16_f32 v100, v116, v117
	v_add_f32_e32 v116, v121, v104
	v_add_f32_e32 v117, v142, v102
	v_exp_f32_e32 v103, v103
	v_exp_f32_e32 v218, v105
	v_exp_f32_e32 v219, v106
	v_exp_f32_e32 v220, v107
	v_cvt_pk_bf16_f32 v101, v119, v120
	v_cvt_pk_bf16_f32 v102, v121, v142
	ds_read_b128 v[104:107], v181 offset:13408
	ds_read_b128 v[138:141], v181 offset:20064
	s_waitcnt lgkmcnt(3)
	v_mfma_f32_32x32x16_bf16 v[122:137], v[96:99], v[152:155], v[122:137]
	v_add_f32_e32 v96, v143, v116
	v_add_f32_e32 v97, v103, v117
	v_add_f32_e32 v98, v213, v96
	v_add_f32_e32 v97, v218, v97
	v_add_f32_e32 v98, v219, v98
	v_add_f32_e32 v99, v220, v97
	s_waitcnt lgkmcnt(2)
	v_mfma_f32_32x32x16_bf16 v[80:95], v[112:115], v[152:155], v[80:95]
	v_exp_f32_e32 v119, v108
	v_exp_f32_e32 v120, v109
	v_exp_f32_e32 v121, v110
	v_exp_f32_e32 v142, v111
	v_cvt_pk_bf16_f32 v103, v143, v103
	v_cvt_pk_bf16_f32 v96, v213, v218
	v_cvt_pk_bf16_f32 v97, v219, v220
	ds_read_b128 v[108:111], v181 offset:13440
	ds_read_b128 v[112:115], v181 offset:20096
	s_waitcnt lgkmcnt(3)
	v_mfma_f32_32x32x16_bf16 v[122:137], v[104:107], v[156:159], v[122:137]
	v_exp_f32_e32 v116, v64
	v_exp_f32_e32 v117, v65
	v_add_f32_e32 v64, v119, v98
	v_add_f32_e32 v65, v120, v99
	v_exp_f32_e32 v214, v68
	v_exp_f32_e32 v215, v69
	s_waitcnt lgkmcnt(2)
	v_mfma_f32_32x32x16_bf16 v[80:95], v[138:141], v[156:159], v[80:95]
	v_add_f32_e32 v68, v121, v64
	v_add_f32_e32 v69, v142, v65
	v_exp_f32_e32 v143, v66
	v_exp_f32_e32 v213, v67
	v_cvt_pk_bf16_f32 v98, v119, v120
	v_cvt_pk_bf16_f32 v99, v121, v142
	ds_read_b128 v[64:67], v181 offset:13472
	ds_read_b128 v[104:107], v181 offset:20128
	s_waitcnt lgkmcnt(3)
	v_mfma_f32_32x32x16_bf16 v[122:137], v[108:111], v[160:163], v[122:137]
	v_exp_f32_e32 v119, v70
	v_add_f32_e32 v70, v116, v68
	v_add_f32_e32 v69, v117, v69
	v_exp_f32_e32 v120, v72
	v_add_f32_e32 v70, v143, v70
	v_add_f32_e32 v72, v213, v69
	s_waitcnt lgkmcnt(2)
	v_mfma_f32_32x32x16_bf16 v[80:95], v[112:115], v[160:163], v[80:95]
	v_add_f32_e32 v112, v214, v70
	v_add_f32_e32 v113, v215, v72
	v_exp_f32_e32 v71, v71
	v_exp_f32_e32 v121, v73
	v_exp_f32_e32 v138, v74
	v_exp_f32_e32 v139, v75
	v_cvt_pk_bf16_f32 v68, v116, v117
	v_cvt_pk_bf16_f32 v69, v143, v213
	v_cvt_pk_bf16_f32 v70, v214, v215
	ds_read_b128 v[72:75], v210 offset:53248
	ds_read_b128 v[108:111], v210 offset:57856
	s_waitcnt lgkmcnt(3)
	v_mfma_f32_32x32x16_bf16 v[122:137], v[64:67], v[164:167], v[122:137]
	v_add_f32_e32 v64, v119, v112
	v_add_f32_e32 v65, v71, v113
	v_add_f32_e32 v66, v120, v64
	v_add_f32_e32 v65, v121, v65
	v_add_f32_e32 v66, v138, v66
	v_add_f32_e32 v67, v139, v65
	s_waitcnt lgkmcnt(2)
	v_mfma_f32_32x32x16_bf16 v[80:95], v[104:107], v[164:167], v[80:95]
	v_exp_f32_e32 v114, v76
	v_exp_f32_e32 v115, v77
	v_exp_f32_e32 v116, v78
	v_exp_f32_e32 v117, v79
	v_cvt_pk_bf16_f32 v71, v119, v71
	v_cvt_pk_bf16_f32 v64, v120, v121
	v_cvt_pk_bf16_f32 v65, v138, v139
	ds_read_b128 v[76:79], v210 offset:53280
	ds_read_b128 v[104:107], v210 offset:57888
	s_waitcnt lgkmcnt(3)
	v_mfma_f32_32x32x16_bf16 v[0:15], v[72:75], v[100:103], v[0:15]
	v_add_f32_e32 v72, v114, v66
	v_add_f32_e32 v67, v115, v67
	v_add_f32_e32 v112, v116, v72
	v_add_f32_e32 v113, v117, v67
	v_cvt_pk_bf16_f32 v66, v114, v115
	v_cvt_pk_bf16_f32 v67, v116, v117
	s_waitcnt lgkmcnt(2)
	v_mfma_f32_32x32x16_bf16 v[16:31], v[108:111], v[100:103], v[16:31]
	ds_read_b128 v[72:75], v210 offset:53312
	s_waitcnt lgkmcnt(2)
	v_mfma_f32_32x32x16_bf16 v[0:15], v[76:79], v[96:99], v[0:15]
	ds_read_b128 v[76:79], v210 offset:57920
	s_waitcnt lgkmcnt(2)
	v_mfma_f32_32x32x16_bf16 v[16:31], v[104:107], v[96:99], v[16:31]
	ds_read_b128 v[96:99], v210 offset:53344
	ds_read_b128 v[102:105], v210 offset:57952
	s_waitcnt lgkmcnt(3)
	v_mfma_f32_32x32x16_bf16 v[0:15], v[72:75], v[68:71], v[0:15]
	s_waitcnt lgkmcnt(2)
	v_mfma_f32_32x32x16_bf16 v[16:31], v[76:79], v[68:71], v[16:31]
	s_waitcnt lgkmcnt(1)
	v_mfma_f32_32x32x16_bf16 v[0:15], v[96:99], v[64:67], v[0:15]
	v_add_f32_e32 v221, v112, v113
	v_add_f32_e32 v100, v118, v221
	s_waitcnt lgkmcnt(0)
	v_mfma_f32_32x32x16_bf16 v[16:31], v[102:105], v[64:67], v[16:31]
	ds_read_b128 v[64:67], v181 offset:26624
	ds_read_b128 v[96:99], v181 offset:33280
	v_cmp_lt_f32_e32 vcc, s58, v221
	s_cbranch_vccz .LBB0_931
	v_mov_b32_e32 v222, v221
	v_mov_b32_e32 v223, v221
	s_nop 1
	v_permlane32_swap_b32_e32 v222, v223
	v_add_f32_e32 v222, v222, v223
	v_log_f32_e32 v222, v222
	s_nop 0
	v_max_f32_e32 v33, 0, v222
	v_exp_f32_e64 v34, -v33
	v_add_f32_e32 v212, v212, v33
	v_xor_b32_e32 v32, 0x80000000, v212
	v_sub_f32_e32 v137, v137, v33
	v_pk_mul_f32 v[14:15], v[14:15], v[34:35] op_sel_hi:[1,0]
	v_pk_mul_f32 v[12:13], v[12:13], v[34:35] op_sel_hi:[1,0]
	v_pk_mul_f32 v[10:11], v[10:11], v[34:35] op_sel_hi:[1,0]
	v_pk_mul_f32 v[8:9], v[8:9], v[34:35] op_sel_hi:[1,0]
	v_pk_mul_f32 v[6:7], v[6:7], v[34:35] op_sel_hi:[1,0]
	v_pk_mul_f32 v[4:5], v[4:5], v[34:35] op_sel_hi:[1,0]
	v_pk_mul_f32 v[2:3], v[2:3], v[34:35] op_sel_hi:[1,0]
	v_pk_mul_f32 v[0:1], v[0:1], v[34:35] op_sel_hi:[1,0]
	v_pk_mul_f32 v[30:31], v[30:31], v[34:35] op_sel_hi:[1,0]
	v_pk_mul_f32 v[28:29], v[28:29], v[34:35] op_sel_hi:[1,0]
	v_pk_mul_f32 v[26:27], v[26:27], v[34:35] op_sel_hi:[1,0]
	v_pk_mul_f32 v[24:25], v[24:25], v[34:35] op_sel_hi:[1,0]
	v_pk_mul_f32 v[22:23], v[22:23], v[34:35] op_sel_hi:[1,0]
	v_pk_mul_f32 v[20:21], v[20:21], v[34:35] op_sel_hi:[1,0]
	v_pk_mul_f32 v[18:19], v[18:19], v[34:35] op_sel_hi:[1,0]
	v_pk_mul_f32 v[16:17], v[16:17], v[34:35] op_sel_hi:[1,0]
	v_sub_f32_e32 v136, v136, v33
	v_sub_f32_e32 v135, v135, v33
	v_sub_f32_e32 v134, v134, v33
	v_sub_f32_e32 v133, v133, v33
	v_sub_f32_e32 v132, v132, v33
	v_sub_f32_e32 v131, v131, v33
	v_sub_f32_e32 v130, v130, v33
	v_sub_f32_e32 v129, v129, v33
	v_sub_f32_e32 v128, v128, v33
	v_sub_f32_e32 v127, v127, v33
	v_sub_f32_e32 v126, v126, v33
	v_sub_f32_e32 v125, v125, v33
	v_sub_f32_e32 v124, v124, v33
	v_sub_f32_e32 v123, v123, v33
	v_sub_f32_e32 v122, v122, v33
	v_sub_f32_e32 v95, v95, v33
	v_sub_f32_e32 v94, v94, v33
	v_sub_f32_e32 v93, v93, v33
	v_sub_f32_e32 v92, v92, v33
	v_sub_f32_e32 v91, v91, v33
	v_sub_f32_e32 v90, v90, v33
	v_sub_f32_e32 v89, v89, v33
	v_sub_f32_e32 v88, v88, v33
	v_sub_f32_e32 v87, v87, v33
	v_sub_f32_e32 v86, v86, v33
	v_sub_f32_e32 v85, v85, v33
	v_sub_f32_e32 v84, v84, v33
	v_sub_f32_e32 v83, v83, v33
	v_sub_f32_e32 v82, v82, v33
	v_sub_f32_e32 v81, v81, v33
	v_sub_f32_e32 v80, v80, v33
	v_mul_f32_e32 v100, v100, v34
	v_mov_b32_e32 v33, v32
	v_mov_b32_e32 v34, v32
	v_mov_b32_e32 v35, v32
	v_mov_b32_e32 v36, v32
	v_mov_b32_e32 v37, v32
	v_mov_b32_e32 v38, v32
	v_mov_b32_e32 v39, v32
	v_mov_b32_e32 v40, v32
	v_mov_b32_e32 v41, v32
	v_mov_b32_e32 v42, v32
	v_mov_b32_e32 v43, v32
	v_mov_b32_e32 v44, v32
	v_mov_b32_e32 v45, v32
	v_mov_b32_e32 v46, v32
	v_mov_b32_e32 v47, v32
	v_mov_b32_e32 v48, v32
	v_mov_b32_e32 v49, v32
	v_mov_b32_e32 v50, v32
	v_mov_b32_e32 v51, v32
	v_mov_b32_e32 v52, v32
	v_mov_b32_e32 v53, v32
	v_mov_b32_e32 v54, v32
	v_mov_b32_e32 v55, v32
	v_mov_b32_e32 v56, v32
	v_mov_b32_e32 v57, v32
	v_mov_b32_e32 v58, v32
	v_mov_b32_e32 v59, v32
	v_mov_b32_e32 v60, v32
	v_mov_b32_e32 v61, v32
	v_mov_b32_e32 v62, v32
	v_mov_b32_e32 v63, v32

.LBB0_935:
	ds_read_b128 v[102:105], v181 offset:26656
	ds_read_b128 v[138:141], v181 offset:33312
	s_waitcnt lgkmcnt(3)
	v_mfma_f32_32x32x16_bf16 v[106:121], v[64:67], v[144:147], v[32:47]
	v_exp_f32_e32 v101, v122
	v_exp_f32_e32 v142, v123
	v_exp_f32_e32 v143, v124
	v_exp_f32_e32 v202, v125
	v_exp_f32_e32 v126, v126
	v_exp_f32_e32 v127, v127
	s_waitcnt lgkmcnt(2)
	v_mfma_f32_32x32x16_bf16 v[64:79], v[96:99], v[144:147], v[32:47]
	ds_read_b128 v[96:99], v181 offset:26688
	ds_read_b128 v[122:125], v181 offset:33344
	s_waitcnt lgkmcnt(3)
	v_mfma_f32_32x32x16_bf16 v[106:121], v[102:105], v[148:151], v[106:121]
	v_add_f32_e32 v103, 0, v101
	v_add_f32_e32 v104, 0, v142
	v_cvt_pk_bf16_f32 v102, v101, v142
	v_add_f32_e32 v101, v143, v103
	v_add_f32_e32 v104, v202, v104
	v_add_f32_e32 v101, v126, v101
	s_waitcnt lgkmcnt(2)
	v_mfma_f32_32x32x16_bf16 v[64:79], v[138:141], v[148:151], v[64:79]
	v_add_f32_e32 v105, v127, v104
	v_exp_f32_e32 v203, v128
	v_exp_f32_e32 v204, v129
	v_exp_f32_e32 v205, v130
	v_exp_f32_e32 v213, v131
	v_exp_f32_e32 v214, v132
	v_exp_f32_e32 v215, v133
	v_cvt_pk_bf16_f32 v103, v143, v202
	v_cvt_pk_bf16_f32 v104, v126, v127
	ds_read_b128 v[126:129], v181 offset:26720
	ds_read_b128 v[130:133], v181 offset:33376
	s_waitcnt lgkmcnt(3)
	v_mfma_f32_32x32x16_bf16 v[106:121], v[96:99], v[152:155], v[106:121]
	v_add_f32_e32 v96, v203, v101
	v_add_f32_e32 v97, v204, v105
	v_add_f32_e32 v98, v205, v96
	v_add_f32_e32 v97, v213, v97
	v_add_f32_e32 v98, v214, v98
	v_add_f32_e32 v99, v215, v97
	s_waitcnt lgkmcnt(2)
	v_mfma_f32_32x32x16_bf16 v[64:79], v[122:125], v[152:155], v[64:79]
	v_exp_f32_e32 v138, v134
	v_exp_f32_e32 v139, v135
	v_exp_f32_e32 v140, v136
	v_exp_f32_e32 v141, v137
	v_cvt_pk_bf16_f32 v105, v203, v204
	v_cvt_pk_bf16_f32 v96, v205, v213
	v_cvt_pk_bf16_f32 v97, v214, v215
	ds_read_b128 v[122:125], v181 offset:26752
	ds_read_b128 v[134:137], v181 offset:33408
	s_waitcnt lgkmcnt(3)
	v_mfma_f32_32x32x16_bf16 v[106:121], v[126:129], v[156:159], v[106:121]
	v_exp_f32_e32 v101, v80
	v_exp_f32_e32 v142, v81
	v_add_f32_e32 v80, v138, v98
	v_add_f32_e32 v81, v139, v99
	v_exp_f32_e32 v203, v84
	v_exp_f32_e32 v204, v85
	s_waitcnt lgkmcnt(2)
	v_mfma_f32_32x32x16_bf16 v[64:79], v[130:133], v[156:159], v[64:79]
	v_add_f32_e32 v84, v140, v80
	v_add_f32_e32 v85, v141, v81
	v_exp_f32_e32 v143, v82
	v_exp_f32_e32 v202, v83
	v_cvt_pk_bf16_f32 v98, v138, v139
	v_cvt_pk_bf16_f32 v99, v140, v141
	ds_read_b128 v[80:83], v181 offset:26784
	ds_read_b128 v[126:129], v181 offset:33440
	s_waitcnt lgkmcnt(3)
	v_mfma_f32_32x32x16_bf16 v[106:121], v[122:125], v[160:163], v[106:121]
	v_exp_f32_e32 v87, v87
	v_exp_f32_e32 v130, v86
	v_add_f32_e32 v86, v101, v84
	v_add_f32_e32 v85, v142, v85
	v_exp_f32_e32 v131, v88
	v_add_f32_e32 v86, v143, v86
	s_waitcnt lgkmcnt(2)
	v_mfma_f32_32x32x16_bf16 v[64:79], v[134:137], v[160:163], v[64:79]
	v_add_f32_e32 v88, v202, v85
	v_cvt_pk_bf16_f32 v84, v101, v142
	v_add_f32_e32 v101, v203, v86
	v_add_f32_e32 v134, v204, v88
	v_exp_f32_e32 v132, v89
	v_exp_f32_e32 v133, v90
	v_exp_f32_e32 v138, v91
	v_cvt_pk_bf16_f32 v85, v143, v202
	v_cvt_pk_bf16_f32 v86, v203, v204
	ds_read_b128 v[88:91], v210 offset:62464
	ds_read_b128 v[122:125], v211 offset:13824
	s_waitcnt lgkmcnt(3)
	v_mfma_f32_32x32x16_bf16 v[106:121], v[80:83], v[164:167], v[106:121]
	v_add_f32_e32 v80, v130, v101
	v_add_f32_e32 v81, v87, v134
	v_add_f32_e32 v82, v131, v80
	v_add_f32_e32 v81, v132, v81
	v_add_f32_e32 v82, v133, v82
	v_add_f32_e32 v83, v138, v81
	s_waitcnt lgkmcnt(2)
	v_mfma_f32_32x32x16_bf16 v[64:79], v[126:129], v[164:167], v[64:79]
	v_exp_f32_e32 v135, v92
	v_exp_f32_e32 v136, v93
	v_exp_f32_e32 v137, v94
	v_exp_f32_e32 v139, v95
	v_cvt_pk_bf16_f32 v87, v130, v87
	v_cvt_pk_bf16_f32 v80, v131, v132
	v_cvt_pk_bf16_f32 v81, v133, v138
	ds_read_b128 v[92:95], v210 offset:62496
	ds_read_b128 v[126:129], v211 offset:13856
	s_waitcnt lgkmcnt(3)
	v_mfma_f32_32x32x16_bf16 v[0:15], v[88:91], v[102:105], v[0:15]
	v_add_f32_e32 v88, v135, v82
	v_add_f32_e32 v83, v136, v83
	v_add_f32_e32 v101, v137, v88
	v_add_f32_e32 v130, v139, v83
	v_cvt_pk_bf16_f32 v82, v135, v136
	v_cvt_pk_bf16_f32 v83, v137, v139
	s_waitcnt lgkmcnt(2)
	v_mfma_f32_32x32x16_bf16 v[16:31], v[122:125], v[102:105], v[16:31]
	ds_read_b128 v[88:91], v210 offset:62528
	s_waitcnt lgkmcnt(2)
	v_mfma_f32_32x32x16_bf16 v[0:15], v[92:95], v[96:99], v[0:15]
	ds_read_b128 v[92:95], v211 offset:13888
	s_waitcnt lgkmcnt(2)
	v_mfma_f32_32x32x16_bf16 v[16:31], v[126:129], v[96:99], v[16:31]
	ds_read_b128 v[96:99], v210 offset:62560
	ds_read_b128 v[102:105], v211 offset:13920
	s_waitcnt lgkmcnt(3)
	v_mfma_f32_32x32x16_bf16 v[0:15], v[88:91], v[84:87], v[0:15]
	s_waitcnt lgkmcnt(2)
	v_mfma_f32_32x32x16_bf16 v[16:31], v[92:95], v[84:87], v[16:31]
	s_waitcnt lgkmcnt(1)
	v_mfma_f32_32x32x16_bf16 v[0:15], v[96:99], v[80:83], v[0:15]
	v_add_f32_e32 v221, v101, v130
	v_add_f32_e32 v88, v100, v221
	s_waitcnt lgkmcnt(0)
	v_mfma_f32_32x32x16_bf16 v[16:31], v[102:105], v[80:83], v[16:31]
	s_waitcnt vmcnt(0)
	s_barrier
	ds_read_b128 v[84:87], v181 offset:39936
	ds_read_b128 v[80:83], v181 offset:46592
	v_cmp_lt_f32_e32 vcc, s58, v221
	s_cbranch_vccz .LBB0_937
	v_mov_b32_e32 v222, v221
	v_mov_b32_e32 v223, v221
	s_nop 1
	v_permlane32_swap_b32_e32 v222, v223
	v_add_f32_e32 v222, v222, v223
	v_log_f32_e32 v222, v222
	s_nop 0
	v_max_f32_e32 v33, 0, v222
	v_exp_f32_e64 v34, -v33
	v_add_f32_e32 v212, v212, v33
	v_xor_b32_e32 v32, 0x80000000, v212
	v_sub_f32_e32 v121, v121, v33
	v_pk_mul_f32 v[14:15], v[14:15], v[34:35] op_sel_hi:[1,0]
	v_pk_mul_f32 v[12:13], v[12:13], v[34:35] op_sel_hi:[1,0]
	v_pk_mul_f32 v[10:11], v[10:11], v[34:35] op_sel_hi:[1,0]
	v_pk_mul_f32 v[8:9], v[8:9], v[34:35] op_sel_hi:[1,0]
	v_pk_mul_f32 v[6:7], v[6:7], v[34:35] op_sel_hi:[1,0]
	v_pk_mul_f32 v[4:5], v[4:5], v[34:35] op_sel_hi:[1,0]
	v_pk_mul_f32 v[2:3], v[2:3], v[34:35] op_sel_hi:[1,0]
	v_pk_mul_f32 v[0:1], v[0:1], v[34:35] op_sel_hi:[1,0]
	v_pk_mul_f32 v[30:31], v[30:31], v[34:35] op_sel_hi:[1,0]
	v_pk_mul_f32 v[28:29], v[28:29], v[34:35] op_sel_hi:[1,0]
	v_pk_mul_f32 v[26:27], v[26:27], v[34:35] op_sel_hi:[1,0]
	v_pk_mul_f32 v[24:25], v[24:25], v[34:35] op_sel_hi:[1,0]
	v_pk_mul_f32 v[22:23], v[22:23], v[34:35] op_sel_hi:[1,0]
	v_pk_mul_f32 v[20:21], v[20:21], v[34:35] op_sel_hi:[1,0]
	v_pk_mul_f32 v[18:19], v[18:19], v[34:35] op_sel_hi:[1,0]
	v_pk_mul_f32 v[16:17], v[16:17], v[34:35] op_sel_hi:[1,0]
	v_sub_f32_e32 v120, v120, v33
	v_sub_f32_e32 v119, v119, v33
	v_sub_f32_e32 v118, v118, v33
	v_sub_f32_e32 v117, v117, v33
	v_sub_f32_e32 v116, v116, v33
	v_sub_f32_e32 v115, v115, v33
	v_sub_f32_e32 v114, v114, v33
	v_sub_f32_e32 v113, v113, v33
	v_sub_f32_e32 v112, v112, v33
	v_sub_f32_e32 v111, v111, v33
	v_sub_f32_e32 v110, v110, v33
	v_sub_f32_e32 v109, v109, v33
	v_sub_f32_e32 v108, v108, v33
	v_sub_f32_e32 v107, v107, v33
	v_sub_f32_e32 v106, v106, v33
	v_sub_f32_e32 v79, v79, v33
	v_sub_f32_e32 v78, v78, v33
	v_sub_f32_e32 v77, v77, v33
	v_sub_f32_e32 v76, v76, v33
	v_sub_f32_e32 v75, v75, v33
	v_sub_f32_e32 v74, v74, v33
	v_sub_f32_e32 v73, v73, v33
	v_sub_f32_e32 v72, v72, v33
	v_sub_f32_e32 v71, v71, v33
	v_sub_f32_e32 v70, v70, v33
	v_sub_f32_e32 v69, v69, v33
	v_sub_f32_e32 v68, v68, v33
	v_sub_f32_e32 v67, v67, v33
	v_sub_f32_e32 v66, v66, v33
	v_sub_f32_e32 v65, v65, v33
	v_sub_f32_e32 v64, v64, v33
	v_mul_f32_e32 v88, v88, v34
	v_mov_b32_e32 v33, v32
	v_mov_b32_e32 v34, v32
	v_mov_b32_e32 v35, v32
	v_mov_b32_e32 v36, v32
	v_mov_b32_e32 v37, v32
	v_mov_b32_e32 v38, v32
	v_mov_b32_e32 v39, v32
	v_mov_b32_e32 v40, v32
	v_mov_b32_e32 v41, v32
	v_mov_b32_e32 v42, v32
	v_mov_b32_e32 v43, v32
	v_mov_b32_e32 v44, v32
	v_mov_b32_e32 v45, v32
	v_mov_b32_e32 v46, v32
	v_mov_b32_e32 v47, v32
	v_mov_b32_e32 v48, v32
	v_mov_b32_e32 v49, v32
	v_mov_b32_e32 v50, v32
	v_mov_b32_e32 v51, v32
	v_mov_b32_e32 v52, v32
	v_mov_b32_e32 v53, v32
	v_mov_b32_e32 v54, v32
	v_mov_b32_e32 v55, v32
	v_mov_b32_e32 v56, v32
	v_mov_b32_e32 v57, v32
	v_mov_b32_e32 v58, v32
	v_mov_b32_e32 v59, v32
	v_mov_b32_e32 v60, v32
	v_mov_b32_e32 v61, v32
	v_mov_b32_e32 v62, v32
	v_mov_b32_e32 v63, v32

.LBB0_941:
	s_waitcnt lgkmcnt(1)
	v_mfma_f32_32x32x16_bf16 v[122:137], v[84:87], v[144:147], v[32:47]
	v_exp_f32_e32 v89, v106
	v_exp_f32_e32 v94, v107
	v_exp_f32_e32 v95, v108
	v_exp_f32_e32 v142, v109
	v_exp_f32_e32 v143, v110
	v_exp_f32_e32 v202, v111
	ds_read_b128 v[84:87], v181 offset:39968
	ds_read_b128 v[90:93], v181 offset:46624
	s_waitcnt lgkmcnt(2)
	v_mfma_f32_32x32x16_bf16 v[96:111], v[80:83], v[144:147], v[32:47]
	ds_read_b128 v[80:83], v181 offset:40000
	ds_read_b128 v[138:141], v181 offset:46656
	s_waitcnt lgkmcnt(3)
	v_mfma_f32_32x32x16_bf16 v[122:137], v[84:87], v[148:151], v[122:137]
	v_exp_f32_e32 v116, v116
	v_add_f32_e32 v85, 0, v89
	v_add_f32_e32 v86, 0, v94
	v_add_f32_e32 v87, v95, v85
	v_add_f32_e32 v86, v142, v86
	v_cvt_pk_bf16_f32 v84, v89, v94
	s_waitcnt lgkmcnt(2)
	v_mfma_f32_32x32x16_bf16 v[96:111], v[90:93], v[148:151], v[96:111]
	v_add_f32_e32 v87, v143, v87
	v_add_f32_e32 v89, v202, v86
	v_exp_f32_e32 v203, v112
	v_exp_f32_e32 v204, v113
	v_exp_f32_e32 v205, v114
	v_exp_f32_e32 v213, v115
	v_exp_f32_e32 v117, v117
	v_cvt_pk_bf16_f32 v85, v95, v142
	v_cvt_pk_bf16_f32 v86, v143, v202
	ds_read_b128 v[90:93], v181 offset:40032
	ds_read_b128 v[112:115], v181 offset:46688
	s_waitcnt lgkmcnt(3)
	v_mfma_f32_32x32x16_bf16 v[122:137], v[80:83], v[152:155], v[122:137]
	v_add_f32_e32 v80, v203, v87
	v_add_f32_e32 v81, v204, v89
	v_add_f32_e32 v82, v205, v80
	v_add_f32_e32 v81, v213, v81
	v_add_f32_e32 v82, v116, v82
	v_add_f32_e32 v83, v117, v81
	s_waitcnt lgkmcnt(2)
	v_mfma_f32_32x32x16_bf16 v[96:111], v[138:141], v[152:155], v[96:111]
	v_exp_f32_e32 v94, v118
	v_exp_f32_e32 v95, v119
	v_exp_f32_e32 v120, v120
	v_exp_f32_e32 v121, v121
	v_cvt_pk_bf16_f32 v87, v203, v204
	v_cvt_pk_bf16_f32 v80, v205, v213
	v_cvt_pk_bf16_f32 v81, v116, v117
	ds_read_b128 v[116:119], v181 offset:40064
	ds_read_b128 v[138:141], v181 offset:46720
	s_waitcnt lgkmcnt(3)
	v_mfma_f32_32x32x16_bf16 v[122:137], v[90:93], v[156:159], v[122:137]
	v_exp_f32_e32 v89, v64
	v_exp_f32_e32 v142, v65
	v_add_f32_e32 v64, v94, v82
	v_add_f32_e32 v65, v95, v83
	v_exp_f32_e32 v203, v68
	v_exp_f32_e32 v204, v69
	s_waitcnt lgkmcnt(2)
	v_mfma_f32_32x32x16_bf16 v[96:111], v[112:115], v[156:159], v[96:111]
	v_add_f32_e32 v68, v120, v64
	v_add_f32_e32 v69, v121, v65
	v_exp_f32_e32 v143, v66
	v_exp_f32_e32 v202, v67
	v_cvt_pk_bf16_f32 v82, v94, v95
	v_cvt_pk_bf16_f32 v83, v120, v121
	ds_read_b128 v[64:67], v181 offset:40096
	ds_read_b128 v[90:93], v181 offset:46752
	s_waitcnt lgkmcnt(3)
	v_mfma_f32_32x32x16_bf16 v[122:137], v[116:119], v[160:163], v[122:137]
	v_exp_f32_e32 v116, v74
	v_exp_f32_e32 v94, v70
	v_add_f32_e32 v70, v89, v68
	v_add_f32_e32 v69, v142, v69
	v_exp_f32_e32 v95, v72
	v_add_f32_e32 v70, v143, v70
	s_waitcnt lgkmcnt(2)
	v_mfma_f32_32x32x16_bf16 v[96:111], v[138:141], v[160:163], v[96:111]
	v_add_f32_e32 v72, v202, v69
	v_cvt_pk_bf16_f32 v68, v89, v142
	v_add_f32_e32 v89, v203, v70
	v_add_f32_e32 v118, v204, v72
	v_exp_f32_e32 v71, v71
	v_exp_f32_e32 v120, v73
	v_exp_f32_e32 v117, v75
	v_cvt_pk_bf16_f32 v69, v143, v202
	v_cvt_pk_bf16_f32 v70, v203, v204
	ds_read_b128 v[72:75], v211 offset:18432
	ds_read_b128 v[112:115], v211 offset:23040
	s_waitcnt lgkmcnt(3)
	v_mfma_f32_32x32x16_bf16 v[122:137], v[64:67], v[164:167], v[122:137]
	v_add_f32_e32 v64, v94, v89
	v_add_f32_e32 v65, v71, v118
	v_add_f32_e32 v66, v95, v64
	v_add_f32_e32 v65, v120, v65
	v_add_f32_e32 v66, v116, v66
	v_add_f32_e32 v67, v117, v65
	s_waitcnt lgkmcnt(2)
	v_mfma_f32_32x32x16_bf16 v[96:111], v[90:93], v[164:167], v[96:111]
	v_exp_f32_e32 v119, v76
	v_exp_f32_e32 v121, v77
	v_exp_f32_e32 v138, v78
	v_exp_f32_e32 v139, v79
	v_cvt_pk_bf16_f32 v71, v94, v71
	v_cvt_pk_bf16_f32 v64, v95, v120
	v_cvt_pk_bf16_f32 v65, v116, v117
	ds_read_b128 v[76:79], v211 offset:18464
	ds_read_b128 v[90:93], v211 offset:23072
	s_waitcnt lgkmcnt(3)
	v_mfma_f32_32x32x16_bf16 v[0:15], v[72:75], v[84:87], v[0:15]
	v_add_f32_e32 v72, v119, v66
	v_add_f32_e32 v67, v121, v67
	v_add_f32_e32 v89, v138, v72
	v_add_f32_e32 v94, v139, v67
	v_cvt_pk_bf16_f32 v66, v119, v121
	v_cvt_pk_bf16_f32 v67, v138, v139
	s_waitcnt lgkmcnt(2)
	v_mfma_f32_32x32x16_bf16 v[16:31], v[112:115], v[84:87], v[16:31]
	ds_read_b128 v[72:75], v211 offset:18496
	s_waitcnt lgkmcnt(2)
	v_mfma_f32_32x32x16_bf16 v[0:15], v[76:79], v[80:83], v[0:15]
	ds_read_b128 v[76:79], v211 offset:23104
	s_waitcnt lgkmcnt(2)
	v_mfma_f32_32x32x16_bf16 v[16:31], v[90:93], v[80:83], v[16:31]
	ds_read_b128 v[80:83], v211 offset:18528
	ds_read_b128 v[84:87], v211 offset:23136
	s_waitcnt lgkmcnt(3)
	v_mfma_f32_32x32x16_bf16 v[0:15], v[72:75], v[68:71], v[0:15]
	s_waitcnt lgkmcnt(2)
	v_mfma_f32_32x32x16_bf16 v[16:31], v[76:79], v[68:71], v[16:31]
	s_waitcnt lgkmcnt(1)
	v_mfma_f32_32x32x16_bf16 v[0:15], v[80:83], v[64:67], v[0:15]
	v_add_f32_e32 v221, v89, v94
	v_add_f32_e32 v116, v88, v221
	s_waitcnt lgkmcnt(0)
	v_mfma_f32_32x32x16_bf16 v[16:31], v[84:87], v[64:67], v[16:31]
	ds_read_b128 v[64:67], v181
	ds_read_b128 v[112:115], v181 offset:6656
	v_cmp_lt_f32_e32 vcc, s58, v221
	s_cbranch_vccz .LBB0_943
	v_mov_b32_e32 v222, v221
	v_mov_b32_e32 v223, v221
	s_nop 1
	v_permlane32_swap_b32_e32 v222, v223
	v_add_f32_e32 v222, v222, v223
	v_log_f32_e32 v222, v222
	s_nop 0
	v_max_f32_e32 v33, 0, v222
	v_exp_f32_e64 v34, -v33
	v_add_f32_e32 v212, v212, v33
	v_xor_b32_e32 v32, 0x80000000, v212
	v_sub_f32_e32 v137, v137, v33
	v_pk_mul_f32 v[14:15], v[14:15], v[34:35] op_sel_hi:[1,0]
	v_pk_mul_f32 v[12:13], v[12:13], v[34:35] op_sel_hi:[1,0]
	v_pk_mul_f32 v[10:11], v[10:11], v[34:35] op_sel_hi:[1,0]
	v_pk_mul_f32 v[8:9], v[8:9], v[34:35] op_sel_hi:[1,0]
	v_pk_mul_f32 v[6:7], v[6:7], v[34:35] op_sel_hi:[1,0]
	v_pk_mul_f32 v[4:5], v[4:5], v[34:35] op_sel_hi:[1,0]
	v_pk_mul_f32 v[2:3], v[2:3], v[34:35] op_sel_hi:[1,0]
	v_pk_mul_f32 v[0:1], v[0:1], v[34:35] op_sel_hi:[1,0]
	v_pk_mul_f32 v[30:31], v[30:31], v[34:35] op_sel_hi:[1,0]
	v_pk_mul_f32 v[28:29], v[28:29], v[34:35] op_sel_hi:[1,0]
	v_pk_mul_f32 v[26:27], v[26:27], v[34:35] op_sel_hi:[1,0]
	v_pk_mul_f32 v[24:25], v[24:25], v[34:35] op_sel_hi:[1,0]
	v_pk_mul_f32 v[22:23], v[22:23], v[34:35] op_sel_hi:[1,0]
	v_pk_mul_f32 v[20:21], v[20:21], v[34:35] op_sel_hi:[1,0]
	v_pk_mul_f32 v[18:19], v[18:19], v[34:35] op_sel_hi:[1,0]
	v_pk_mul_f32 v[16:17], v[16:17], v[34:35] op_sel_hi:[1,0]
	v_sub_f32_e32 v136, v136, v33
	v_sub_f32_e32 v135, v135, v33
	v_sub_f32_e32 v134, v134, v33
	v_sub_f32_e32 v133, v133, v33
	v_sub_f32_e32 v132, v132, v33
	v_sub_f32_e32 v131, v131, v33
	v_sub_f32_e32 v130, v130, v33
	v_sub_f32_e32 v129, v129, v33
	v_sub_f32_e32 v128, v128, v33
	v_sub_f32_e32 v127, v127, v33
	v_sub_f32_e32 v126, v126, v33
	v_sub_f32_e32 v125, v125, v33
	v_sub_f32_e32 v124, v124, v33
	v_sub_f32_e32 v123, v123, v33
	v_sub_f32_e32 v122, v122, v33
	v_sub_f32_e32 v111, v111, v33
	v_sub_f32_e32 v110, v110, v33
	v_sub_f32_e32 v109, v109, v33
	v_sub_f32_e32 v108, v108, v33
	v_sub_f32_e32 v107, v107, v33
	v_sub_f32_e32 v106, v106, v33
	v_sub_f32_e32 v105, v105, v33
	v_sub_f32_e32 v104, v104, v33
	v_sub_f32_e32 v103, v103, v33
	v_sub_f32_e32 v102, v102, v33
	v_sub_f32_e32 v101, v101, v33
	v_sub_f32_e32 v100, v100, v33
	v_sub_f32_e32 v99, v99, v33
	v_sub_f32_e32 v98, v98, v33
	v_sub_f32_e32 v97, v97, v33
	v_sub_f32_e32 v96, v96, v33
	v_mul_f32_e32 v116, v116, v34
	v_mov_b32_e32 v33, v32
	v_mov_b32_e32 v34, v32
	v_mov_b32_e32 v35, v32
	v_mov_b32_e32 v36, v32
	v_mov_b32_e32 v37, v32
	v_mov_b32_e32 v38, v32
	v_mov_b32_e32 v39, v32
	v_mov_b32_e32 v40, v32
	v_mov_b32_e32 v41, v32
	v_mov_b32_e32 v42, v32
	v_mov_b32_e32 v43, v32
	v_mov_b32_e32 v44, v32
	v_mov_b32_e32 v45, v32
	v_mov_b32_e32 v46, v32
	v_mov_b32_e32 v47, v32
	v_mov_b32_e32 v48, v32
	v_mov_b32_e32 v49, v32
	v_mov_b32_e32 v50, v32
	v_mov_b32_e32 v51, v32
	v_mov_b32_e32 v52, v32
	v_mov_b32_e32 v53, v32
	v_mov_b32_e32 v54, v32
	v_mov_b32_e32 v55, v32
	v_mov_b32_e32 v56, v32
	v_mov_b32_e32 v57, v32
	v_mov_b32_e32 v58, v32
	v_mov_b32_e32 v59, v32
	v_mov_b32_e32 v60, v32
	v_mov_b32_e32 v61, v32
	v_mov_b32_e32 v62, v32
	v_mov_b32_e32 v63, v32

; template <bool NA>
; __device__ __forceinline__ void attn_unit(LAS unsigned char* lds, const bf16_t* Q, const bf16_t* Kg, const bf16_t* Kr, const bf16_t* Vt, bf16_t* O,
;                                           int h, int seqrow0, int q0, int t0, int NT, int rows, int g0, const float* rpb_h, int wid) {
;     ...
;     const unsigned lds_u = (unsigned)(uintptr_t)lds;
;     const char* dk_src[2] = {nullptr, nullptr}; unsigned dk_str[2] = {0u, 0u}; const char* dv_src[2] = {nullptr, nullptr};
;     {
;         constexpr int CPR = NA ? 9 : 13;
; #pragma unroll
;         for (int j = 0; j < 2; ++j) { const int ci = 64 * (wid + 8 * j) + lane, row = (ci / CPR) & 63, col = ci % CPR;
;             const bool rope = !NA && (col >= 8 && col < 12);
;             dk_src[j] = rope ? (const char*)(Kr + (size_t)(seqrow0 + t0 * 64 + row) * 32 + 8 * (col - 8)) : (const char*)(Kg + (size_t)(seqrow0 + t0 * 64 + row) * 512 + h * 64 + 8 * (col & 7));
;             dk_str[j] = rope ? 64u * 64u : 64u * 1024u; }
; #pragma unroll
;         for (int j = 0; j < 2; ++j) { const int ci = 64 * (wid + 8 * j) + lane, row = ci / 9, col = ci - 9 * row;
;             dv_src[j] = (const char*)(Vt + (size_t)(h * 64 + (row & 63)) * MT + seqrow0 + t0 * 64 + 8 * (col & 7)); }
;     }
; __global__ void __launch_bounds__(512, 2) fwd_kernel(Params P) {
;     ...
;         for (int u = vcu; u < 1024; u += G) {
;             const int pair = u >> 6, qb = u & 63;
;             attn_unit<false>(lds, QM, KN, krope, VTM, MLAO, pair & 7, MP + (pair >> 3) * SS, 256 * qb, 0, SS / 64, 0, 0, nullptr, wave);
.LBB0_948:
	s_cmpk_gt_i32 s33, 0x3ff
	s_cbranch_scc1 .LBB0_1025
	v_readlane_b32 s0, v244, 18
	v_readlane_b32 s1, v244, 19
	s_load_dwordx2 s[0:1], s[0:1], 0xb0
	s_movk_i32 s30, 0xff80
	s_mov_b32 s9, 0
	s_mov_b32 s53, 0x4ec4ec4f
	v_mov_b32_e32 v169, 0
	s_waitcnt lgkmcnt(0)
	s_add_u32 s2, s0, 0x5c00000
	s_addc_u32 s3, s1, 0
	s_add_u32 s48, s0, 0x2cc00000
	s_addc_u32 s49, s1, 0
	s_add_u32 s24, s0, 0x2600000
	s_addc_u32 s25, s1, 0
	s_add_u32 s50, s0, 0x34400000
	s_addc_u32 s51, s1, 0
	s_add_u32 s26, s0, 0x23c00000
	s_addc_u32 s27, s1, 0
	s_lshl_b32 s52, s87, 5
	s_lshl_b32 s6, s87, 10
	s_cmpk_lt_u32 s86, 0x140
	s_cselect_b64 s[0:1], -1, 0
	s_cmp_eq_u32 s86, 0x140
	s_cselect_b64 s[28:29], -1, 0
	v_cndmask_b32_e64 v0, 0, 1, s[0:1]
	s_add_i32 s63, s6, 0
	s_mov_b32 s31, -1
	s_movk_i32 s54, 0x600
	v_mov_b64_e32 v[170:171], s[2:3]
	v_mov_b32_e32 v207, s6
	v_cmp_ne_u32_e64 s[4:5], 1, v0
	s_mov_b32 s55, 0x38e38e39
	s_add_i32 s56, 0, 0xf000
	s_mov_b64 s[34:35], 0x80
	s_add_i32 s57, 0, 0x11400
	s_movk_i32 s58, 0x68
	s_mov_b32 s59, 0x43800000
	s_mov_b32 s60, 0xe0ad78ec
	s_mov_b64 s[36:37], 0x100
	s_add_i32 s61, 0, 0x13800
	s_mov_b64 s[38:39], 0x180
	s_add_i32 s62, 0, 0x15c00
	s_mov_b64 s[40:41], 0x200
	s_mov_b64 s[42:43], 0x280
	s_mov_b64 s[44:45], 0x300
	s_mov_b64 s[46:47], 0x380
	v_mbcnt_hi_u32_b32 v208, -1, v206
	s_add_i32 s64, s63, 0x2000
	s_add_i32 s65, s63, 0xd000
	s_add_i32 s66, s63, 0x3400
	s_add_i32 s67, s63, 0x5400
	s_add_i32 s68, s63, 0x6800
	s_add_i32 s69, s63, 0x8800
	s_add_i32 s70, s63, 0xf400
	s_branch .LBB0_951

; __device__ __forceinline__ unsigned pk2(float lo, float hi) { return pg8::cvt_pk_bf16(lo, hi); }
; template <int LO, int HI> __device__ __forceinline__ void g_exp(f32x16& X) {
; #pragma unroll
;     for (int r = LO; r < HI; ++r) X[r] = __builtin_amdgcn_exp2f(X[r]);
; }
; template <int LO, int HI> __device__ __forceinline__ void g_sumpk(const f32x16& X, float& psa, float& psb, u32x4& pwlo, u32x4& pwhi) {
; #pragma unroll
;     for (int r = LO; r < HI; r += 2) { psa += X[r]; psb += X[r + 1]; const unsigned w = pk2(X[r], X[r + 1]); if (r < 8) pwlo[(r >> 1) & 3] = w; else pwhi[(r >> 1) & 3] = w; }
;     asm volatile("" : "+v"(psa), "+v"(psb));
; }
.LBB0_970:
	ds_read_b128 v[118:121], v181 offset:32
	ds_read_b128 v[138:141], v181 offset:6688
	s_waitcnt lgkmcnt(3)
	v_mfma_f32_32x32x16_bf16 v[80:95], v[64:67], v[144:147], v[32:47]
	v_exp_f32_e32 v117, v122
	v_exp_f32_e32 v142, v123
	v_exp_f32_e32 v143, v124
	v_exp_f32_e32 v202, v125
	v_exp_f32_e32 v126, v126
	v_exp_f32_e32 v127, v127
	s_waitcnt lgkmcnt(2)
	v_mfma_f32_32x32x16_bf16 v[64:79], v[112:115], v[144:147], v[32:47]
	ds_read_b128 v[112:115], v181 offset:64
	ds_read_b128 v[122:125], v181 offset:6720
	s_waitcnt lgkmcnt(3)
	v_mfma_f32_32x32x16_bf16 v[80:95], v[118:121], v[148:151], v[80:95]
	v_add_f32_e32 v119, 0, v117
	v_add_f32_e32 v120, 0, v142
	v_cvt_pk_bf16_f32 v118, v117, v142
	v_add_f32_e32 v117, v143, v119
	v_add_f32_e32 v120, v202, v120
	v_add_f32_e32 v117, v126, v117
	s_waitcnt lgkmcnt(2)
	v_mfma_f32_32x32x16_bf16 v[64:79], v[138:141], v[148:151], v[64:79]
	v_add_f32_e32 v121, v127, v120
	v_exp_f32_e32 v203, v128
	v_exp_f32_e32 v204, v129
	v_exp_f32_e32 v205, v130
	v_exp_f32_e32 v213, v131
	v_exp_f32_e32 v214, v132
	v_exp_f32_e32 v215, v133
	v_cvt_pk_bf16_f32 v119, v143, v202
	v_cvt_pk_bf16_f32 v120, v126, v127
	ds_read_b128 v[126:129], v181 offset:96
	ds_read_b128 v[130:133], v181 offset:6752
	s_waitcnt lgkmcnt(3)
	v_mfma_f32_32x32x16_bf16 v[80:95], v[112:115], v[152:155], v[80:95]
	v_add_f32_e32 v112, v203, v117
	v_add_f32_e32 v113, v204, v121
	v_add_f32_e32 v114, v205, v112
	v_add_f32_e32 v113, v213, v113
	v_add_f32_e32 v114, v214, v114
	v_add_f32_e32 v115, v215, v113
	s_waitcnt lgkmcnt(2)
	v_mfma_f32_32x32x16_bf16 v[64:79], v[122:125], v[152:155], v[64:79]
	v_exp_f32_e32 v138, v134
	v_exp_f32_e32 v139, v135
	v_exp_f32_e32 v140, v136
	v_exp_f32_e32 v141, v137
	v_cvt_pk_bf16_f32 v121, v203, v204
	v_cvt_pk_bf16_f32 v112, v205, v213
	v_cvt_pk_bf16_f32 v113, v214, v215
	ds_read_b128 v[122:125], v181 offset:128
	ds_read_b128 v[134:137], v181 offset:6784
	s_waitcnt lgkmcnt(3)
	v_mfma_f32_32x32x16_bf16 v[80:95], v[126:129], v[156:159], v[80:95]
	v_exp_f32_e32 v117, v96
	v_exp_f32_e32 v142, v97
	v_add_f32_e32 v96, v138, v114
	v_add_f32_e32 v97, v139, v115
	v_exp_f32_e32 v203, v100
	v_exp_f32_e32 v204, v101
	s_waitcnt lgkmcnt(2)
	v_mfma_f32_32x32x16_bf16 v[64:79], v[130:133], v[156:159], v[64:79]
	v_add_f32_e32 v100, v140, v96
	v_add_f32_e32 v101, v141, v97
	v_exp_f32_e32 v143, v98
	v_exp_f32_e32 v202, v99
	v_cvt_pk_bf16_f32 v114, v138, v139
	v_cvt_pk_bf16_f32 v115, v140, v141
	ds_read_b128 v[96:99], v181 offset:160
	ds_read_b128 v[126:129], v181 offset:6816
	s_waitcnt lgkmcnt(3)
	v_mfma_f32_32x32x16_bf16 v[80:95], v[122:125], v[160:163], v[80:95]
	v_exp_f32_e32 v130, v102
	v_add_f32_e32 v102, v117, v100
	v_add_f32_e32 v101, v142, v101
	v_exp_f32_e32 v131, v104
	v_add_f32_e32 v102, v143, v102
	v_add_f32_e32 v104, v202, v101
	s_waitcnt lgkmcnt(2)
	v_mfma_f32_32x32x16_bf16 v[64:79], v[134:137], v[160:163], v[64:79]
	v_cvt_pk_bf16_f32 v100, v117, v142
	v_add_f32_e32 v117, v203, v102
	v_add_f32_e32 v134, v204, v104
	v_exp_f32_e32 v103, v103
	v_exp_f32_e32 v132, v105
	v_exp_f32_e32 v133, v106
	v_exp_f32_e32 v138, v107
	v_cvt_pk_bf16_f32 v101, v143, v202
	v_cvt_pk_bf16_f32 v102, v203, v204
	ds_read_b128 v[104:107], v211 offset:27648
	ds_read_b128 v[122:125], v211 offset:32256
	s_waitcnt lgkmcnt(3)
	v_mfma_f32_32x32x16_bf16 v[80:95], v[96:99], v[164:167], v[80:95]
	v_add_f32_e32 v96, v130, v117
	v_add_f32_e32 v97, v103, v134
	v_add_f32_e32 v98, v131, v96
	v_add_f32_e32 v97, v132, v97
	v_add_f32_e32 v98, v133, v98
	v_add_f32_e32 v99, v138, v97
	s_waitcnt lgkmcnt(2)
	v_mfma_f32_32x32x16_bf16 v[64:79], v[126:129], v[164:167], v[64:79]
	v_exp_f32_e32 v135, v108
	v_exp_f32_e32 v136, v109
	v_exp_f32_e32 v137, v110
	v_exp_f32_e32 v139, v111
	v_cvt_pk_bf16_f32 v103, v130, v103
	v_cvt_pk_bf16_f32 v96, v131, v132
	v_cvt_pk_bf16_f32 v97, v133, v138
	ds_read_b128 v[108:111], v211 offset:27680
	ds_read_b128 v[126:129], v211 offset:32288
	s_waitcnt lgkmcnt(3)
	v_mfma_f32_32x32x16_bf16 v[0:15], v[104:107], v[118:121], v[0:15]
	v_add_f32_e32 v104, v135, v98
	v_add_f32_e32 v99, v136, v99
	v_add_f32_e32 v117, v137, v104
	v_add_f32_e32 v130, v139, v99
	v_cvt_pk_bf16_f32 v98, v135, v136
	v_cvt_pk_bf16_f32 v99, v137, v139
	s_waitcnt lgkmcnt(2)
	v_mfma_f32_32x32x16_bf16 v[16:31], v[122:125], v[118:121], v[16:31]
	ds_read_b128 v[104:107], v211 offset:27712
	s_waitcnt lgkmcnt(2)
	v_mfma_f32_32x32x16_bf16 v[0:15], v[108:111], v[112:115], v[0:15]
	ds_read_b128 v[108:111], v211 offset:32320
	s_waitcnt lgkmcnt(2)
	v_mfma_f32_32x32x16_bf16 v[16:31], v[126:129], v[112:115], v[16:31]
	ds_read_b128 v[112:115], v211 offset:27744
	ds_read_b128 v[118:121], v211 offset:32352
	s_waitcnt lgkmcnt(3)
	v_mfma_f32_32x32x16_bf16 v[0:15], v[104:107], v[100:103], v[0:15]
	s_waitcnt lgkmcnt(2)
	v_mfma_f32_32x32x16_bf16 v[16:31], v[108:111], v[100:103], v[16:31]
	s_waitcnt lgkmcnt(1)
	v_mfma_f32_32x32x16_bf16 v[0:15], v[112:115], v[96:99], v[0:15]
	v_add_f32_e32 v221, v117, v130
	v_add_f32_e32 v116, v116, v221
	s_waitcnt lgkmcnt(0)
	v_mfma_f32_32x32x16_bf16 v[16:31], v[118:121], v[96:99], v[16:31]
	s_waitcnt vmcnt(0)
	s_add_u32 s10, s10, 0x400
	s_addc_u32 s11, s11, 0
	v_lshl_add_u64 v[200:201], v[200:201], 0, v[168:169]
	s_cmpk_lt_u32 s16, 0xf8
	v_lshl_add_u64 v[196:197], v[196:197], 0, v[198:199]
	s_barrier
	s_cbranch_scc0 .LBB0_950
.LBB0_971:
	ds_read_b128 v[96:99], v181 offset:13312
	ds_read_b128 v[112:115], v181 offset:19968
	s_cmp_eq_u32 s10, 0
	s_cbranch_scc1 .LBB0_1024
	v_cmp_lt_f32_e32 vcc, s59, v221
	s_mov_b64 s[14:15], 0
	s_mov_b64 s[12:13], 0
	s_cbranch_vccz .LBB0_974
	v_mov_b32_e32 v222, v221
	v_mov_b32_e32 v223, v221
	s_nop 1
	v_permlane32_swap_b32_e32 v222, v223
	v_add_f32_e32 v222, v222, v223
	v_log_f32_e32 v222, v222
	s_nop 0
	v_max_f32_e32 v101, 0, v222
	s_mov_b64 s[12:13], -1

.LBB0_982:
	ds_read_b128 v[118:121], v181 offset:13344
	ds_read_b128 v[122:125], v181 offset:20000
	s_waitcnt lgkmcnt(3)
	v_mfma_f32_32x32x16_bf16 v[128:143], v[96:99], v[144:147], v[32:47]
	v_exp_f32_e32 v117, v80
	v_exp_f32_e32 v126, v81
	v_exp_f32_e32 v127, v82
	v_exp_f32_e32 v213, v83
	v_exp_f32_e32 v214, v84
	v_exp_f32_e32 v215, v85
	s_waitcnt lgkmcnt(2)
	v_mfma_f32_32x32x16_bf16 v[96:111], v[112:115], v[144:147], v[32:47]
	ds_read_b128 v[80:83], v181 offset:13376
	ds_read_b128 v[112:115], v181 offset:20032
	s_waitcnt lgkmcnt(3)
	v_mfma_f32_32x32x16_bf16 v[128:143], v[118:121], v[148:151], v[128:143]
	v_exp_f32_e32 v216, v86
	v_add_f32_e32 v85, 0, v117
	v_add_f32_e32 v86, 0, v126
	v_exp_f32_e32 v217, v88
	v_add_f32_e32 v88, v127, v85
	v_add_f32_e32 v86, v213, v86
	s_waitcnt lgkmcnt(2)
	v_mfma_f32_32x32x16_bf16 v[96:111], v[122:125], v[148:151], v[96:111]
	v_cvt_pk_bf16_f32 v84, v117, v126
	v_add_f32_e32 v117, v214, v88
	v_add_f32_e32 v122, v215, v86
	v_exp_f32_e32 v87, v87
	v_exp_f32_e32 v218, v89
	v_exp_f32_e32 v219, v90
	v_exp_f32_e32 v220, v91
	v_cvt_pk_bf16_f32 v85, v127, v213
	v_cvt_pk_bf16_f32 v86, v214, v215
	ds_read_b128 v[88:91], v181 offset:13408
	ds_read_b128 v[118:121], v181 offset:20064
	s_waitcnt lgkmcnt(3)
	v_mfma_f32_32x32x16_bf16 v[128:143], v[80:83], v[152:155], v[128:143]
	v_add_f32_e32 v80, v216, v117
	v_add_f32_e32 v81, v87, v122
	v_add_f32_e32 v82, v217, v80
	v_add_f32_e32 v81, v218, v81
	v_add_f32_e32 v82, v219, v82
	v_add_f32_e32 v83, v220, v81
	s_waitcnt lgkmcnt(2)
	v_mfma_f32_32x32x16_bf16 v[96:111], v[112:115], v[152:155], v[96:111]
	v_exp_f32_e32 v123, v92
	v_exp_f32_e32 v124, v93
	v_exp_f32_e32 v125, v94
	v_exp_f32_e32 v126, v95
	v_cvt_pk_bf16_f32 v87, v216, v87
	v_cvt_pk_bf16_f32 v80, v217, v218
	v_cvt_pk_bf16_f32 v81, v219, v220
	ds_read_b128 v[92:95], v181 offset:13440
	ds_read_b128 v[112:115], v181 offset:20096
	s_waitcnt lgkmcnt(3)
	v_mfma_f32_32x32x16_bf16 v[128:143], v[88:91], v[156:159], v[128:143]
	v_exp_f32_e32 v117, v64
	v_exp_f32_e32 v122, v65
	v_add_f32_e32 v64, v123, v82
	v_add_f32_e32 v65, v124, v83
	v_exp_f32_e32 v214, v68
	v_exp_f32_e32 v215, v69
	s_waitcnt lgkmcnt(2)
	v_mfma_f32_32x32x16_bf16 v[96:111], v[118:121], v[156:159], v[96:111]
	v_add_f32_e32 v68, v125, v64
	v_add_f32_e32 v69, v126, v65
	v_exp_f32_e32 v127, v66
	v_exp_f32_e32 v213, v67
	v_cvt_pk_bf16_f32 v82, v123, v124
	v_cvt_pk_bf16_f32 v83, v125, v126
	ds_read_b128 v[64:67], v181 offset:13472
	ds_read_b128 v[88:91], v181 offset:20128
	s_waitcnt lgkmcnt(3)
	v_mfma_f32_32x32x16_bf16 v[128:143], v[92:95], v[160:163], v[128:143]
	v_exp_f32_e32 v118, v70
	v_add_f32_e32 v70, v117, v68
	v_add_f32_e32 v69, v122, v69
	v_exp_f32_e32 v119, v72
	v_add_f32_e32 v70, v127, v70
	v_add_f32_e32 v72, v213, v69
	s_waitcnt lgkmcnt(2)
	v_mfma_f32_32x32x16_bf16 v[96:111], v[112:115], v[160:163], v[96:111]
	v_add_f32_e32 v112, v214, v70
	v_add_f32_e32 v113, v215, v72
	v_exp_f32_e32 v71, v71
	v_exp_f32_e32 v120, v73
	v_exp_f32_e32 v121, v74
	v_exp_f32_e32 v123, v75
	v_cvt_pk_bf16_f32 v68, v117, v122
	v_cvt_pk_bf16_f32 v69, v127, v213
	v_cvt_pk_bf16_f32 v70, v214, v215
	ds_read_b128 v[72:75], v210 offset:53248
	ds_read_b128 v[92:95], v210 offset:57856
	s_waitcnt lgkmcnt(3)
	v_mfma_f32_32x32x16_bf16 v[128:143], v[64:67], v[164:167], v[128:143]
	v_add_f32_e32 v64, v118, v112
	v_add_f32_e32 v65, v71, v113
	v_add_f32_e32 v66, v119, v64
	v_add_f32_e32 v65, v120, v65
	v_add_f32_e32 v66, v121, v66
	v_add_f32_e32 v67, v123, v65
	s_waitcnt lgkmcnt(2)
	v_mfma_f32_32x32x16_bf16 v[96:111], v[88:91], v[164:167], v[96:111]
	v_exp_f32_e32 v114, v76
	v_exp_f32_e32 v115, v77
	v_exp_f32_e32 v117, v78
	v_exp_f32_e32 v122, v79
	v_cvt_pk_bf16_f32 v71, v118, v71
	v_cvt_pk_bf16_f32 v64, v119, v120
	v_cvt_pk_bf16_f32 v65, v121, v123
	ds_read_b128 v[76:79], v210 offset:53280
	ds_read_b128 v[88:91], v210 offset:57888
	s_waitcnt lgkmcnt(3)
	v_mfma_f32_32x32x16_bf16 v[0:15], v[72:75], v[84:87], v[0:15]
	v_add_f32_e32 v72, v114, v66
	v_add_f32_e32 v67, v115, v67
	v_add_f32_e32 v112, v117, v72
	v_add_f32_e32 v113, v122, v67
	v_cvt_pk_bf16_f32 v66, v114, v115
	v_cvt_pk_bf16_f32 v67, v117, v122
	s_waitcnt lgkmcnt(2)
	v_mfma_f32_32x32x16_bf16 v[16:31], v[92:95], v[84:87], v[16:31]
	ds_read_b128 v[72:75], v210 offset:53312
	s_waitcnt lgkmcnt(2)
	v_mfma_f32_32x32x16_bf16 v[0:15], v[76:79], v[80:83], v[0:15]
	ds_read_b128 v[76:79], v210 offset:57920
	s_waitcnt lgkmcnt(2)
	v_mfma_f32_32x32x16_bf16 v[16:31], v[88:91], v[80:83], v[16:31]
	ds_read_b128 v[80:83], v210 offset:53344
	ds_read_b128 v[88:91], v210 offset:57952
	s_waitcnt lgkmcnt(3)
	v_mfma_f32_32x32x16_bf16 v[0:15], v[72:75], v[68:71], v[0:15]
	s_waitcnt lgkmcnt(2)
	v_mfma_f32_32x32x16_bf16 v[16:31], v[76:79], v[68:71], v[16:31]
	s_waitcnt lgkmcnt(1)
	v_mfma_f32_32x32x16_bf16 v[0:15], v[80:83], v[64:67], v[0:15]
	v_add_f32_e32 v221, v112, v113
	v_add_f32_e32 v86, v116, v221
	s_waitcnt lgkmcnt(0)
	v_mfma_f32_32x32x16_bf16 v[16:31], v[88:91], v[64:67], v[16:31]
	ds_read_b128 v[64:67], v181 offset:26624
	ds_read_b128 v[80:83], v181 offset:33280
	v_cmp_lt_f32_e32 vcc, s59, v221
	s_cbranch_vccz .LBB0_984
	v_mov_b32_e32 v222, v221
	v_mov_b32_e32 v223, v221
	s_nop 1
	v_permlane32_swap_b32_e32 v222, v223
	v_add_f32_e32 v222, v222, v223
	v_log_f32_e32 v222, v222
	s_nop 0
	v_max_f32_e32 v33, 0, v222
	v_exp_f32_e64 v34, -v33
	v_add_f32_e32 v212, v212, v33
	v_xor_b32_e32 v32, 0x80000000, v212
	v_sub_f32_e32 v143, v143, v33
	v_pk_mul_f32 v[14:15], v[14:15], v[34:35] op_sel_hi:[1,0]
	v_pk_mul_f32 v[12:13], v[12:13], v[34:35] op_sel_hi:[1,0]
	v_pk_mul_f32 v[10:11], v[10:11], v[34:35] op_sel_hi:[1,0]
	v_pk_mul_f32 v[8:9], v[8:9], v[34:35] op_sel_hi:[1,0]
	v_pk_mul_f32 v[6:7], v[6:7], v[34:35] op_sel_hi:[1,0]
	v_pk_mul_f32 v[4:5], v[4:5], v[34:35] op_sel_hi:[1,0]
	v_pk_mul_f32 v[2:3], v[2:3], v[34:35] op_sel_hi:[1,0]
	v_pk_mul_f32 v[0:1], v[0:1], v[34:35] op_sel_hi:[1,0]
	v_pk_mul_f32 v[30:31], v[30:31], v[34:35] op_sel_hi:[1,0]
	v_pk_mul_f32 v[28:29], v[28:29], v[34:35] op_sel_hi:[1,0]
	v_pk_mul_f32 v[26:27], v[26:27], v[34:35] op_sel_hi:[1,0]
	v_pk_mul_f32 v[24:25], v[24:25], v[34:35] op_sel_hi:[1,0]
	v_pk_mul_f32 v[22:23], v[22:23], v[34:35] op_sel_hi:[1,0]
	v_pk_mul_f32 v[20:21], v[20:21], v[34:35] op_sel_hi:[1,0]
	v_pk_mul_f32 v[18:19], v[18:19], v[34:35] op_sel_hi:[1,0]
	v_pk_mul_f32 v[16:17], v[16:17], v[34:35] op_sel_hi:[1,0]
	v_sub_f32_e32 v142, v142, v33
	v_sub_f32_e32 v141, v141, v33
	v_sub_f32_e32 v140, v140, v33
	v_sub_f32_e32 v139, v139, v33
	v_sub_f32_e32 v138, v138, v33
	v_sub_f32_e32 v137, v137, v33
	v_sub_f32_e32 v136, v136, v33
	v_sub_f32_e32 v135, v135, v33
	v_sub_f32_e32 v134, v134, v33
	v_sub_f32_e32 v133, v133, v33
	v_sub_f32_e32 v132, v132, v33
	v_sub_f32_e32 v131, v131, v33
	v_sub_f32_e32 v130, v130, v33
	v_sub_f32_e32 v129, v129, v33
	v_sub_f32_e32 v128, v128, v33
	v_sub_f32_e32 v111, v111, v33
	v_sub_f32_e32 v110, v110, v33
	v_sub_f32_e32 v109, v109, v33
	v_sub_f32_e32 v108, v108, v33
	v_sub_f32_e32 v107, v107, v33
	v_sub_f32_e32 v106, v106, v33
	v_sub_f32_e32 v105, v105, v33
	v_sub_f32_e32 v104, v104, v33
	v_sub_f32_e32 v103, v103, v33
	v_sub_f32_e32 v102, v102, v33
	v_sub_f32_e32 v101, v101, v33
	v_sub_f32_e32 v100, v100, v33
	v_sub_f32_e32 v99, v99, v33
	v_sub_f32_e32 v98, v98, v33
	v_sub_f32_e32 v97, v97, v33
	v_sub_f32_e32 v96, v96, v33
	v_mul_f32_e32 v86, v86, v34
	v_mov_b32_e32 v33, v32
	v_mov_b32_e32 v34, v32
	v_mov_b32_e32 v35, v32
	v_mov_b32_e32 v36, v32
	v_mov_b32_e32 v37, v32
	v_mov_b32_e32 v38, v32
	v_mov_b32_e32 v39, v32
	v_mov_b32_e32 v40, v32
	v_mov_b32_e32 v41, v32
	v_mov_b32_e32 v42, v32
	v_mov_b32_e32 v43, v32
	v_mov_b32_e32 v44, v32
	v_mov_b32_e32 v45, v32
	v_mov_b32_e32 v46, v32
	v_mov_b32_e32 v47, v32
	v_mov_b32_e32 v48, v32
	v_mov_b32_e32 v49, v32
	v_mov_b32_e32 v50, v32
	v_mov_b32_e32 v51, v32
	v_mov_b32_e32 v52, v32
	v_mov_b32_e32 v53, v32
	v_mov_b32_e32 v54, v32
	v_mov_b32_e32 v55, v32
	v_mov_b32_e32 v56, v32
	v_mov_b32_e32 v57, v32
	v_mov_b32_e32 v58, v32
	v_mov_b32_e32 v59, v32
	v_mov_b32_e32 v60, v32
	v_mov_b32_e32 v61, v32
	v_mov_b32_e32 v62, v32
	v_mov_b32_e32 v63, v32

.LBB0_988:
	ds_read_b128 v[88:91], v181 offset:26656
	ds_read_b128 v[92:95], v181 offset:33312
	s_waitcnt lgkmcnt(3)
	v_mfma_f32_32x32x16_bf16 v[112:127], v[64:67], v[144:147], v[32:47]
	v_exp_f32_e32 v87, v128
	v_exp_f32_e32 v213, v129
	v_exp_f32_e32 v214, v130
	v_exp_f32_e32 v215, v131
	v_exp_f32_e32 v132, v132
	v_exp_f32_e32 v133, v133
	s_waitcnt lgkmcnt(2)
	v_mfma_f32_32x32x16_bf16 v[64:79], v[80:83], v[144:147], v[32:47]
	ds_read_b128 v[80:83], v181 offset:26688
	ds_read_b128 v[128:131], v181 offset:33344
	s_waitcnt lgkmcnt(3)
	v_mfma_f32_32x32x16_bf16 v[112:127], v[88:91], v[148:151], v[112:127]
	v_add_f32_e32 v89, 0, v87
	v_add_f32_e32 v90, 0, v213
	v_cvt_pk_bf16_f32 v88, v87, v213
	v_add_f32_e32 v87, v214, v89
	v_add_f32_e32 v90, v215, v90
	v_add_f32_e32 v87, v132, v87
	s_waitcnt lgkmcnt(2)
	v_mfma_f32_32x32x16_bf16 v[64:79], v[92:95], v[148:151], v[64:79]
	v_add_f32_e32 v91, v133, v90
	v_exp_f32_e32 v216, v134
	v_exp_f32_e32 v217, v135
	v_exp_f32_e32 v136, v136
	v_exp_f32_e32 v137, v137
	v_exp_f32_e32 v138, v138
	v_exp_f32_e32 v139, v139
	v_cvt_pk_bf16_f32 v89, v214, v215
	v_cvt_pk_bf16_f32 v90, v132, v133
	ds_read_b128 v[92:95], v181 offset:26720
	ds_read_b128 v[132:135], v181 offset:33376
	s_waitcnt lgkmcnt(3)
	v_mfma_f32_32x32x16_bf16 v[112:127], v[80:83], v[152:155], v[112:127]
	v_add_f32_e32 v80, v216, v87
	v_add_f32_e32 v81, v217, v91
	v_add_f32_e32 v82, v136, v80
	v_add_f32_e32 v81, v137, v81
	v_add_f32_e32 v82, v138, v82
	v_add_f32_e32 v83, v139, v81
	s_waitcnt lgkmcnt(2)
	v_mfma_f32_32x32x16_bf16 v[64:79], v[128:131], v[152:155], v[64:79]
	v_exp_f32_e32 v140, v140
	v_exp_f32_e32 v141, v141
	v_exp_f32_e32 v142, v142
	v_exp_f32_e32 v143, v143
	v_cvt_pk_bf16_f32 v91, v216, v217
	v_cvt_pk_bf16_f32 v80, v136, v137
	v_cvt_pk_bf16_f32 v81, v138, v139
	ds_read_b128 v[128:131], v181 offset:26752
	ds_read_b128 v[136:139], v181 offset:33408
	s_waitcnt lgkmcnt(3)
	v_mfma_f32_32x32x16_bf16 v[112:127], v[92:95], v[156:159], v[112:127]
	v_exp_f32_e32 v87, v96
	v_add_f32_e32 v92, v140, v82
	v_add_f32_e32 v83, v141, v83
	v_exp_f32_e32 v216, v100
	v_exp_f32_e32 v217, v101
	v_add_f32_e32 v100, v142, v92
	s_waitcnt lgkmcnt(2)
	v_mfma_f32_32x32x16_bf16 v[64:79], v[132:135], v[156:159], v[64:79]
	v_add_f32_e32 v101, v143, v83
	v_exp_f32_e32 v213, v97
	v_exp_f32_e32 v214, v98
	v_exp_f32_e32 v215, v99
	v_cvt_pk_bf16_f32 v82, v140, v141
	v_cvt_pk_bf16_f32 v83, v142, v143
	ds_read_b128 v[92:95], v181 offset:26784
	ds_read_b128 v[96:99], v181 offset:33440
	s_waitcnt lgkmcnt(3)
	v_mfma_f32_32x32x16_bf16 v[112:127], v[128:131], v[160:163], v[112:127]
	v_exp_f32_e32 v132, v102
	v_add_f32_e32 v102, v87, v100
	v_add_f32_e32 v101, v213, v101
	v_cvt_pk_bf16_f32 v100, v87, v213
	v_add_f32_e32 v87, v214, v102
	v_add_f32_e32 v102, v215, v101
	s_waitcnt lgkmcnt(2)
	v_mfma_f32_32x32x16_bf16 v[64:79], v[136:139], v[160:163], v[64:79]
	v_add_f32_e32 v87, v216, v87
	v_add_f32_e32 v136, v217, v102
	v_exp_f32_e32 v103, v103
	v_exp_f32_e32 v133, v104
	v_exp_f32_e32 v134, v105
	v_exp_f32_e32 v135, v106
	v_exp_f32_e32 v140, v107
	v_cvt_pk_bf16_f32 v101, v214, v215
	v_cvt_pk_bf16_f32 v102, v216, v217
	ds_read_b128 v[104:107], v210 offset:62464
	ds_read_b128 v[128:131], v211 offset:13824
	s_waitcnt lgkmcnt(3)
	v_mfma_f32_32x32x16_bf16 v[112:127], v[92:95], v[164:167], v[112:127]
	v_add_f32_e32 v87, v132, v87
	v_add_f32_e32 v92, v103, v136
	v_add_f32_e32 v87, v133, v87
	v_add_f32_e32 v93, v134, v92
	v_add_f32_e32 v87, v135, v87
	v_add_f32_e32 v94, v140, v93
	s_waitcnt lgkmcnt(2)
	v_mfma_f32_32x32x16_bf16 v[64:79], v[96:99], v[164:167], v[64:79]
	v_exp_f32_e32 v137, v108
	v_exp_f32_e32 v138, v109
	v_exp_f32_e32 v139, v110
	v_exp_f32_e32 v141, v111
	v_cvt_pk_bf16_f32 v103, v132, v103
	v_cvt_pk_bf16_f32 v92, v133, v134
	v_cvt_pk_bf16_f32 v93, v135, v140
	ds_read_b128 v[96:99], v210 offset:62496
	ds_read_b128 v[108:111], v211 offset:13856
	s_waitcnt lgkmcnt(3)
	v_mfma_f32_32x32x16_bf16 v[0:15], v[104:107], v[88:91], v[0:15]
	v_add_f32_e32 v87, v137, v87
	v_add_f32_e32 v95, v138, v94
	v_add_f32_e32 v132, v139, v87
	v_add_f32_e32 v133, v141, v95
	v_cvt_pk_bf16_f32 v94, v137, v138
	v_cvt_pk_bf16_f32 v95, v139, v141
	s_waitcnt lgkmcnt(2)
	v_mfma_f32_32x32x16_bf16 v[16:31], v[128:131], v[88:91], v[16:31]
	ds_read_b128 v[88:91], v210 offset:62528
	s_waitcnt lgkmcnt(2)
	v_mfma_f32_32x32x16_bf16 v[0:15], v[96:99], v[80:83], v[0:15]
	ds_read_b128 v[96:99], v211 offset:13888
	s_waitcnt lgkmcnt(2)
	v_mfma_f32_32x32x16_bf16 v[16:31], v[108:111], v[80:83], v[16:31]
	ds_read_b128 v[80:83], v210 offset:62560
	ds_read_b128 v[104:107], v211 offset:13920
	s_waitcnt lgkmcnt(3)
	v_mfma_f32_32x32x16_bf16 v[0:15], v[88:91], v[100:103], v[0:15]
	s_waitcnt lgkmcnt(2)
	v_mfma_f32_32x32x16_bf16 v[16:31], v[96:99], v[100:103], v[16:31]
	s_waitcnt lgkmcnt(1)
	v_mfma_f32_32x32x16_bf16 v[0:15], v[80:83], v[92:95], v[0:15]
	v_add_f32_e32 v221, v132, v133
	v_add_f32_e32 v102, v86, v221
	s_waitcnt lgkmcnt(0)
	v_mfma_f32_32x32x16_bf16 v[16:31], v[104:107], v[92:95], v[16:31]
	s_waitcnt vmcnt(0)
	s_barrier
	ds_read_b128 v[80:83], v181 offset:39936
	ds_read_b128 v[96:99], v181 offset:46592
	v_cmp_lt_f32_e32 vcc, s59, v221
	s_cbranch_vccz .LBB0_990
	v_mov_b32_e32 v222, v221
	v_mov_b32_e32 v223, v221
	s_nop 1
	v_permlane32_swap_b32_e32 v222, v223
	v_add_f32_e32 v222, v222, v223
	v_log_f32_e32 v222, v222
	s_nop 0
	v_max_f32_e32 v33, 0, v222
	v_exp_f32_e64 v34, -v33
	v_add_f32_e32 v212, v212, v33
	v_xor_b32_e32 v32, 0x80000000, v212
	v_sub_f32_e32 v127, v127, v33
	v_pk_mul_f32 v[14:15], v[14:15], v[34:35] op_sel_hi:[1,0]
	v_pk_mul_f32 v[12:13], v[12:13], v[34:35] op_sel_hi:[1,0]
	v_pk_mul_f32 v[10:11], v[10:11], v[34:35] op_sel_hi:[1,0]
	v_pk_mul_f32 v[8:9], v[8:9], v[34:35] op_sel_hi:[1,0]
	v_pk_mul_f32 v[6:7], v[6:7], v[34:35] op_sel_hi:[1,0]
	v_pk_mul_f32 v[4:5], v[4:5], v[34:35] op_sel_hi:[1,0]
	v_pk_mul_f32 v[2:3], v[2:3], v[34:35] op_sel_hi:[1,0]
	v_pk_mul_f32 v[0:1], v[0:1], v[34:35] op_sel_hi:[1,0]
	v_pk_mul_f32 v[30:31], v[30:31], v[34:35] op_sel_hi:[1,0]
	v_pk_mul_f32 v[28:29], v[28:29], v[34:35] op_sel_hi:[1,0]
	v_pk_mul_f32 v[26:27], v[26:27], v[34:35] op_sel_hi:[1,0]
	v_pk_mul_f32 v[24:25], v[24:25], v[34:35] op_sel_hi:[1,0]
	v_pk_mul_f32 v[22:23], v[22:23], v[34:35] op_sel_hi:[1,0]
	v_pk_mul_f32 v[20:21], v[20:21], v[34:35] op_sel_hi:[1,0]
	v_pk_mul_f32 v[18:19], v[18:19], v[34:35] op_sel_hi:[1,0]
	v_pk_mul_f32 v[16:17], v[16:17], v[34:35] op_sel_hi:[1,0]
	v_sub_f32_e32 v126, v126, v33
	v_sub_f32_e32 v125, v125, v33
	v_sub_f32_e32 v124, v124, v33
	v_sub_f32_e32 v123, v123, v33
	v_sub_f32_e32 v122, v122, v33
	v_sub_f32_e32 v121, v121, v33
	v_sub_f32_e32 v120, v120, v33
	v_sub_f32_e32 v119, v119, v33
	v_sub_f32_e32 v118, v118, v33
	v_sub_f32_e32 v117, v117, v33
	v_sub_f32_e32 v116, v116, v33
	v_sub_f32_e32 v115, v115, v33
	v_sub_f32_e32 v114, v114, v33
	v_sub_f32_e32 v113, v113, v33
	v_sub_f32_e32 v112, v112, v33
	v_sub_f32_e32 v79, v79, v33
	v_sub_f32_e32 v78, v78, v33
	v_sub_f32_e32 v77, v77, v33
	v_sub_f32_e32 v76, v76, v33
	v_sub_f32_e32 v75, v75, v33
	v_sub_f32_e32 v74, v74, v33
	v_sub_f32_e32 v73, v73, v33
	v_sub_f32_e32 v72, v72, v33
	v_sub_f32_e32 v71, v71, v33
	v_sub_f32_e32 v70, v70, v33
	v_sub_f32_e32 v69, v69, v33
	v_sub_f32_e32 v68, v68, v33
	v_sub_f32_e32 v67, v67, v33
	v_sub_f32_e32 v66, v66, v33
	v_sub_f32_e32 v65, v65, v33
	v_sub_f32_e32 v64, v64, v33
	v_mul_f32_e32 v102, v102, v34
	v_mov_b32_e32 v33, v32
	v_mov_b32_e32 v34, v32
	v_mov_b32_e32 v35, v32
	v_mov_b32_e32 v36, v32
	v_mov_b32_e32 v37, v32
	v_mov_b32_e32 v38, v32
	v_mov_b32_e32 v39, v32
	v_mov_b32_e32 v40, v32
	v_mov_b32_e32 v41, v32
	v_mov_b32_e32 v42, v32
	v_mov_b32_e32 v43, v32
	v_mov_b32_e32 v44, v32
	v_mov_b32_e32 v45, v32
	v_mov_b32_e32 v46, v32
	v_mov_b32_e32 v47, v32
	v_mov_b32_e32 v48, v32
	v_mov_b32_e32 v49, v32
	v_mov_b32_e32 v50, v32
	v_mov_b32_e32 v51, v32
	v_mov_b32_e32 v52, v32
	v_mov_b32_e32 v53, v32
	v_mov_b32_e32 v54, v32
	v_mov_b32_e32 v55, v32
	v_mov_b32_e32 v56, v32
	v_mov_b32_e32 v57, v32
	v_mov_b32_e32 v58, v32
	v_mov_b32_e32 v59, v32
	v_mov_b32_e32 v60, v32
	v_mov_b32_e32 v61, v32
	v_mov_b32_e32 v62, v32
	v_mov_b32_e32 v63, v32

.LBB0_994:
	ds_read_b128 v[104:107], v181 offset:39968
	ds_read_b128 v[108:111], v181 offset:46624
	s_waitcnt lgkmcnt(3)
	v_mfma_f32_32x32x16_bf16 v[128:143], v[80:83], v[144:147], v[32:47]
	v_exp_f32_e32 v103, v112
	v_exp_f32_e32 v213, v113
	v_exp_f32_e32 v214, v114
	v_exp_f32_e32 v215, v115
	v_exp_f32_e32 v116, v116
	v_exp_f32_e32 v117, v117
	s_waitcnt lgkmcnt(2)
	v_mfma_f32_32x32x16_bf16 v[80:95], v[96:99], v[144:147], v[32:47]
	ds_read_b128 v[96:99], v181 offset:40000
	ds_read_b128 v[112:115], v181 offset:46656
	s_waitcnt lgkmcnt(3)
	v_mfma_f32_32x32x16_bf16 v[128:143], v[104:107], v[148:151], v[128:143]
	v_add_f32_e32 v105, 0, v103
	v_add_f32_e32 v106, 0, v213
	v_cvt_pk_bf16_f32 v104, v103, v213
	v_add_f32_e32 v103, v214, v105
	v_add_f32_e32 v106, v215, v106
	v_add_f32_e32 v103, v116, v103
	s_waitcnt lgkmcnt(2)
	v_mfma_f32_32x32x16_bf16 v[80:95], v[108:111], v[148:151], v[80:95]
	v_add_f32_e32 v107, v117, v106
	v_exp_f32_e32 v216, v118
	v_exp_f32_e32 v217, v119
	v_exp_f32_e32 v120, v120
	v_exp_f32_e32 v121, v121
	v_exp_f32_e32 v122, v122
	v_exp_f32_e32 v123, v123
	v_cvt_pk_bf16_f32 v105, v214, v215
	v_cvt_pk_bf16_f32 v106, v116, v117
	ds_read_b128 v[108:111], v181 offset:40032
	ds_read_b128 v[116:119], v181 offset:46688
	s_waitcnt lgkmcnt(3)
	v_mfma_f32_32x32x16_bf16 v[128:143], v[96:99], v[152:155], v[128:143]
	v_add_f32_e32 v96, v216, v103
	v_add_f32_e32 v97, v217, v107
	v_add_f32_e32 v98, v120, v96
	v_add_f32_e32 v97, v121, v97
	v_add_f32_e32 v98, v122, v98
	v_add_f32_e32 v99, v123, v97
	s_waitcnt lgkmcnt(2)
	v_mfma_f32_32x32x16_bf16 v[80:95], v[112:115], v[152:155], v[80:95]
	v_exp_f32_e32 v124, v124
	v_exp_f32_e32 v125, v125
	v_exp_f32_e32 v126, v126
	v_exp_f32_e32 v127, v127
	v_cvt_pk_bf16_f32 v107, v216, v217
	v_cvt_pk_bf16_f32 v96, v120, v121
	v_cvt_pk_bf16_f32 v97, v122, v123
	ds_read_b128 v[112:115], v181 offset:40064
	ds_read_b128 v[120:123], v181 offset:46720
	s_waitcnt lgkmcnt(3)
	v_mfma_f32_32x32x16_bf16 v[128:143], v[108:111], v[156:159], v[128:143]
	v_exp_f32_e32 v103, v64
	v_exp_f32_e32 v213, v65
	v_add_f32_e32 v64, v124, v98
	v_add_f32_e32 v65, v125, v99
	v_exp_f32_e32 v216, v68
	v_exp_f32_e32 v217, v69
	s_waitcnt lgkmcnt(2)
	v_mfma_f32_32x32x16_bf16 v[80:95], v[116:119], v[156:159], v[80:95]
	v_add_f32_e32 v68, v126, v64
	v_add_f32_e32 v69, v127, v65
	v_exp_f32_e32 v214, v66
	v_exp_f32_e32 v215, v67
	v_cvt_pk_bf16_f32 v98, v124, v125
	v_cvt_pk_bf16_f32 v99, v126, v127
	ds_read_b128 v[64:67], v181 offset:40096
	ds_read_b128 v[108:111], v181 offset:46752
	s_waitcnt lgkmcnt(3)
	v_mfma_f32_32x32x16_bf16 v[128:143], v[112:115], v[160:163], v[128:143]
	v_exp_f32_e32 v118, v73
	v_exp_f32_e32 v116, v70
	v_add_f32_e32 v70, v103, v68
	v_add_f32_e32 v69, v213, v69
	v_exp_f32_e32 v117, v72
	v_add_f32_e32 v70, v214, v70
	s_waitcnt lgkmcnt(2)
	v_mfma_f32_32x32x16_bf16 v[80:95], v[120:123], v[160:163], v[80:95]
	v_add_f32_e32 v72, v215, v69
	v_cvt_pk_bf16_f32 v68, v103, v213
	v_add_f32_e32 v103, v216, v70
	v_add_f32_e32 v120, v217, v72
	v_exp_f32_e32 v71, v71
	v_exp_f32_e32 v119, v74
	v_exp_f32_e32 v124, v75
	v_cvt_pk_bf16_f32 v69, v214, v215
	v_cvt_pk_bf16_f32 v70, v216, v217
	ds_read_b128 v[72:75], v211 offset:18432
	ds_read_b128 v[112:115], v211 offset:23040
	s_waitcnt lgkmcnt(3)
	v_mfma_f32_32x32x16_bf16 v[128:143], v[64:67], v[164:167], v[128:143]
	v_add_f32_e32 v64, v116, v103
	v_add_f32_e32 v65, v71, v120
	v_add_f32_e32 v66, v117, v64
	v_add_f32_e32 v65, v118, v65
	v_add_f32_e32 v66, v119, v66
	v_add_f32_e32 v67, v124, v65
	s_waitcnt lgkmcnt(2)
	v_mfma_f32_32x32x16_bf16 v[80:95], v[108:111], v[164:167], v[80:95]
	v_exp_f32_e32 v121, v76
	v_exp_f32_e32 v122, v77
	v_exp_f32_e32 v123, v78
	v_exp_f32_e32 v125, v79
	v_cvt_pk_bf16_f32 v71, v116, v71
	v_cvt_pk_bf16_f32 v64, v117, v118
	v_cvt_pk_bf16_f32 v65, v119, v124
	ds_read_b128 v[76:79], v211 offset:18464
	ds_read_b128 v[108:111], v211 offset:23072
	s_waitcnt lgkmcnt(3)
	v_mfma_f32_32x32x16_bf16 v[0:15], v[72:75], v[104:107], v[0:15]
	v_add_f32_e32 v72, v121, v66
	v_add_f32_e32 v67, v122, v67
	v_add_f32_e32 v103, v123, v72
	v_add_f32_e32 v116, v125, v67
	v_cvt_pk_bf16_f32 v66, v121, v122
	v_cvt_pk_bf16_f32 v67, v123, v125
	s_waitcnt lgkmcnt(2)
	v_mfma_f32_32x32x16_bf16 v[16:31], v[112:115], v[104:107], v[16:31]
	ds_read_b128 v[72:75], v211 offset:18496
	s_waitcnt lgkmcnt(2)
	v_mfma_f32_32x32x16_bf16 v[0:15], v[76:79], v[96:99], v[0:15]
	ds_read_b128 v[76:79], v211 offset:23104
	s_waitcnt lgkmcnt(2)
	v_mfma_f32_32x32x16_bf16 v[16:31], v[108:111], v[96:99], v[16:31]
	ds_read_b128 v[96:99], v211 offset:18528
	ds_read_b128 v[104:107], v211 offset:23136
	s_waitcnt lgkmcnt(3)
	v_mfma_f32_32x32x16_bf16 v[0:15], v[72:75], v[68:71], v[0:15]
	s_waitcnt lgkmcnt(2)
	v_mfma_f32_32x32x16_bf16 v[16:31], v[76:79], v[68:71], v[16:31]
	s_waitcnt lgkmcnt(1)
	v_mfma_f32_32x32x16_bf16 v[0:15], v[96:99], v[64:67], v[0:15]
	v_add_f32_e32 v221, v103, v116
	v_add_f32_e32 v118, v102, v221
	s_waitcnt lgkmcnt(0)
	v_mfma_f32_32x32x16_bf16 v[16:31], v[104:107], v[64:67], v[16:31]
	ds_read_b128 v[64:67], v181
	ds_read_b128 v[112:115], v181 offset:6656
	v_cmp_lt_f32_e32 vcc, s59, v221
	s_cbranch_vccz .LBB0_996
	v_mov_b32_e32 v222, v221
	v_mov_b32_e32 v223, v221
	s_nop 1
	v_permlane32_swap_b32_e32 v222, v223
	v_add_f32_e32 v222, v222, v223
	v_log_f32_e32 v222, v222
	s_nop 0
	v_max_f32_e32 v33, 0, v222
	v_exp_f32_e64 v34, -v33
	v_add_f32_e32 v212, v212, v33
	v_xor_b32_e32 v32, 0x80000000, v212
	v_sub_f32_e32 v143, v143, v33
	v_pk_mul_f32 v[14:15], v[14:15], v[34:35] op_sel_hi:[1,0]
	v_pk_mul_f32 v[12:13], v[12:13], v[34:35] op_sel_hi:[1,0]
	v_pk_mul_f32 v[10:11], v[10:11], v[34:35] op_sel_hi:[1,0]
	v_pk_mul_f32 v[8:9], v[8:9], v[34:35] op_sel_hi:[1,0]
	v_pk_mul_f32 v[6:7], v[6:7], v[34:35] op_sel_hi:[1,0]
	v_pk_mul_f32 v[4:5], v[4:5], v[34:35] op_sel_hi:[1,0]
	v_pk_mul_f32 v[2:3], v[2:3], v[34:35] op_sel_hi:[1,0]
	v_pk_mul_f32 v[0:1], v[0:1], v[34:35] op_sel_hi:[1,0]
	v_pk_mul_f32 v[30:31], v[30:31], v[34:35] op_sel_hi:[1,0]
	v_pk_mul_f32 v[28:29], v[28:29], v[34:35] op_sel_hi:[1,0]
	v_pk_mul_f32 v[26:27], v[26:27], v[34:35] op_sel_hi:[1,0]
	v_pk_mul_f32 v[24:25], v[24:25], v[34:35] op_sel_hi:[1,0]
	v_pk_mul_f32 v[22:23], v[22:23], v[34:35] op_sel_hi:[1,0]
	v_pk_mul_f32 v[20:21], v[20:21], v[34:35] op_sel_hi:[1,0]
	v_pk_mul_f32 v[18:19], v[18:19], v[34:35] op_sel_hi:[1,0]
	v_pk_mul_f32 v[16:17], v[16:17], v[34:35] op_sel_hi:[1,0]
	v_sub_f32_e32 v142, v142, v33
	v_sub_f32_e32 v141, v141, v33
	v_sub_f32_e32 v140, v140, v33
	v_sub_f32_e32 v139, v139, v33
	v_sub_f32_e32 v138, v138, v33
	v_sub_f32_e32 v137, v137, v33
	v_sub_f32_e32 v136, v136, v33
	v_sub_f32_e32 v135, v135, v33
	v_sub_f32_e32 v134, v134, v33
	v_sub_f32_e32 v133, v133, v33
	v_sub_f32_e32 v132, v132, v33
	v_sub_f32_e32 v131, v131, v33
	v_sub_f32_e32 v130, v130, v33
	v_sub_f32_e32 v129, v129, v33
	v_sub_f32_e32 v128, v128, v33
	v_sub_f32_e32 v95, v95, v33
	v_sub_f32_e32 v94, v94, v33
	v_sub_f32_e32 v93, v93, v33
	v_sub_f32_e32 v92, v92, v33
	v_sub_f32_e32 v91, v91, v33
	v_sub_f32_e32 v90, v90, v33
	v_sub_f32_e32 v89, v89, v33
	v_sub_f32_e32 v88, v88, v33
	v_sub_f32_e32 v87, v87, v33
	v_sub_f32_e32 v86, v86, v33
	v_sub_f32_e32 v85, v85, v33
	v_sub_f32_e32 v84, v84, v33
	v_sub_f32_e32 v83, v83, v33
	v_sub_f32_e32 v82, v82, v33
	v_sub_f32_e32 v81, v81, v33
	v_sub_f32_e32 v80, v80, v33
	v_mul_f32_e32 v118, v118, v34
	v_mov_b32_e32 v33, v32
	v_mov_b32_e32 v34, v32
	v_mov_b32_e32 v35, v32
	v_mov_b32_e32 v36, v32
	v_mov_b32_e32 v37, v32
	v_mov_b32_e32 v38, v32
	v_mov_b32_e32 v39, v32
	v_mov_b32_e32 v40, v32
	v_mov_b32_e32 v41, v32
	v_mov_b32_e32 v42, v32
	v_mov_b32_e32 v43, v32
	v_mov_b32_e32 v44, v32
	v_mov_b32_e32 v45, v32
	v_mov_b32_e32 v46, v32
	v_mov_b32_e32 v47, v32
	v_mov_b32_e32 v48, v32
	v_mov_b32_e32 v49, v32
	v_mov_b32_e32 v50, v32
	v_mov_b32_e32 v51, v32
	v_mov_b32_e32 v52, v32
	v_mov_b32_e32 v53, v32
	v_mov_b32_e32 v54, v32
	v_mov_b32_e32 v55, v32
	v_mov_b32_e32 v56, v32
	v_mov_b32_e32 v57, v32
	v_mov_b32_e32 v58, v32
	v_mov_b32_e32 v59, v32
	v_mov_b32_e32 v60, v32
	v_mov_b32_e32 v61, v32
	v_mov_b32_e32 v62, v32
	v_mov_b32_e32 v63, v32

.LBB0_1000:
	ds_read_b128 v[120:123], v181 offset:32
	ds_read_b128 v[124:127], v181 offset:6688
	s_waitcnt lgkmcnt(3)
	v_mfma_f32_32x32x16_bf16 v[96:111], v[64:67], v[144:147], v[32:47]
	v_exp_f32_e32 v119, v128
	v_exp_f32_e32 v213, v129
	v_exp_f32_e32 v214, v130
	v_exp_f32_e32 v215, v131
	v_exp_f32_e32 v132, v132
	v_exp_f32_e32 v133, v133
	s_waitcnt lgkmcnt(2)
	v_mfma_f32_32x32x16_bf16 v[64:79], v[112:115], v[144:147], v[32:47]
	ds_read_b128 v[112:115], v181 offset:64
	ds_read_b128 v[128:131], v181 offset:6720
	s_waitcnt lgkmcnt(3)
	v_mfma_f32_32x32x16_bf16 v[96:111], v[120:123], v[148:151], v[96:111]
	v_add_f32_e32 v121, 0, v119
	v_add_f32_e32 v122, 0, v213
	v_cvt_pk_bf16_f32 v120, v119, v213
	v_add_f32_e32 v119, v214, v121
	v_add_f32_e32 v122, v215, v122
	v_add_f32_e32 v119, v132, v119
	s_waitcnt lgkmcnt(2)
	v_mfma_f32_32x32x16_bf16 v[64:79], v[124:127], v[148:151], v[64:79]
	v_add_f32_e32 v123, v133, v122
	v_exp_f32_e32 v216, v134
	v_exp_f32_e32 v217, v135
	v_exp_f32_e32 v136, v136
	v_exp_f32_e32 v137, v137
	v_exp_f32_e32 v138, v138
	v_exp_f32_e32 v139, v139
	v_cvt_pk_bf16_f32 v121, v214, v215
	v_cvt_pk_bf16_f32 v122, v132, v133
	ds_read_b128 v[124:127], v181 offset:96
	ds_read_b128 v[132:135], v181 offset:6752
	s_waitcnt lgkmcnt(3)
	v_mfma_f32_32x32x16_bf16 v[96:111], v[112:115], v[152:155], v[96:111]
	v_add_f32_e32 v112, v216, v119
	v_add_f32_e32 v113, v217, v123
	v_add_f32_e32 v114, v136, v112
	v_add_f32_e32 v113, v137, v113
	v_add_f32_e32 v114, v138, v114
	v_add_f32_e32 v115, v139, v113
	s_waitcnt lgkmcnt(2)
	v_mfma_f32_32x32x16_bf16 v[64:79], v[128:131], v[152:155], v[64:79]
	v_exp_f32_e32 v140, v140
	v_exp_f32_e32 v141, v141
	v_exp_f32_e32 v142, v142
	v_exp_f32_e32 v143, v143
	v_cvt_pk_bf16_f32 v123, v216, v217
	v_cvt_pk_bf16_f32 v112, v136, v137
	v_cvt_pk_bf16_f32 v113, v138, v139
	ds_read_b128 v[128:131], v181 offset:128
	ds_read_b128 v[136:139], v181 offset:6784
	s_waitcnt lgkmcnt(3)
	v_mfma_f32_32x32x16_bf16 v[96:111], v[124:127], v[156:159], v[96:111]
	v_exp_f32_e32 v119, v80
	v_exp_f32_e32 v213, v81
	v_add_f32_e32 v80, v140, v114
	v_add_f32_e32 v81, v141, v115
	v_exp_f32_e32 v216, v84
	v_exp_f32_e32 v217, v85
	s_waitcnt lgkmcnt(2)
	v_mfma_f32_32x32x16_bf16 v[64:79], v[132:135], v[156:159], v[64:79]
	v_add_f32_e32 v84, v142, v80
	v_add_f32_e32 v85, v143, v81
	v_exp_f32_e32 v214, v82
	v_exp_f32_e32 v215, v83
	v_cvt_pk_bf16_f32 v114, v140, v141
	v_cvt_pk_bf16_f32 v115, v142, v143
	ds_read_b128 v[80:83], v181 offset:160
	ds_read_b128 v[124:127], v181 offset:6816
	s_waitcnt lgkmcnt(3)
	v_mfma_f32_32x32x16_bf16 v[96:111], v[128:131], v[160:163], v[96:111]
	v_exp_f32_e32 v132, v86
	v_add_f32_e32 v86, v119, v84
	v_add_f32_e32 v85, v213, v85
	v_exp_f32_e32 v133, v88
	v_add_f32_e32 v86, v214, v86
	v_add_f32_e32 v88, v215, v85
	s_waitcnt lgkmcnt(2)
	v_mfma_f32_32x32x16_bf16 v[64:79], v[136:139], v[160:163], v[64:79]
	v_cvt_pk_bf16_f32 v84, v119, v213
	v_add_f32_e32 v119, v216, v86
	v_add_f32_e32 v136, v217, v88
	v_exp_f32_e32 v87, v87
	v_exp_f32_e32 v134, v89
	v_exp_f32_e32 v135, v90
	v_exp_f32_e32 v140, v91
	v_cvt_pk_bf16_f32 v85, v214, v215
	v_cvt_pk_bf16_f32 v86, v216, v217
	ds_read_b128 v[88:91], v211 offset:27648
	ds_read_b128 v[128:131], v211 offset:32256
	s_waitcnt lgkmcnt(3)
	v_mfma_f32_32x32x16_bf16 v[96:111], v[80:83], v[164:167], v[96:111]
	v_add_f32_e32 v80, v132, v119
	v_add_f32_e32 v81, v87, v136
	v_add_f32_e32 v82, v133, v80
	v_add_f32_e32 v81, v134, v81
	v_add_f32_e32 v82, v135, v82
	v_add_f32_e32 v83, v140, v81
	s_waitcnt lgkmcnt(2)
	v_mfma_f32_32x32x16_bf16 v[64:79], v[124:127], v[164:167], v[64:79]
	v_exp_f32_e32 v137, v92
	v_exp_f32_e32 v138, v93
	v_exp_f32_e32 v139, v94
	v_exp_f32_e32 v141, v95
	v_cvt_pk_bf16_f32 v87, v132, v87
	v_cvt_pk_bf16_f32 v80, v133, v134
	v_cvt_pk_bf16_f32 v81, v135, v140
	ds_read_b128 v[92:95], v211 offset:27680
	ds_read_b128 v[124:127], v211 offset:32288
	s_waitcnt lgkmcnt(3)
	v_mfma_f32_32x32x16_bf16 v[0:15], v[88:91], v[120:123], v[0:15]
	v_add_f32_e32 v88, v137, v82
	v_add_f32_e32 v83, v138, v83
	v_add_f32_e32 v119, v139, v88
	v_add_f32_e32 v132, v141, v83
	v_cvt_pk_bf16_f32 v82, v137, v138
	v_cvt_pk_bf16_f32 v83, v139, v141
	s_waitcnt lgkmcnt(2)
	v_mfma_f32_32x32x16_bf16 v[16:31], v[128:131], v[120:123], v[16:31]
	ds_read_b128 v[88:91], v211 offset:27712
	s_waitcnt lgkmcnt(2)
	v_mfma_f32_32x32x16_bf16 v[0:15], v[92:95], v[112:115], v[0:15]
	ds_read_b128 v[92:95], v211 offset:32320
	s_waitcnt lgkmcnt(2)
	v_mfma_f32_32x32x16_bf16 v[16:31], v[124:127], v[112:115], v[16:31]
	ds_read_b128 v[112:115], v211 offset:27744
	ds_read_b128 v[120:123], v211 offset:32352
	s_waitcnt lgkmcnt(3)
	v_mfma_f32_32x32x16_bf16 v[0:15], v[88:91], v[84:87], v[0:15]
	s_waitcnt lgkmcnt(2)
	v_mfma_f32_32x32x16_bf16 v[16:31], v[92:95], v[84:87], v[16:31]
	s_waitcnt lgkmcnt(1)
	v_mfma_f32_32x32x16_bf16 v[0:15], v[112:115], v[80:83], v[0:15]
	v_add_f32_e32 v221, v119, v132
	v_add_f32_e32 v118, v118, v221
	s_waitcnt lgkmcnt(0)
	v_mfma_f32_32x32x16_bf16 v[16:31], v[120:123], v[80:83], v[16:31]
	s_waitcnt vmcnt(0)
	s_barrier
	ds_read_b128 v[80:83], v181 offset:13312
	ds_read_b128 v[112:115], v181 offset:19968
	v_cmp_lt_f32_e32 vcc, s59, v221
	s_cbranch_vccz .LBB0_1002
	v_mov_b32_e32 v222, v221
	v_mov_b32_e32 v223, v221
	s_nop 1
	v_permlane32_swap_b32_e32 v222, v223
	v_add_f32_e32 v222, v222, v223
	v_log_f32_e32 v222, v222
	s_nop 0
	v_max_f32_e32 v33, 0, v222
	v_exp_f32_e64 v34, -v33
	v_add_f32_e32 v212, v212, v33
	v_xor_b32_e32 v32, 0x80000000, v212
	v_sub_f32_e32 v111, v111, v33
	v_pk_mul_f32 v[14:15], v[14:15], v[34:35] op_sel_hi:[1,0]
	v_pk_mul_f32 v[12:13], v[12:13], v[34:35] op_sel_hi:[1,0]
	v_pk_mul_f32 v[10:11], v[10:11], v[34:35] op_sel_hi:[1,0]
	v_pk_mul_f32 v[8:9], v[8:9], v[34:35] op_sel_hi:[1,0]
	v_pk_mul_f32 v[6:7], v[6:7], v[34:35] op_sel_hi:[1,0]
	v_pk_mul_f32 v[4:5], v[4:5], v[34:35] op_sel_hi:[1,0]
	v_pk_mul_f32 v[2:3], v[2:3], v[34:35] op_sel_hi:[1,0]
	v_pk_mul_f32 v[0:1], v[0:1], v[34:35] op_sel_hi:[1,0]
	v_pk_mul_f32 v[30:31], v[30:31], v[34:35] op_sel_hi:[1,0]
	v_pk_mul_f32 v[28:29], v[28:29], v[34:35] op_sel_hi:[1,0]
	v_pk_mul_f32 v[26:27], v[26:27], v[34:35] op_sel_hi:[1,0]
	v_pk_mul_f32 v[24:25], v[24:25], v[34:35] op_sel_hi:[1,0]
	v_pk_mul_f32 v[22:23], v[22:23], v[34:35] op_sel_hi:[1,0]
	v_pk_mul_f32 v[20:21], v[20:21], v[34:35] op_sel_hi:[1,0]
	v_pk_mul_f32 v[18:19], v[18:19], v[34:35] op_sel_hi:[1,0]
	v_pk_mul_f32 v[16:17], v[16:17], v[34:35] op_sel_hi:[1,0]
	v_sub_f32_e32 v110, v110, v33
	v_sub_f32_e32 v109, v109, v33
	v_sub_f32_e32 v108, v108, v33
	v_sub_f32_e32 v107, v107, v33
	v_sub_f32_e32 v106, v106, v33
	v_sub_f32_e32 v105, v105, v33
	v_sub_f32_e32 v104, v104, v33
	v_sub_f32_e32 v103, v103, v33
	v_sub_f32_e32 v102, v102, v33
	v_sub_f32_e32 v101, v101, v33
	v_sub_f32_e32 v100, v100, v33
	v_sub_f32_e32 v99, v99, v33
	v_sub_f32_e32 v98, v98, v33
	v_sub_f32_e32 v97, v97, v33
	v_sub_f32_e32 v96, v96, v33
	v_sub_f32_e32 v79, v79, v33
	v_sub_f32_e32 v78, v78, v33
	v_sub_f32_e32 v77, v77, v33
	v_sub_f32_e32 v76, v76, v33
	v_sub_f32_e32 v75, v75, v33
	v_sub_f32_e32 v74, v74, v33
	v_sub_f32_e32 v73, v73, v33
	v_sub_f32_e32 v72, v72, v33
	v_sub_f32_e32 v71, v71, v33
	v_sub_f32_e32 v70, v70, v33
	v_sub_f32_e32 v69, v69, v33
	v_sub_f32_e32 v68, v68, v33
	v_sub_f32_e32 v67, v67, v33
	v_sub_f32_e32 v66, v66, v33
	v_sub_f32_e32 v65, v65, v33
	v_sub_f32_e32 v64, v64, v33
	v_mul_f32_e32 v118, v118, v34
	v_mov_b32_e32 v33, v32
	v_mov_b32_e32 v34, v32
	v_mov_b32_e32 v35, v32
	v_mov_b32_e32 v36, v32
	v_mov_b32_e32 v37, v32
	v_mov_b32_e32 v38, v32
	v_mov_b32_e32 v39, v32
	v_mov_b32_e32 v40, v32
	v_mov_b32_e32 v41, v32
	v_mov_b32_e32 v42, v32
	v_mov_b32_e32 v43, v32
	v_mov_b32_e32 v44, v32
	v_mov_b32_e32 v45, v32
	v_mov_b32_e32 v46, v32
	v_mov_b32_e32 v47, v32
	v_mov_b32_e32 v48, v32
	v_mov_b32_e32 v49, v32
	v_mov_b32_e32 v50, v32
	v_mov_b32_e32 v51, v32
	v_mov_b32_e32 v52, v32
	v_mov_b32_e32 v53, v32
	v_mov_b32_e32 v54, v32
	v_mov_b32_e32 v55, v32
	v_mov_b32_e32 v56, v32
	v_mov_b32_e32 v57, v32
	v_mov_b32_e32 v58, v32
	v_mov_b32_e32 v59, v32
	v_mov_b32_e32 v60, v32
	v_mov_b32_e32 v61, v32
	v_mov_b32_e32 v62, v32
	v_mov_b32_e32 v63, v32

.LBB0_1006:
	ds_read_b128 v[138:141], v181 offset:13344
	ds_read_b128 v[214:217], v181 offset:20000
	s_waitcnt lgkmcnt(3)
	v_mfma_f32_32x32x16_bf16 v[122:137], v[80:83], v[144:147], v[32:47]
	v_exp_f32_e32 v116, v96
	v_exp_f32_e32 v117, v97
	v_exp_f32_e32 v119, v98
	v_exp_f32_e32 v120, v99
	v_exp_f32_e32 v121, v100
	v_exp_f32_e32 v142, v101
	s_waitcnt lgkmcnt(2)
	v_mfma_f32_32x32x16_bf16 v[80:95], v[112:115], v[144:147], v[32:47]
	ds_read_b128 v[96:99], v181 offset:13376
	ds_read_b128 v[112:115], v181 offset:20032
	s_waitcnt lgkmcnt(3)
	v_mfma_f32_32x32x16_bf16 v[122:137], v[138:141], v[148:151], v[122:137]
	v_exp_f32_e32 v143, v102
	v_add_f32_e32 v101, 0, v116
	v_add_f32_e32 v102, 0, v117
	v_exp_f32_e32 v213, v104
	v_add_f32_e32 v104, v119, v101
	v_add_f32_e32 v102, v120, v102
	s_waitcnt lgkmcnt(2)
	v_mfma_f32_32x32x16_bf16 v[80:95], v[214:217], v[148:151], v[80:95]
	v_cvt_pk_bf16_f32 v100, v116, v117
	v_add_f32_e32 v116, v121, v104
	v_add_f32_e32 v117, v142, v102
	v_exp_f32_e32 v103, v103
	v_exp_f32_e32 v218, v105
	v_exp_f32_e32 v219, v106
	v_exp_f32_e32 v220, v107
	v_cvt_pk_bf16_f32 v101, v119, v120
	v_cvt_pk_bf16_f32 v102, v121, v142
	ds_read_b128 v[104:107], v181 offset:13408
	ds_read_b128 v[138:141], v181 offset:20064
	s_waitcnt lgkmcnt(3)
	v_mfma_f32_32x32x16_bf16 v[122:137], v[96:99], v[152:155], v[122:137]
	v_add_f32_e32 v96, v143, v116
	v_add_f32_e32 v97, v103, v117
	v_add_f32_e32 v98, v213, v96
	v_add_f32_e32 v97, v218, v97
	v_add_f32_e32 v98, v219, v98
	v_add_f32_e32 v99, v220, v97
	s_waitcnt lgkmcnt(2)
	v_mfma_f32_32x32x16_bf16 v[80:95], v[112:115], v[152:155], v[80:95]
	v_exp_f32_e32 v119, v108
	v_exp_f32_e32 v120, v109
	v_exp_f32_e32 v121, v110
	v_exp_f32_e32 v142, v111
	v_cvt_pk_bf16_f32 v103, v143, v103
	v_cvt_pk_bf16_f32 v96, v213, v218
	v_cvt_pk_bf16_f32 v97, v219, v220
	ds_read_b128 v[108:111], v181 offset:13440
	ds_read_b128 v[112:115], v181 offset:20096
	s_waitcnt lgkmcnt(3)
	v_mfma_f32_32x32x16_bf16 v[122:137], v[104:107], v[156:159], v[122:137]
	v_exp_f32_e32 v116, v64
	v_exp_f32_e32 v117, v65
	v_add_f32_e32 v64, v119, v98
	v_add_f32_e32 v65, v120, v99
	v_exp_f32_e32 v214, v68
	v_exp_f32_e32 v215, v69
	s_waitcnt lgkmcnt(2)
	v_mfma_f32_32x32x16_bf16 v[80:95], v[138:141], v[156:159], v[80:95]
	v_add_f32_e32 v68, v121, v64
	v_add_f32_e32 v69, v142, v65
	v_exp_f32_e32 v143, v66
	v_exp_f32_e32 v213, v67
	v_cvt_pk_bf16_f32 v98, v119, v120
	v_cvt_pk_bf16_f32 v99, v121, v142
	ds_read_b128 v[64:67], v181 offset:13472
	ds_read_b128 v[104:107], v181 offset:20128
	s_waitcnt lgkmcnt(3)
	v_mfma_f32_32x32x16_bf16 v[122:137], v[108:111], v[160:163], v[122:137]
	v_exp_f32_e32 v119, v70
	v_add_f32_e32 v70, v116, v68
	v_add_f32_e32 v69, v117, v69
	v_exp_f32_e32 v120, v72
	v_add_f32_e32 v70, v143, v70
	v_add_f32_e32 v72, v213, v69
	s_waitcnt lgkmcnt(2)
	v_mfma_f32_32x32x16_bf16 v[80:95], v[112:115], v[160:163], v[80:95]
	v_add_f32_e32 v112, v214, v70
	v_add_f32_e32 v113, v215, v72
	v_exp_f32_e32 v71, v71
	v_exp_f32_e32 v121, v73
	v_exp_f32_e32 v138, v74
	v_exp_f32_e32 v139, v75
	v_cvt_pk_bf16_f32 v68, v116, v117
	v_cvt_pk_bf16_f32 v69, v143, v213
	v_cvt_pk_bf16_f32 v70, v214, v215
	ds_read_b128 v[72:75], v210 offset:53248
	ds_read_b128 v[108:111], v210 offset:57856
	s_waitcnt lgkmcnt(3)
	v_mfma_f32_32x32x16_bf16 v[122:137], v[64:67], v[164:167], v[122:137]
	v_add_f32_e32 v64, v119, v112
	v_add_f32_e32 v65, v71, v113
	v_add_f32_e32 v66, v120, v64
	v_add_f32_e32 v65, v121, v65
	v_add_f32_e32 v66, v138, v66
	v_add_f32_e32 v67, v139, v65
	s_waitcnt lgkmcnt(2)
	v_mfma_f32_32x32x16_bf16 v[80:95], v[104:107], v[164:167], v[80:95]
	v_exp_f32_e32 v114, v76
	v_exp_f32_e32 v115, v77
	v_exp_f32_e32 v116, v78
	v_exp_f32_e32 v117, v79
	v_cvt_pk_bf16_f32 v71, v119, v71
	v_cvt_pk_bf16_f32 v64, v120, v121
	v_cvt_pk_bf16_f32 v65, v138, v139
	ds_read_b128 v[76:79], v210 offset:53280
	ds_read_b128 v[104:107], v210 offset:57888
	s_waitcnt lgkmcnt(3)
	v_mfma_f32_32x32x16_bf16 v[0:15], v[72:75], v[100:103], v[0:15]
	v_add_f32_e32 v72, v114, v66
	v_add_f32_e32 v67, v115, v67
	v_add_f32_e32 v112, v116, v72
	v_add_f32_e32 v113, v117, v67
	v_cvt_pk_bf16_f32 v66, v114, v115
	v_cvt_pk_bf16_f32 v67, v116, v117
	s_waitcnt lgkmcnt(2)
	v_mfma_f32_32x32x16_bf16 v[16:31], v[108:111], v[100:103], v[16:31]
	ds_read_b128 v[72:75], v210 offset:53312
	s_waitcnt lgkmcnt(2)
	v_mfma_f32_32x32x16_bf16 v[0:15], v[76:79], v[96:99], v[0:15]
	ds_read_b128 v[76:79], v210 offset:57920
	s_waitcnt lgkmcnt(2)
	v_mfma_f32_32x32x16_bf16 v[16:31], v[104:107], v[96:99], v[16:31]
	ds_read_b128 v[96:99], v210 offset:53344
	ds_read_b128 v[102:105], v210 offset:57952
	s_waitcnt lgkmcnt(3)
	v_mfma_f32_32x32x16_bf16 v[0:15], v[72:75], v[68:71], v[0:15]
	s_waitcnt lgkmcnt(2)
	v_mfma_f32_32x32x16_bf16 v[16:31], v[76:79], v[68:71], v[16:31]
	s_waitcnt lgkmcnt(1)
	v_mfma_f32_32x32x16_bf16 v[0:15], v[96:99], v[64:67], v[0:15]
	v_add_f32_e32 v221, v112, v113
	v_add_f32_e32 v100, v118, v221
	s_waitcnt lgkmcnt(0)
	v_mfma_f32_32x32x16_bf16 v[16:31], v[102:105], v[64:67], v[16:31]
	ds_read_b128 v[64:67], v181 offset:26624
	ds_read_b128 v[96:99], v181 offset:33280
	v_cmp_lt_f32_e32 vcc, s59, v221
	s_cbranch_vccz .LBB0_1008
	v_mov_b32_e32 v222, v221
	v_mov_b32_e32 v223, v221
	s_nop 1
	v_permlane32_swap_b32_e32 v222, v223
	v_add_f32_e32 v222, v222, v223
	v_log_f32_e32 v222, v222
	s_nop 0
	v_max_f32_e32 v33, 0, v222
	v_exp_f32_e64 v34, -v33
	v_add_f32_e32 v212, v212, v33
	v_xor_b32_e32 v32, 0x80000000, v212
	v_sub_f32_e32 v137, v137, v33
	v_pk_mul_f32 v[14:15], v[14:15], v[34:35] op_sel_hi:[1,0]
	v_pk_mul_f32 v[12:13], v[12:13], v[34:35] op_sel_hi:[1,0]
	v_pk_mul_f32 v[10:11], v[10:11], v[34:35] op_sel_hi:[1,0]
	v_pk_mul_f32 v[8:9], v[8:9], v[34:35] op_sel_hi:[1,0]
	v_pk_mul_f32 v[6:7], v[6:7], v[34:35] op_sel_hi:[1,0]
	v_pk_mul_f32 v[4:5], v[4:5], v[34:35] op_sel_hi:[1,0]
	v_pk_mul_f32 v[2:3], v[2:3], v[34:35] op_sel_hi:[1,0]
	v_pk_mul_f32 v[0:1], v[0:1], v[34:35] op_sel_hi:[1,0]
	v_pk_mul_f32 v[30:31], v[30:31], v[34:35] op_sel_hi:[1,0]
	v_pk_mul_f32 v[28:29], v[28:29], v[34:35] op_sel_hi:[1,0]
	v_pk_mul_f32 v[26:27], v[26:27], v[34:35] op_sel_hi:[1,0]
	v_pk_mul_f32 v[24:25], v[24:25], v[34:35] op_sel_hi:[1,0]
	v_pk_mul_f32 v[22:23], v[22:23], v[34:35] op_sel_hi:[1,0]
	v_pk_mul_f32 v[20:21], v[20:21], v[34:35] op_sel_hi:[1,0]
	v_pk_mul_f32 v[18:19], v[18:19], v[34:35] op_sel_hi:[1,0]
	v_pk_mul_f32 v[16:17], v[16:17], v[34:35] op_sel_hi:[1,0]
	v_sub_f32_e32 v136, v136, v33
	v_sub_f32_e32 v135, v135, v33
	v_sub_f32_e32 v134, v134, v33
	v_sub_f32_e32 v133, v133, v33
	v_sub_f32_e32 v132, v132, v33
	v_sub_f32_e32 v131, v131, v33
	v_sub_f32_e32 v130, v130, v33
	v_sub_f32_e32 v129, v129, v33
	v_sub_f32_e32 v128, v128, v33
	v_sub_f32_e32 v127, v127, v33
	v_sub_f32_e32 v126, v126, v33
	v_sub_f32_e32 v125, v125, v33
	v_sub_f32_e32 v124, v124, v33
	v_sub_f32_e32 v123, v123, v33
	v_sub_f32_e32 v122, v122, v33
	v_sub_f32_e32 v95, v95, v33
	v_sub_f32_e32 v94, v94, v33
	v_sub_f32_e32 v93, v93, v33
	v_sub_f32_e32 v92, v92, v33
	v_sub_f32_e32 v91, v91, v33
	v_sub_f32_e32 v90, v90, v33
	v_sub_f32_e32 v89, v89, v33
	v_sub_f32_e32 v88, v88, v33
	v_sub_f32_e32 v87, v87, v33
	v_sub_f32_e32 v86, v86, v33
	v_sub_f32_e32 v85, v85, v33
	v_sub_f32_e32 v84, v84, v33
	v_sub_f32_e32 v83, v83, v33
	v_sub_f32_e32 v82, v82, v33
	v_sub_f32_e32 v81, v81, v33
	v_sub_f32_e32 v80, v80, v33
	v_mul_f32_e32 v100, v100, v34
	v_mov_b32_e32 v33, v32
	v_mov_b32_e32 v34, v32
	v_mov_b32_e32 v35, v32
	v_mov_b32_e32 v36, v32
	v_mov_b32_e32 v37, v32
	v_mov_b32_e32 v38, v32
	v_mov_b32_e32 v39, v32
	v_mov_b32_e32 v40, v32
	v_mov_b32_e32 v41, v32
	v_mov_b32_e32 v42, v32
	v_mov_b32_e32 v43, v32
	v_mov_b32_e32 v44, v32
	v_mov_b32_e32 v45, v32
	v_mov_b32_e32 v46, v32
	v_mov_b32_e32 v47, v32
	v_mov_b32_e32 v48, v32
	v_mov_b32_e32 v49, v32
	v_mov_b32_e32 v50, v32
	v_mov_b32_e32 v51, v32
	v_mov_b32_e32 v52, v32
	v_mov_b32_e32 v53, v32
	v_mov_b32_e32 v54, v32
	v_mov_b32_e32 v55, v32
	v_mov_b32_e32 v56, v32
	v_mov_b32_e32 v57, v32
	v_mov_b32_e32 v58, v32
	v_mov_b32_e32 v59, v32
	v_mov_b32_e32 v60, v32
	v_mov_b32_e32 v61, v32
	v_mov_b32_e32 v62, v32
	v_mov_b32_e32 v63, v32

.LBB0_1012:
	ds_read_b128 v[102:105], v181 offset:26656
	ds_read_b128 v[138:141], v181 offset:33312
	s_waitcnt lgkmcnt(3)
	v_mfma_f32_32x32x16_bf16 v[106:121], v[64:67], v[144:147], v[32:47]
	v_exp_f32_e32 v101, v122
	v_exp_f32_e32 v142, v123
	v_exp_f32_e32 v143, v124
	v_exp_f32_e32 v202, v125
	v_exp_f32_e32 v126, v126
	v_exp_f32_e32 v127, v127
	s_waitcnt lgkmcnt(2)
	v_mfma_f32_32x32x16_bf16 v[64:79], v[96:99], v[144:147], v[32:47]
	ds_read_b128 v[96:99], v181 offset:26688
	ds_read_b128 v[122:125], v181 offset:33344
	s_waitcnt lgkmcnt(3)
	v_mfma_f32_32x32x16_bf16 v[106:121], v[102:105], v[148:151], v[106:121]
	v_add_f32_e32 v103, 0, v101
	v_add_f32_e32 v104, 0, v142
	v_cvt_pk_bf16_f32 v102, v101, v142
	v_add_f32_e32 v101, v143, v103
	v_add_f32_e32 v104, v202, v104
	v_add_f32_e32 v101, v126, v101
	s_waitcnt lgkmcnt(2)
	v_mfma_f32_32x32x16_bf16 v[64:79], v[138:141], v[148:151], v[64:79]
	v_add_f32_e32 v105, v127, v104
	v_exp_f32_e32 v203, v128
	v_exp_f32_e32 v204, v129
	v_exp_f32_e32 v205, v130
	v_exp_f32_e32 v213, v131
	v_exp_f32_e32 v214, v132
	v_exp_f32_e32 v215, v133
	v_cvt_pk_bf16_f32 v103, v143, v202
	v_cvt_pk_bf16_f32 v104, v126, v127
	ds_read_b128 v[126:129], v181 offset:26720
	ds_read_b128 v[130:133], v181 offset:33376
	s_waitcnt lgkmcnt(3)
	v_mfma_f32_32x32x16_bf16 v[106:121], v[96:99], v[152:155], v[106:121]
	v_add_f32_e32 v96, v203, v101
	v_add_f32_e32 v97, v204, v105
	v_add_f32_e32 v98, v205, v96
	v_add_f32_e32 v97, v213, v97
	v_add_f32_e32 v98, v214, v98
	v_add_f32_e32 v99, v215, v97
	s_waitcnt lgkmcnt(2)
	v_mfma_f32_32x32x16_bf16 v[64:79], v[122:125], v[152:155], v[64:79]
	v_exp_f32_e32 v138, v134
	v_exp_f32_e32 v139, v135
	v_exp_f32_e32 v140, v136
	v_exp_f32_e32 v141, v137
	v_cvt_pk_bf16_f32 v105, v203, v204
	v_cvt_pk_bf16_f32 v96, v205, v213
	v_cvt_pk_bf16_f32 v97, v214, v215
	ds_read_b128 v[122:125], v181 offset:26752
	ds_read_b128 v[134:137], v181 offset:33408
	s_waitcnt lgkmcnt(3)
	v_mfma_f32_32x32x16_bf16 v[106:121], v[126:129], v[156:159], v[106:121]
	v_exp_f32_e32 v101, v80
	v_exp_f32_e32 v142, v81
	v_add_f32_e32 v80, v138, v98
	v_add_f32_e32 v81, v139, v99
	v_exp_f32_e32 v203, v84
	v_exp_f32_e32 v204, v85
	s_waitcnt lgkmcnt(2)
	v_mfma_f32_32x32x16_bf16 v[64:79], v[130:133], v[156:159], v[64:79]
	v_add_f32_e32 v84, v140, v80
	v_add_f32_e32 v85, v141, v81
	v_exp_f32_e32 v143, v82
	v_exp_f32_e32 v202, v83
	v_cvt_pk_bf16_f32 v98, v138, v139
	v_cvt_pk_bf16_f32 v99, v140, v141
	ds_read_b128 v[80:83], v181 offset:26784
	ds_read_b128 v[126:129], v181 offset:33440
	s_waitcnt lgkmcnt(3)
	v_mfma_f32_32x32x16_bf16 v[106:121], v[122:125], v[160:163], v[106:121]
	v_exp_f32_e32 v87, v87
	v_exp_f32_e32 v130, v86
	v_add_f32_e32 v86, v101, v84
	v_add_f32_e32 v85, v142, v85
	v_exp_f32_e32 v131, v88
	v_add_f32_e32 v86, v143, v86
	s_waitcnt lgkmcnt(2)
	v_mfma_f32_32x32x16_bf16 v[64:79], v[134:137], v[160:163], v[64:79]
	v_add_f32_e32 v88, v202, v85
	v_cvt_pk_bf16_f32 v84, v101, v142
	v_add_f32_e32 v101, v203, v86
	v_add_f32_e32 v134, v204, v88
	v_exp_f32_e32 v132, v89
	v_exp_f32_e32 v133, v90
	v_exp_f32_e32 v138, v91
	v_cvt_pk_bf16_f32 v85, v143, v202
	v_cvt_pk_bf16_f32 v86, v203, v204
	ds_read_b128 v[88:91], v210 offset:62464
	ds_read_b128 v[122:125], v211 offset:13824
	s_waitcnt lgkmcnt(3)
	v_mfma_f32_32x32x16_bf16 v[106:121], v[80:83], v[164:167], v[106:121]
	v_add_f32_e32 v80, v130, v101
	v_add_f32_e32 v81, v87, v134
	v_add_f32_e32 v82, v131, v80
	v_add_f32_e32 v81, v132, v81
	v_add_f32_e32 v82, v133, v82
	v_add_f32_e32 v83, v138, v81
	s_waitcnt lgkmcnt(2)
	v_mfma_f32_32x32x16_bf16 v[64:79], v[126:129], v[164:167], v[64:79]
	v_exp_f32_e32 v135, v92
	v_exp_f32_e32 v136, v93
	v_exp_f32_e32 v137, v94
	v_exp_f32_e32 v139, v95
	v_cvt_pk_bf16_f32 v87, v130, v87
	v_cvt_pk_bf16_f32 v80, v131, v132
	v_cvt_pk_bf16_f32 v81, v133, v138
	ds_read_b128 v[92:95], v210 offset:62496
	ds_read_b128 v[126:129], v211 offset:13856
	s_waitcnt lgkmcnt(3)
	v_mfma_f32_32x32x16_bf16 v[0:15], v[88:91], v[102:105], v[0:15]
	v_add_f32_e32 v88, v135, v82
	v_add_f32_e32 v83, v136, v83
	v_add_f32_e32 v101, v137, v88
	v_add_f32_e32 v130, v139, v83
	v_cvt_pk_bf16_f32 v82, v135, v136
	v_cvt_pk_bf16_f32 v83, v137, v139
	s_waitcnt lgkmcnt(2)
	v_mfma_f32_32x32x16_bf16 v[16:31], v[122:125], v[102:105], v[16:31]
	ds_read_b128 v[88:91], v210 offset:62528
	s_waitcnt lgkmcnt(2)
	v_mfma_f32_32x32x16_bf16 v[0:15], v[92:95], v[96:99], v[0:15]
	ds_read_b128 v[92:95], v211 offset:13888
	s_waitcnt lgkmcnt(2)
	v_mfma_f32_32x32x16_bf16 v[16:31], v[126:129], v[96:99], v[16:31]
	ds_read_b128 v[96:99], v210 offset:62560
	ds_read_b128 v[102:105], v211 offset:13920
	s_waitcnt lgkmcnt(3)
	v_mfma_f32_32x32x16_bf16 v[0:15], v[88:91], v[84:87], v[0:15]
	s_waitcnt lgkmcnt(2)
	v_mfma_f32_32x32x16_bf16 v[16:31], v[92:95], v[84:87], v[16:31]
	s_waitcnt lgkmcnt(1)
	v_mfma_f32_32x32x16_bf16 v[0:15], v[96:99], v[80:83], v[0:15]
	v_add_f32_e32 v221, v101, v130
	v_add_f32_e32 v88, v100, v221
	s_waitcnt lgkmcnt(0)
	v_mfma_f32_32x32x16_bf16 v[16:31], v[102:105], v[80:83], v[16:31]
	s_waitcnt vmcnt(0)
	s_barrier
	ds_read_b128 v[84:87], v181 offset:39936
	ds_read_b128 v[80:83], v181 offset:46592
	v_cmp_lt_f32_e32 vcc, s59, v221
	s_cbranch_vccz .LBB0_1014
	v_mov_b32_e32 v222, v221
	v_mov_b32_e32 v223, v221
	s_nop 1
	v_permlane32_swap_b32_e32 v222, v223
	v_add_f32_e32 v222, v222, v223
	v_log_f32_e32 v222, v222
	s_nop 0
	v_max_f32_e32 v33, 0, v222
	v_exp_f32_e64 v34, -v33
	v_add_f32_e32 v212, v212, v33
	v_xor_b32_e32 v32, 0x80000000, v212
	v_sub_f32_e32 v121, v121, v33
	v_pk_mul_f32 v[14:15], v[14:15], v[34:35] op_sel_hi:[1,0]
	v_pk_mul_f32 v[12:13], v[12:13], v[34:35] op_sel_hi:[1,0]
	v_pk_mul_f32 v[10:11], v[10:11], v[34:35] op_sel_hi:[1,0]
	v_pk_mul_f32 v[8:9], v[8:9], v[34:35] op_sel_hi:[1,0]
	v_pk_mul_f32 v[6:7], v[6:7], v[34:35] op_sel_hi:[1,0]
	v_pk_mul_f32 v[4:5], v[4:5], v[34:35] op_sel_hi:[1,0]
	v_pk_mul_f32 v[2:3], v[2:3], v[34:35] op_sel_hi:[1,0]
	v_pk_mul_f32 v[0:1], v[0:1], v[34:35] op_sel_hi:[1,0]
	v_pk_mul_f32 v[30:31], v[30:31], v[34:35] op_sel_hi:[1,0]
	v_pk_mul_f32 v[28:29], v[28:29], v[34:35] op_sel_hi:[1,0]
	v_pk_mul_f32 v[26:27], v[26:27], v[34:35] op_sel_hi:[1,0]
	v_pk_mul_f32 v[24:25], v[24:25], v[34:35] op_sel_hi:[1,0]
	v_pk_mul_f32 v[22:23], v[22:23], v[34:35] op_sel_hi:[1,0]
	v_pk_mul_f32 v[20:21], v[20:21], v[34:35] op_sel_hi:[1,0]
	v_pk_mul_f32 v[18:19], v[18:19], v[34:35] op_sel_hi:[1,0]
	v_pk_mul_f32 v[16:17], v[16:17], v[34:35] op_sel_hi:[1,0]
	v_sub_f32_e32 v120, v120, v33
	v_sub_f32_e32 v119, v119, v33
	v_sub_f32_e32 v118, v118, v33
	v_sub_f32_e32 v117, v117, v33
	v_sub_f32_e32 v116, v116, v33
	v_sub_f32_e32 v115, v115, v33
	v_sub_f32_e32 v114, v114, v33
	v_sub_f32_e32 v113, v113, v33
	v_sub_f32_e32 v112, v112, v33
	v_sub_f32_e32 v111, v111, v33
	v_sub_f32_e32 v110, v110, v33
	v_sub_f32_e32 v109, v109, v33
	v_sub_f32_e32 v108, v108, v33
	v_sub_f32_e32 v107, v107, v33
	v_sub_f32_e32 v106, v106, v33
	v_sub_f32_e32 v79, v79, v33
	v_sub_f32_e32 v78, v78, v33
	v_sub_f32_e32 v77, v77, v33
	v_sub_f32_e32 v76, v76, v33
	v_sub_f32_e32 v75, v75, v33
	v_sub_f32_e32 v74, v74, v33
	v_sub_f32_e32 v73, v73, v33
	v_sub_f32_e32 v72, v72, v33
	v_sub_f32_e32 v71, v71, v33
	v_sub_f32_e32 v70, v70, v33
	v_sub_f32_e32 v69, v69, v33
	v_sub_f32_e32 v68, v68, v33
	v_sub_f32_e32 v67, v67, v33
	v_sub_f32_e32 v66, v66, v33
	v_sub_f32_e32 v65, v65, v33
	v_sub_f32_e32 v64, v64, v33
	v_mul_f32_e32 v88, v88, v34
	v_mov_b32_e32 v33, v32
	v_mov_b32_e32 v34, v32
	v_mov_b32_e32 v35, v32
	v_mov_b32_e32 v36, v32
	v_mov_b32_e32 v37, v32
	v_mov_b32_e32 v38, v32
	v_mov_b32_e32 v39, v32
	v_mov_b32_e32 v40, v32
	v_mov_b32_e32 v41, v32
	v_mov_b32_e32 v42, v32
	v_mov_b32_e32 v43, v32
	v_mov_b32_e32 v44, v32
	v_mov_b32_e32 v45, v32
	v_mov_b32_e32 v46, v32
	v_mov_b32_e32 v47, v32
	v_mov_b32_e32 v48, v32
	v_mov_b32_e32 v49, v32
	v_mov_b32_e32 v50, v32
	v_mov_b32_e32 v51, v32
	v_mov_b32_e32 v52, v32
	v_mov_b32_e32 v53, v32
	v_mov_b32_e32 v54, v32
	v_mov_b32_e32 v55, v32
	v_mov_b32_e32 v56, v32
	v_mov_b32_e32 v57, v32
	v_mov_b32_e32 v58, v32
	v_mov_b32_e32 v59, v32
	v_mov_b32_e32 v60, v32
	v_mov_b32_e32 v61, v32
	v_mov_b32_e32 v62, v32
	v_mov_b32_e32 v63, v32

.LBB0_1018:
	s_waitcnt lgkmcnt(1)
	v_mfma_f32_32x32x16_bf16 v[122:137], v[84:87], v[144:147], v[32:47]
	v_exp_f32_e32 v89, v106
	v_exp_f32_e32 v94, v107
	v_exp_f32_e32 v95, v108
	v_exp_f32_e32 v142, v109
	v_exp_f32_e32 v143, v110
	v_exp_f32_e32 v202, v111
	ds_read_b128 v[84:87], v181 offset:39968
	ds_read_b128 v[90:93], v181 offset:46624
	s_waitcnt lgkmcnt(2)
	v_mfma_f32_32x32x16_bf16 v[96:111], v[80:83], v[144:147], v[32:47]
	ds_read_b128 v[80:83], v181 offset:40000
	ds_read_b128 v[138:141], v181 offset:46656
	s_waitcnt lgkmcnt(3)
	v_mfma_f32_32x32x16_bf16 v[122:137], v[84:87], v[148:151], v[122:137]
	v_exp_f32_e32 v116, v116
	v_add_f32_e32 v85, 0, v89
	v_add_f32_e32 v86, 0, v94
	v_add_f32_e32 v87, v95, v85
	v_add_f32_e32 v86, v142, v86
	v_cvt_pk_bf16_f32 v84, v89, v94
	s_waitcnt lgkmcnt(2)
	v_mfma_f32_32x32x16_bf16 v[96:111], v[90:93], v[148:151], v[96:111]
	v_add_f32_e32 v87, v143, v87
	v_add_f32_e32 v89, v202, v86
	v_exp_f32_e32 v203, v112
	v_exp_f32_e32 v204, v113
	v_exp_f32_e32 v205, v114
	v_exp_f32_e32 v213, v115
	v_exp_f32_e32 v117, v117
	v_cvt_pk_bf16_f32 v85, v95, v142
	v_cvt_pk_bf16_f32 v86, v143, v202
	ds_read_b128 v[90:93], v181 offset:40032
	ds_read_b128 v[112:115], v181 offset:46688
	s_waitcnt lgkmcnt(3)
	v_mfma_f32_32x32x16_bf16 v[122:137], v[80:83], v[152:155], v[122:137]
	v_add_f32_e32 v80, v203, v87
	v_add_f32_e32 v81, v204, v89
	v_add_f32_e32 v82, v205, v80
	v_add_f32_e32 v81, v213, v81
	v_add_f32_e32 v82, v116, v82
	v_add_f32_e32 v83, v117, v81
	s_waitcnt lgkmcnt(2)
	v_mfma_f32_32x32x16_bf16 v[96:111], v[138:141], v[152:155], v[96:111]
	v_exp_f32_e32 v94, v118
	v_exp_f32_e32 v95, v119
	v_exp_f32_e32 v120, v120
	v_exp_f32_e32 v121, v121
	v_cvt_pk_bf16_f32 v87, v203, v204
	v_cvt_pk_bf16_f32 v80, v205, v213
	v_cvt_pk_bf16_f32 v81, v116, v117
	ds_read_b128 v[116:119], v181 offset:40064
	ds_read_b128 v[138:141], v181 offset:46720
	s_waitcnt lgkmcnt(3)
	v_mfma_f32_32x32x16_bf16 v[122:137], v[90:93], v[156:159], v[122:137]
	v_exp_f32_e32 v89, v64
	v_exp_f32_e32 v142, v65
	v_add_f32_e32 v64, v94, v82
	v_add_f32_e32 v65, v95, v83
	v_exp_f32_e32 v203, v68
	v_exp_f32_e32 v204, v69
	s_waitcnt lgkmcnt(2)
	v_mfma_f32_32x32x16_bf16 v[96:111], v[112:115], v[156:159], v[96:111]
	v_add_f32_e32 v68, v120, v64
	v_add_f32_e32 v69, v121, v65
	v_exp_f32_e32 v143, v66
	v_exp_f32_e32 v202, v67
	v_cvt_pk_bf16_f32 v82, v94, v95
	v_cvt_pk_bf16_f32 v83, v120, v121
	ds_read_b128 v[64:67], v181 offset:40096
	ds_read_b128 v[90:93], v181 offset:46752
	s_waitcnt lgkmcnt(3)
	v_mfma_f32_32x32x16_bf16 v[122:137], v[116:119], v[160:163], v[122:137]
	v_exp_f32_e32 v116, v74
	v_exp_f32_e32 v94, v70
	v_add_f32_e32 v70, v89, v68
	v_add_f32_e32 v69, v142, v69
	v_exp_f32_e32 v95, v72
	v_add_f32_e32 v70, v143, v70
	s_waitcnt lgkmcnt(2)
	v_mfma_f32_32x32x16_bf16 v[96:111], v[138:141], v[160:163], v[96:111]
	v_add_f32_e32 v72, v202, v69
	v_cvt_pk_bf16_f32 v68, v89, v142
	v_add_f32_e32 v89, v203, v70
	v_add_f32_e32 v118, v204, v72
	v_exp_f32_e32 v71, v71
	v_exp_f32_e32 v120, v73
	v_exp_f32_e32 v117, v75
	v_cvt_pk_bf16_f32 v69, v143, v202
	v_cvt_pk_bf16_f32 v70, v203, v204
	ds_read_b128 v[72:75], v211 offset:18432
	ds_read_b128 v[112:115], v211 offset:23040
	s_waitcnt lgkmcnt(3)
	v_mfma_f32_32x32x16_bf16 v[122:137], v[64:67], v[164:167], v[122:137]
	v_add_f32_e32 v64, v94, v89
	v_add_f32_e32 v65, v71, v118
	v_add_f32_e32 v66, v95, v64
	v_add_f32_e32 v65, v120, v65
	v_add_f32_e32 v66, v116, v66
	v_add_f32_e32 v67, v117, v65
	s_waitcnt lgkmcnt(2)
	v_mfma_f32_32x32x16_bf16 v[96:111], v[90:93], v[164:167], v[96:111]
	v_exp_f32_e32 v119, v76
	v_exp_f32_e32 v121, v77
	v_exp_f32_e32 v138, v78
	v_exp_f32_e32 v139, v79
	v_cvt_pk_bf16_f32 v71, v94, v71
	v_cvt_pk_bf16_f32 v64, v95, v120
	v_cvt_pk_bf16_f32 v65, v116, v117
	ds_read_b128 v[76:79], v211 offset:18464
	ds_read_b128 v[90:93], v211 offset:23072
	s_waitcnt lgkmcnt(3)
	v_mfma_f32_32x32x16_bf16 v[0:15], v[72:75], v[84:87], v[0:15]
	v_add_f32_e32 v72, v119, v66
	v_add_f32_e32 v67, v121, v67
	v_add_f32_e32 v89, v138, v72
	v_add_f32_e32 v94, v139, v67
	v_cvt_pk_bf16_f32 v66, v119, v121
	v_cvt_pk_bf16_f32 v67, v138, v139
	s_waitcnt lgkmcnt(2)
	v_mfma_f32_32x32x16_bf16 v[16:31], v[112:115], v[84:87], v[16:31]
	ds_read_b128 v[72:75], v211 offset:18496
	s_waitcnt lgkmcnt(2)
	v_mfma_f32_32x32x16_bf16 v[0:15], v[76:79], v[80:83], v[0:15]
	ds_read_b128 v[76:79], v211 offset:23104
	s_waitcnt lgkmcnt(2)
	v_mfma_f32_32x32x16_bf16 v[16:31], v[90:93], v[80:83], v[16:31]
	ds_read_b128 v[80:83], v211 offset:18528
	ds_read_b128 v[84:87], v211 offset:23136
	s_waitcnt lgkmcnt(3)
	v_mfma_f32_32x32x16_bf16 v[0:15], v[72:75], v[68:71], v[0:15]
	s_waitcnt lgkmcnt(2)
	v_mfma_f32_32x32x16_bf16 v[16:31], v[76:79], v[68:71], v[16:31]
	s_waitcnt lgkmcnt(1)
	v_mfma_f32_32x32x16_bf16 v[0:15], v[80:83], v[64:67], v[0:15]
	v_add_f32_e32 v221, v89, v94
	v_add_f32_e32 v116, v88, v221
	s_waitcnt lgkmcnt(0)
	v_mfma_f32_32x32x16_bf16 v[16:31], v[84:87], v[64:67], v[16:31]
	ds_read_b128 v[64:67], v181
	ds_read_b128 v[112:115], v181 offset:6656
	v_cmp_lt_f32_e32 vcc, s59, v221
	s_cbranch_vccz .LBB0_1020
	v_mov_b32_e32 v222, v221
	v_mov_b32_e32 v223, v221
	s_nop 1
	v_permlane32_swap_b32_e32 v222, v223
	v_add_f32_e32 v222, v222, v223
	v_log_f32_e32 v222, v222
	s_nop 0
	v_max_f32_e32 v33, 0, v222
	v_exp_f32_e64 v34, -v33
	v_add_f32_e32 v212, v212, v33
	v_xor_b32_e32 v32, 0x80000000, v212
	v_sub_f32_e32 v137, v137, v33
	v_pk_mul_f32 v[14:15], v[14:15], v[34:35] op_sel_hi:[1,0]
	v_pk_mul_f32 v[12:13], v[12:13], v[34:35] op_sel_hi:[1,0]
	v_pk_mul_f32 v[10:11], v[10:11], v[34:35] op_sel_hi:[1,0]
	v_pk_mul_f32 v[8:9], v[8:9], v[34:35] op_sel_hi:[1,0]
	v_pk_mul_f32 v[6:7], v[6:7], v[34:35] op_sel_hi:[1,0]
	v_pk_mul_f32 v[4:5], v[4:5], v[34:35] op_sel_hi:[1,0]
	v_pk_mul_f32 v[2:3], v[2:3], v[34:35] op_sel_hi:[1,0]
	v_pk_mul_f32 v[0:1], v[0:1], v[34:35] op_sel_hi:[1,0]
	v_pk_mul_f32 v[30:31], v[30:31], v[34:35] op_sel_hi:[1,0]
	v_pk_mul_f32 v[28:29], v[28:29], v[34:35] op_sel_hi:[1,0]
	v_pk_mul_f32 v[26:27], v[26:27], v[34:35] op_sel_hi:[1,0]
	v_pk_mul_f32 v[24:25], v[24:25], v[34:35] op_sel_hi:[1,0]
	v_pk_mul_f32 v[22:23], v[22:23], v[34:35] op_sel_hi:[1,0]
	v_pk_mul_f32 v[20:21], v[20:21], v[34:35] op_sel_hi:[1,0]
	v_pk_mul_f32 v[18:19], v[18:19], v[34:35] op_sel_hi:[1,0]
	v_pk_mul_f32 v[16:17], v[16:17], v[34:35] op_sel_hi:[1,0]
	v_sub_f32_e32 v136, v136, v33
	v_sub_f32_e32 v135, v135, v33
	v_sub_f32_e32 v134, v134, v33
	v_sub_f32_e32 v133, v133, v33
	v_sub_f32_e32 v132, v132, v33
	v_sub_f32_e32 v131, v131, v33
	v_sub_f32_e32 v130, v130, v33
	v_sub_f32_e32 v129, v129, v33
	v_sub_f32_e32 v128, v128, v33
	v_sub_f32_e32 v127, v127, v33
	v_sub_f32_e32 v126, v126, v33
	v_sub_f32_e32 v125, v125, v33
	v_sub_f32_e32 v124, v124, v33
	v_sub_f32_e32 v123, v123, v33
	v_sub_f32_e32 v122, v122, v33
	v_sub_f32_e32 v111, v111, v33
	v_sub_f32_e32 v110, v110, v33
	v_sub_f32_e32 v109, v109, v33
	v_sub_f32_e32 v108, v108, v33
	v_sub_f32_e32 v107, v107, v33
	v_sub_f32_e32 v106, v106, v33
	v_sub_f32_e32 v105, v105, v33
	v_sub_f32_e32 v104, v104, v33
	v_sub_f32_e32 v103, v103, v33
	v_sub_f32_e32 v102, v102, v33
	v_sub_f32_e32 v101, v101, v33
	v_sub_f32_e32 v100, v100, v33
	v_sub_f32_e32 v99, v99, v33
	v_sub_f32_e32 v98, v98, v33
	v_sub_f32_e32 v97, v97, v33
	v_sub_f32_e32 v96, v96, v33
	v_mul_f32_e32 v116, v116, v34
	v_mov_b32_e32 v33, v32
	v_mov_b32_e32 v34, v32
	v_mov_b32_e32 v35, v32
	v_mov_b32_e32 v36, v32
	v_mov_b32_e32 v37, v32
	v_mov_b32_e32 v38, v32
	v_mov_b32_e32 v39, v32
	v_mov_b32_e32 v40, v32
	v_mov_b32_e32 v41, v32
	v_mov_b32_e32 v42, v32
	v_mov_b32_e32 v43, v32
	v_mov_b32_e32 v44, v32
	v_mov_b32_e32 v45, v32
	v_mov_b32_e32 v46, v32
	v_mov_b32_e32 v47, v32
	v_mov_b32_e32 v48, v32
	v_mov_b32_e32 v49, v32
	v_mov_b32_e32 v50, v32
	v_mov_b32_e32 v51, v32
	v_mov_b32_e32 v52, v32
	v_mov_b32_e32 v53, v32
	v_mov_b32_e32 v54, v32
	v_mov_b32_e32 v55, v32
	v_mov_b32_e32 v56, v32
	v_mov_b32_e32 v57, v32
	v_mov_b32_e32 v58, v32
	v_mov_b32_e32 v59, v32
	v_mov_b32_e32 v60, v32
	v_mov_b32_e32 v61, v32
	v_mov_b32_e32 v62, v32
	v_mov_b32_e32 v63, v32
